# GEMM K loops: counted LDS-DMA waits re-spread (vmcnt(8) at phases 4/8 plus vmcnt(10) at phases 2/6) so each DMA load has two more phases to land
# baseline (speedup 1.0000x reference)
; #define PG8_STAGE(bufoff, gbase, voff) do { _Pragma("unroll") for (int _i = 0; _i < 2; ++_i) \
;     __builtin_amdgcn_global_load_lds((const unsigned*)((const char*)(gbase) + (voff)[_i]), (LAS unsigned*)(lds + (bufoff) + ldsw + _i * 8192), 16, 0, 0); } while (0)
; #define PG8_LDA(dst, b, h) do { _Pragma("unroll") for (int m = 0; m < 4; ++m) _Pragma("unroll") for (int k = 0; k < 2; ++k) dst[m][k] = *(const LAS bf16x8*)(lds + PG8_SA(b, h) + aoff + m * 2048 + k * 1024); } while (0)
; #define PG8_LDB(dst, b, h) do { _Pragma("unroll") for (int n = 0; n < 2; ++n) _Pragma("unroll") for (int k = 0; k < 2; ++k) dst[n][k] = *(const LAS bf16x8*)(lds + PG8_SB(b, h) + boff + n * 2048 + k * 1024); } while (0)
; #define PG8_MMA(ai, bj, At, Bt) do { __builtin_amdgcn_s_setprio(1); _Pragma("unroll") for (int m = 0; m < 4; ++m) _Pragma("unroll") for (int n = 0; n < 2; ++n) _Pragma("unroll") for (int k = 0; k < 2; ++k) \
;     acc[ai][bj][m][n] = __builtin_amdgcn_mfma_f32_16x16x32_bf16(Bt[n][k], At[m][k], acc[ai][bj][m][n], 0, 0, 0); __builtin_amdgcn_s_setprio(0); } while (0)
; #define PG8_WAIT_L(n) asm volatile("s_waitcnt lgkmcnt(" #n ")" ::: "memory")
; #define PG8_BAR __builtin_amdgcn_s_barrier()
; #define PG8_SCHED __builtin_amdgcn_sched_barrier(0)
; template <class Epi, class Sched>
; DI void gemm_phase(LAS unsigned char* lds, const Gemm g, const Sched& S, const Epi& E) {
;     ...
;     for (int t = 0; t < nt; t += 2) {
;       const bool last = (t == nt - 2);
;       const char* a1 = cA + (size_t)(t + 1) * kstep;
;       const char* a2 = last ? nA : cA + (size_t)(t + 2) * kstep; const char* b2 = last ? nB : cB + (size_t)(t + 2) * kstep;
;       const char* a3 = a2 + kstep; const char* b3 = b2 + kstep;
;       PG8_LDB(B0, 0, 0); PG8_SCHED; PG8_LDA(At, 0, 0); PG8_STAGE(PG8_SA(1, 1), a1 + hstep, voffA);
;       PG8_WAIT_L(8); PG8_BAR; PG8_WAIT_L(0); PG8_MMA(0, 0, At, B0); PG8_BAR; PG8_SCHED;
;       PG8_LDB(B1, 0, 1); PG8_STAGE(PG8_SB(0, 0), b2, voffB);
;       PG8_BAR; PG8_WAIT_L(0); PG8_MMA(0, 1, At, B1); PG8_BAR;
;       PG8_LDA(At, 0, 1); PG8_STAGE(PG8_SA(0, 0), a2, voffA);
;       PG8_BAR; PG8_WAIT_L(0); PG8_MMA(1, 0, At, B0); PG8_BAR; PG8_SCHED;
.LBB0_137:
	s_add_i32 s41, s1, 2
	s_add_u32 s18, s16, 0x80
	s_addc_u32 s19, s17, 0
	s_cmp_lg_u32 s40, s1
	s_cselect_b32 s20, s18, 0
	s_cselect_b32 s1, s19, 0
	s_add_u32 s18, s14, s20
	s_addc_u32 s19, s15, s1
	s_add_i32 s42, 16, 0x10000
	v_add_u32_e32 v139, s42, v137
	ds_read_b128 v[140:143], v139
	ds_read_b128 v[144:147], v139 offset:1024
	ds_read_b128 v[150:153], v139 offset:2048
	ds_read_b128 v[154:157], v139 offset:3072
	s_add_u32 s20, s12, s20
	s_addc_u32 s21, s13, s1
	v_lshl_add_u64 v[180:181], v[132:133], 0, s[16:17]
	s_add_i32 m0, s31, 0xc000
	ds_read_b128 v[158:161], v138
	ds_read_b128 v[162:165], v138 offset:1024
	ds_read_b128 v[166:169], v138 offset:2048
	ds_read_b128 v[170:173], v138 offset:3072
	ds_read_b128 v[174:177], v138 offset:4096
	ds_read_b128 v[186:189], v138 offset:5120
	ds_read_b128 v[190:193], v138 offset:6144
	ds_read_b128 v[198:201], v138 offset:7168
	global_load_lds_dwordx4 v[180:181], off
	v_lshl_add_u64 v[180:181], v[134:135], 0, s[16:17]
	s_add_i32 m0, s31, 0xe000
	s_nop 0
	global_load_lds_dwordx4 v[180:181], off
	s_waitcnt lgkmcnt(8)
	s_barrier
	s_waitcnt lgkmcnt(0)
	s_waitcnt lgkmcnt(0)
	v_mfma_f32_16x16x32_bf16 v[126:129], v[140:143], v[158:161], v[126:129]
	v_mfma_f32_16x16x32_bf16 v[122:125], v[150:153], v[158:161], v[122:125]
	v_mfma_f32_16x16x32_bf16 v[110:113], v[140:143], v[166:169], v[110:113]
	v_mfma_f32_16x16x32_bf16 v[106:109], v[150:153], v[166:169], v[106:109]
	v_mfma_f32_16x16x32_bf16 v[94:97], v[140:143], v[174:177], v[94:97]
	v_mfma_f32_16x16x32_bf16 v[90:93], v[150:153], v[174:177], v[90:93]
	v_mfma_f32_16x16x32_bf16 v[78:81], v[140:143], v[190:193], v[78:81]
	v_mfma_f32_16x16x32_bf16 v[74:77], v[150:153], v[190:193], v[74:77]
	v_mfma_f32_16x16x32_bf16 v[126:129], v[144:147], v[162:165], v[126:129]
	v_mfma_f32_16x16x32_bf16 v[122:125], v[154:157], v[162:165], v[122:125]
	v_mfma_f32_16x16x32_bf16 v[110:113], v[144:147], v[170:173], v[110:113]
	v_mfma_f32_16x16x32_bf16 v[106:109], v[154:157], v[170:173], v[106:109]
	v_mfma_f32_16x16x32_bf16 v[94:97], v[144:147], v[186:189], v[94:97]
	v_mfma_f32_16x16x32_bf16 v[90:93], v[154:157], v[186:189], v[90:93]
	v_mfma_f32_16x16x32_bf16 v[78:81], v[144:147], v[198:201], v[78:81]
	v_mfma_f32_16x16x32_bf16 v[74:77], v[154:157], v[198:201], v[74:77]
	s_barrier
	s_add_i32 s1, 16, 0x14000
	s_add_i32 s42, s42, s30
	v_add_u32_e32 v139, s1, v137
	v_lshl_add_u64 v[180:181], s[20:21], 0, v[0:1]
	s_mov_b32 m0, s42
	ds_read_b128 v[202:205], v139
	ds_read_b128 v[206:209], v139 offset:1024
	ds_read_b128 v[214:217], v139 offset:2048
	ds_read_b128 v[218:221], v139 offset:3072
	global_load_lds_dwordx4 v[180:181], off
	v_lshl_add_u64 v[182:183], s[20:21], 0, v[130:131]
	s_add_i32 m0, s42, 0x2000
	s_nop 0
	global_load_lds_dwordx4 v[182:183], off
	s_waitcnt vmcnt(10)
	s_barrier
	s_waitcnt lgkmcnt(0)
	s_waitcnt lgkmcnt(0)
	v_mfma_f32_16x16x32_bf16 v[118:121], v[202:205], v[158:161], v[118:121]
	v_mfma_f32_16x16x32_bf16 v[114:117], v[214:217], v[158:161], v[114:117]
	v_mfma_f32_16x16x32_bf16 v[102:105], v[202:205], v[166:169], v[102:105]
	v_mfma_f32_16x16x32_bf16 v[98:101], v[214:217], v[166:169], v[98:101]
	v_mfma_f32_16x16x32_bf16 v[86:89], v[202:205], v[174:177], v[86:89]
	v_mfma_f32_16x16x32_bf16 v[82:85], v[214:217], v[174:177], v[82:85]
	v_mfma_f32_16x16x32_bf16 v[70:73], v[202:205], v[190:193], v[70:73]
	v_mfma_f32_16x16x32_bf16 v[66:69], v[214:217], v[190:193], v[66:69]
	v_mfma_f32_16x16x32_bf16 v[118:121], v[206:209], v[162:165], v[118:121]
	v_mfma_f32_16x16x32_bf16 v[114:117], v[218:221], v[162:165], v[114:117]
	v_mfma_f32_16x16x32_bf16 v[102:105], v[206:209], v[170:173], v[102:105]
	v_mfma_f32_16x16x32_bf16 v[98:101], v[218:221], v[170:173], v[98:101]
	v_mfma_f32_16x16x32_bf16 v[86:89], v[206:209], v[186:189], v[86:89]
	v_mfma_f32_16x16x32_bf16 v[82:85], v[218:221], v[186:189], v[82:85]
	v_mfma_f32_16x16x32_bf16 v[70:73], v[206:209], v[198:201], v[70:73]
	v_mfma_f32_16x16x32_bf16 v[66:69], v[218:221], v[198:201], v[66:69]
	s_mov_b32 m0, s31
	v_lshl_add_u64 v[184:185], s[18:19], 0, v[0:1]
	s_barrier
	ds_read_b128 v[158:161], v138 offset:16384
	ds_read_b128 v[162:165], v138 offset:17408
	ds_read_b128 v[166:169], v138 offset:18432
	ds_read_b128 v[170:173], v138 offset:19456
	ds_read_b128 v[174:177], v138 offset:20480
	ds_read_b128 v[186:189], v138 offset:21504
	ds_read_b128 v[190:193], v138 offset:22528
	ds_read_b128 v[198:201], v138 offset:23552
	global_load_lds_dwordx4 v[184:185], off
	v_lshl_add_u64 v[222:223], s[18:19], 0, v[130:131]
	s_mov_b32 m0, s34
	s_nop 0
	global_load_lds_dwordx4 v[222:223], off
	s_barrier
	s_waitcnt lgkmcnt(0)
	s_waitcnt lgkmcnt(0)
	v_mfma_f32_16x16x32_bf16 v[62:65], v[140:143], v[158:161], v[62:65]
	v_mfma_f32_16x16x32_bf16 v[58:61], v[150:153], v[158:161], v[58:61]
	v_mfma_f32_16x16x32_bf16 v[46:49], v[140:143], v[166:169], v[46:49]
	v_mfma_f32_16x16x32_bf16 v[42:45], v[150:153], v[166:169], v[42:45]
	v_mfma_f32_16x16x32_bf16 v[30:33], v[140:143], v[174:177], v[30:33]
	v_mfma_f32_16x16x32_bf16 v[26:29], v[150:153], v[174:177], v[26:29]
	v_mfma_f32_16x16x32_bf16 v[14:17], v[140:143], v[190:193], v[14:17]
	v_mfma_f32_16x16x32_bf16 v[10:13], v[150:153], v[190:193], v[10:13]
	v_mfma_f32_16x16x32_bf16 v[62:65], v[144:147], v[162:165], v[62:65]
	v_mfma_f32_16x16x32_bf16 v[58:61], v[154:157], v[162:165], v[58:61]
	v_mfma_f32_16x16x32_bf16 v[46:49], v[144:147], v[170:173], v[46:49]
	v_mfma_f32_16x16x32_bf16 v[42:45], v[154:157], v[170:173], v[42:45]
	v_mfma_f32_16x16x32_bf16 v[30:33], v[144:147], v[186:189], v[30:33]
	v_mfma_f32_16x16x32_bf16 v[26:29], v[154:157], v[186:189], v[26:29]
	v_mfma_f32_16x16x32_bf16 v[14:17], v[144:147], v[198:201], v[14:17]
	v_mfma_f32_16x16x32_bf16 v[10:13], v[154:157], v[198:201], v[10:13]
	s_barrier
; #define PG8_STAGE(bufoff, gbase, voff) do { _Pragma("unroll") for (int _i = 0; _i < 2; ++_i) \
;     __builtin_amdgcn_global_load_lds((const unsigned*)((const char*)(gbase) + (voff)[_i]), (LAS unsigned*)(lds + (bufoff) + ldsw + _i * 8192), 16, 0, 0); } while (0)
; #define PG8_LDA(dst, b, h) do { _Pragma("unroll") for (int m = 0; m < 4; ++m) _Pragma("unroll") for (int k = 0; k < 2; ++k) dst[m][k] = *(const LAS bf16x8*)(lds + PG8_SA(b, h) + aoff + m * 2048 + k * 1024); } while (0)
; #define PG8_LDB(dst, b, h) do { _Pragma("unroll") for (int n = 0; n < 2; ++n) _Pragma("unroll") for (int k = 0; k < 2; ++k) dst[n][k] = *(const LAS bf16x8*)(lds + PG8_SB(b, h) + boff + n * 2048 + k * 1024); } while (0)
; #define PG8_MMA(ai, bj, At, Bt) do { __builtin_amdgcn_s_setprio(1); _Pragma("unroll") for (int m = 0; m < 4; ++m) _Pragma("unroll") for (int n = 0; n < 2; ++n) _Pragma("unroll") for (int k = 0; k < 2; ++k) \
;     acc[ai][bj][m][n] = __builtin_amdgcn_mfma_f32_16x16x32_bf16(Bt[n][k], At[m][k], acc[ai][bj][m][n], 0, 0, 0); __builtin_amdgcn_s_setprio(0); } while (0)
; #define PG8_WAIT_V(n) asm volatile("s_waitcnt vmcnt(" #n ")" ::: "memory")
; #define PG8_WAIT_L(n) asm volatile("s_waitcnt lgkmcnt(" #n ")" ::: "memory")
; #define PG8_BAR __builtin_amdgcn_s_barrier()
; #define PG8_SCHED __builtin_amdgcn_sched_barrier(0)
; template <class Epi, class Sched>
; DI void gemm_phase(LAS unsigned char* lds, const Gemm g, const Sched& S, const Epi& E) {
;     ...
;       PG8_STAGE(PG8_SB(0, 1), b2 + hstepB, voffB);
;       PG8_WAIT_V(6); PG8_BAR; PG8_MMA(1, 1, At, B1); PG8_BAR;
;       PG8_LDB(B0, 1, 0); PG8_SCHED; PG8_LDA(At, 1, 0); PG8_STAGE(PG8_SA(0, 1), a2 + hstep, voffA);
;       PG8_WAIT_L(8); PG8_BAR; PG8_WAIT_L(0); PG8_MMA(0, 0, At, B0); PG8_BAR; PG8_SCHED;
;       PG8_LDB(B1, 1, 1); PG8_STAGE(PG8_SB(1, 0), b3, voffB);
	s_add_u32 s20, s20, s2
	s_addc_u32 s21, s21, s3
	s_add_i32 s1, s1, s30
	v_lshl_add_u64 v[224:225], s[20:21], 0, v[0:1]
	s_mov_b32 m0, s1
	v_lshl_add_u64 v[226:227], s[20:21], 0, v[130:131]
	global_load_lds_dwordx4 v[224:225], off
	s_add_i32 m0, s1, 0x2000
	s_nop 0
	global_load_lds_dwordx4 v[226:227], off
	s_waitcnt vmcnt(8)
	s_barrier
	v_mfma_f32_16x16x32_bf16 v[54:57], v[202:205], v[158:161], v[54:57]
	v_mfma_f32_16x16x32_bf16 v[50:53], v[214:217], v[158:161], v[50:53]
	v_mfma_f32_16x16x32_bf16 v[38:41], v[202:205], v[166:169], v[38:41]
	v_mfma_f32_16x16x32_bf16 v[34:37], v[214:217], v[166:169], v[34:37]
	v_mfma_f32_16x16x32_bf16 v[22:25], v[202:205], v[174:177], v[22:25]
	v_mfma_f32_16x16x32_bf16 v[18:21], v[214:217], v[174:177], v[18:21]
	v_mfma_f32_16x16x32_bf16 v[6:9], v[202:205], v[190:193], v[6:9]
	v_mfma_f32_16x16x32_bf16 v[2:5], v[214:217], v[190:193], v[2:5]
	v_mfma_f32_16x16x32_bf16 v[54:57], v[206:209], v[162:165], v[54:57]
	v_mfma_f32_16x16x32_bf16 v[50:53], v[218:221], v[162:165], v[50:53]
	v_mfma_f32_16x16x32_bf16 v[38:41], v[206:209], v[170:173], v[38:41]
	v_mfma_f32_16x16x32_bf16 v[34:37], v[218:221], v[170:173], v[34:37]
	v_mfma_f32_16x16x32_bf16 v[22:25], v[206:209], v[186:189], v[22:25]
	v_mfma_f32_16x16x32_bf16 v[18:21], v[218:221], v[186:189], v[18:21]
	v_mfma_f32_16x16x32_bf16 v[6:9], v[206:209], v[198:201], v[6:9]
	v_mfma_f32_16x16x32_bf16 v[2:5], v[218:221], v[198:201], v[2:5]
	s_add_i32 s1, 16, 0x18000
	v_add_u32_e32 v139, s1, v137
	s_barrier
	ds_read_b128 v[140:143], v139
	ds_read_b128 v[144:147], v139 offset:1024
	ds_read_b128 v[150:153], v139 offset:2048
	ds_read_b128 v[154:157], v139 offset:3072
	s_add_u32 s18, s18, s2
	s_addc_u32 s19, s19, s3
	s_mov_b32 m0, s35
	v_lshl_add_u64 v[202:203], s[18:19], 0, v[0:1]
	ds_read_b128 v[158:161], v138 offset:32768
	ds_read_b128 v[162:165], v138 offset:33792
	ds_read_b128 v[166:169], v138 offset:34816
	ds_read_b128 v[170:173], v138 offset:35840
	ds_read_b128 v[174:177], v138 offset:36864
	ds_read_b128 v[186:189], v138 offset:37888
	ds_read_b128 v[190:193], v138 offset:38912
	ds_read_b128 v[198:201], v138 offset:39936
	global_load_lds_dwordx4 v[202:203], off
	v_lshl_add_u64 v[202:203], s[18:19], 0, v[130:131]
	s_mov_b32 m0, s36
	s_nop 0
	global_load_lds_dwordx4 v[202:203], off
	s_waitcnt lgkmcnt(8)
	s_barrier
	s_waitcnt lgkmcnt(0)
	s_waitcnt lgkmcnt(0)
	v_mfma_f32_16x16x32_bf16 v[126:129], v[140:143], v[158:161], v[126:129]
	v_mfma_f32_16x16x32_bf16 v[122:125], v[150:153], v[158:161], v[122:125]
	v_mfma_f32_16x16x32_bf16 v[110:113], v[140:143], v[166:169], v[110:113]
	v_mfma_f32_16x16x32_bf16 v[106:109], v[150:153], v[166:169], v[106:109]
	v_mfma_f32_16x16x32_bf16 v[94:97], v[140:143], v[174:177], v[94:97]
	v_mfma_f32_16x16x32_bf16 v[90:93], v[150:153], v[174:177], v[90:93]
	v_mfma_f32_16x16x32_bf16 v[78:81], v[140:143], v[190:193], v[78:81]
	v_mfma_f32_16x16x32_bf16 v[74:77], v[150:153], v[190:193], v[74:77]
	v_mfma_f32_16x16x32_bf16 v[126:129], v[144:147], v[162:165], v[126:129]
	v_mfma_f32_16x16x32_bf16 v[122:125], v[154:157], v[162:165], v[122:125]
	v_mfma_f32_16x16x32_bf16 v[110:113], v[144:147], v[170:173], v[110:113]
	v_mfma_f32_16x16x32_bf16 v[106:109], v[154:157], v[170:173], v[106:109]
	v_mfma_f32_16x16x32_bf16 v[94:97], v[144:147], v[186:189], v[94:97]
	v_mfma_f32_16x16x32_bf16 v[90:93], v[154:157], v[186:189], v[90:93]
	v_mfma_f32_16x16x32_bf16 v[78:81], v[144:147], v[198:201], v[78:81]
	v_mfma_f32_16x16x32_bf16 v[74:77], v[154:157], v[198:201], v[74:77]
	s_barrier
	s_add_i32 s18, 16, 0x1c000
	s_add_i32 s1, s1, s30
	v_add_u32_e32 v139, s18, v137
	v_lshl_add_u64 v[180:181], v[180:181], 0, s[70:71]
	s_mov_b32 m0, s1
	ds_read_b128 v[202:205], v139
	ds_read_b128 v[206:209], v139 offset:1024
	ds_read_b128 v[214:217], v139 offset:2048
	ds_read_b128 v[218:221], v139 offset:3072
	global_load_lds_dwordx4 v[180:181], off
	v_lshl_add_u64 v[180:181], v[182:183], 0, s[70:71]
	s_add_i32 m0, s1, 0x2000
	s_nop 0
	global_load_lds_dwordx4 v[180:181], off
	s_waitcnt vmcnt(10)
	s_barrier
; #define PG8_STAGE(bufoff, gbase, voff) do { _Pragma("unroll") for (int _i = 0; _i < 2; ++_i) \
;     __builtin_amdgcn_global_load_lds((const unsigned*)((const char*)(gbase) + (voff)[_i]), (LAS unsigned*)(lds + (bufoff) + ldsw + _i * 8192), 16, 0, 0); } while (0)
; #define PG8_LDA(dst, b, h) do { _Pragma("unroll") for (int m = 0; m < 4; ++m) _Pragma("unroll") for (int k = 0; k < 2; ++k) dst[m][k] = *(const LAS bf16x8*)(lds + PG8_SA(b, h) + aoff + m * 2048 + k * 1024); } while (0)
; #define PG8_LDB(dst, b, h) do { _Pragma("unroll") for (int n = 0; n < 2; ++n) _Pragma("unroll") for (int k = 0; k < 2; ++k) dst[n][k] = *(const LAS bf16x8*)(lds + PG8_SB(b, h) + boff + n * 2048 + k * 1024); } while (0)
; #define PG8_MMA(ai, bj, At, Bt) do { __builtin_amdgcn_s_setprio(1); _Pragma("unroll") for (int m = 0; m < 4; ++m) _Pragma("unroll") for (int n = 0; n < 2; ++n) _Pragma("unroll") for (int k = 0; k < 2; ++k) \
;     acc[ai][bj][m][n] = __builtin_amdgcn_mfma_f32_16x16x32_bf16(Bt[n][k], At[m][k], acc[ai][bj][m][n], 0, 0, 0); __builtin_amdgcn_s_setprio(0); } while (0)
; #define PG8_WAIT_V(n) asm volatile("s_waitcnt vmcnt(" #n ")" ::: "memory")
; #define PG8_WAIT_L(n) asm volatile("s_waitcnt lgkmcnt(" #n ")" ::: "memory")
; #define PG8_BAR __builtin_amdgcn_s_barrier()
; #define PG8_SCHED __builtin_amdgcn_sched_barrier(0)
; template <class Epi, class Sched>
; DI void gemm_phase(LAS unsigned char* lds, const Gemm g, const Sched& S, const Epi& E) {
;     ...
;       PG8_LDB(B1, 1, 1); PG8_STAGE(PG8_SB(1, 0), b3, voffB);
;       PG8_BAR; PG8_WAIT_L(0); PG8_MMA(0, 1, At, B1); PG8_BAR;
;       PG8_LDA(At, 1, 1); PG8_STAGE(PG8_SA(1, 0), a3, voffA);
;       PG8_BAR; PG8_WAIT_L(0); PG8_MMA(1, 0, At, B0); PG8_BAR; PG8_SCHED;
;       PG8_STAGE(PG8_SB(1, 1), b3 + hstepB, voffB);
;       PG8_WAIT_V(6); PG8_BAR; PG8_MMA(1, 1, At, B1); PG8_BAR;
;     }
	s_waitcnt lgkmcnt(0)
	s_waitcnt lgkmcnt(0)
	v_mfma_f32_16x16x32_bf16 v[118:121], v[202:205], v[158:161], v[118:121]
	v_mfma_f32_16x16x32_bf16 v[114:117], v[214:217], v[158:161], v[114:117]
	v_mfma_f32_16x16x32_bf16 v[102:105], v[202:205], v[166:169], v[102:105]
	v_mfma_f32_16x16x32_bf16 v[98:101], v[214:217], v[166:169], v[98:101]
	v_mfma_f32_16x16x32_bf16 v[86:89], v[202:205], v[174:177], v[86:89]
	v_mfma_f32_16x16x32_bf16 v[82:85], v[214:217], v[174:177], v[82:85]
	v_mfma_f32_16x16x32_bf16 v[70:73], v[202:205], v[190:193], v[70:73]
	v_mfma_f32_16x16x32_bf16 v[66:69], v[214:217], v[190:193], v[66:69]
	v_mfma_f32_16x16x32_bf16 v[118:121], v[206:209], v[162:165], v[118:121]
	v_mfma_f32_16x16x32_bf16 v[114:117], v[218:221], v[162:165], v[114:117]
	v_mfma_f32_16x16x32_bf16 v[102:105], v[206:209], v[170:173], v[102:105]
	v_mfma_f32_16x16x32_bf16 v[98:101], v[218:221], v[170:173], v[98:101]
	v_mfma_f32_16x16x32_bf16 v[86:89], v[206:209], v[186:189], v[86:89]
	v_mfma_f32_16x16x32_bf16 v[82:85], v[218:221], v[186:189], v[82:85]
	v_mfma_f32_16x16x32_bf16 v[70:73], v[206:209], v[198:201], v[70:73]
	v_mfma_f32_16x16x32_bf16 v[66:69], v[218:221], v[198:201], v[66:69]
	s_mov_b32 m0, s37
	v_lshl_add_u64 v[180:181], v[184:185], 0, s[70:71]
	s_barrier
	ds_read_b128 v[158:161], v138 offset:49152
	ds_read_b128 v[162:165], v138 offset:50176
	ds_read_b128 v[166:169], v138 offset:51200
	ds_read_b128 v[170:173], v138 offset:52224
	ds_read_b128 v[174:177], v138 offset:53248
	ds_read_b128 v[186:189], v138 offset:54272
	ds_read_b128 v[190:193], v138 offset:55296
	ds_read_b128 v[198:201], v138 offset:56320
	global_load_lds_dwordx4 v[180:181], off
	v_lshl_add_u64 v[180:181], v[222:223], 0, s[70:71]
	s_mov_b32 m0, s38
	s_nop 0
	global_load_lds_dwordx4 v[180:181], off
	s_barrier
	s_waitcnt lgkmcnt(0)
	s_waitcnt lgkmcnt(0)
	v_mfma_f32_16x16x32_bf16 v[62:65], v[140:143], v[158:161], v[62:65]
	v_mfma_f32_16x16x32_bf16 v[58:61], v[150:153], v[158:161], v[58:61]
	v_mfma_f32_16x16x32_bf16 v[46:49], v[140:143], v[166:169], v[46:49]
	v_mfma_f32_16x16x32_bf16 v[42:45], v[150:153], v[166:169], v[42:45]
	v_mfma_f32_16x16x32_bf16 v[30:33], v[140:143], v[174:177], v[30:33]
	v_mfma_f32_16x16x32_bf16 v[26:29], v[150:153], v[174:177], v[26:29]
	v_mfma_f32_16x16x32_bf16 v[14:17], v[140:143], v[190:193], v[14:17]
	v_mfma_f32_16x16x32_bf16 v[10:13], v[150:153], v[190:193], v[10:13]
	v_mfma_f32_16x16x32_bf16 v[62:65], v[144:147], v[162:165], v[62:65]
	v_mfma_f32_16x16x32_bf16 v[58:61], v[154:157], v[162:165], v[58:61]
	v_mfma_f32_16x16x32_bf16 v[46:49], v[144:147], v[170:173], v[46:49]
	v_mfma_f32_16x16x32_bf16 v[42:45], v[154:157], v[170:173], v[42:45]
	v_mfma_f32_16x16x32_bf16 v[30:33], v[144:147], v[186:189], v[30:33]
	v_mfma_f32_16x16x32_bf16 v[26:29], v[154:157], v[186:189], v[26:29]
	v_mfma_f32_16x16x32_bf16 v[14:17], v[144:147], v[198:201], v[14:17]
	v_mfma_f32_16x16x32_bf16 v[10:13], v[154:157], v[198:201], v[10:13]
	s_barrier
	s_add_i32 s1, s18, s30
	v_lshl_add_u64 v[140:141], v[224:225], 0, s[70:71]
	s_mov_b32 m0, s1
	s_nop 0
	global_load_lds_dwordx4 v[140:141], off
	v_lshl_add_u64 v[140:141], v[226:227], 0, s[70:71]
	s_add_i32 m0, s1, 0x2000
	s_nop 0
	global_load_lds_dwordx4 v[140:141], off
	s_waitcnt vmcnt(8)
	s_barrier
	v_mfma_f32_16x16x32_bf16 v[54:57], v[202:205], v[158:161], v[54:57]
	v_mfma_f32_16x16x32_bf16 v[50:53], v[214:217], v[158:161], v[50:53]
	v_mfma_f32_16x16x32_bf16 v[38:41], v[202:205], v[166:169], v[38:41]
	v_mfma_f32_16x16x32_bf16 v[34:37], v[214:217], v[166:169], v[34:37]
	v_mfma_f32_16x16x32_bf16 v[22:25], v[202:205], v[174:177], v[22:25]
	v_mfma_f32_16x16x32_bf16 v[18:21], v[214:217], v[174:177], v[18:21]
	v_mfma_f32_16x16x32_bf16 v[6:9], v[202:205], v[190:193], v[6:9]
	v_mfma_f32_16x16x32_bf16 v[2:5], v[214:217], v[190:193], v[2:5]
	v_mfma_f32_16x16x32_bf16 v[54:57], v[206:209], v[162:165], v[54:57]
	v_mfma_f32_16x16x32_bf16 v[50:53], v[218:221], v[162:165], v[50:53]
	v_mfma_f32_16x16x32_bf16 v[38:41], v[206:209], v[170:173], v[38:41]
	v_mfma_f32_16x16x32_bf16 v[34:37], v[218:221], v[170:173], v[34:37]
	v_mfma_f32_16x16x32_bf16 v[22:25], v[206:209], v[186:189], v[22:25]
	v_mfma_f32_16x16x32_bf16 v[18:21], v[218:221], v[186:189], v[18:21]
	v_mfma_f32_16x16x32_bf16 v[6:9], v[206:209], v[198:201], v[6:9]
	v_mfma_f32_16x16x32_bf16 v[2:5], v[218:221], v[198:201], v[2:5]
	s_add_u32 s16, s16, 0x100
	s_addc_u32 s17, s17, 0
	s_cmp_ge_i32 s41, s39
	s_mov_b32 s1, s41
	s_barrier
	s_cbranch_scc0 .LBB0_137

; #define PG8_STAGE(bufoff, gbase, voff) do { _Pragma("unroll") for (int _i = 0; _i < 2; ++_i) \
;     __builtin_amdgcn_global_load_lds((const unsigned*)((const char*)(gbase) + (voff)[_i]), (LAS unsigned*)(lds + (bufoff) + ldsw + _i * 8192), 16, 0, 0); } while (0)
; #define PG8_LDA(dst, b, h) do { _Pragma("unroll") for (int m = 0; m < 4; ++m) _Pragma("unroll") for (int k = 0; k < 2; ++k) dst[m][k] = *(const LAS bf16x8*)(lds + PG8_SA(b, h) + aoff + m * 2048 + k * 1024); } while (0)
; #define PG8_LDB(dst, b, h) do { _Pragma("unroll") for (int n = 0; n < 2; ++n) _Pragma("unroll") for (int k = 0; k < 2; ++k) dst[n][k] = *(const LAS bf16x8*)(lds + PG8_SB(b, h) + boff + n * 2048 + k * 1024); } while (0)
; #define PG8_MMA(ai, bj, At, Bt) do { __builtin_amdgcn_s_setprio(1); _Pragma("unroll") for (int m = 0; m < 4; ++m) _Pragma("unroll") for (int n = 0; n < 2; ++n) _Pragma("unroll") for (int k = 0; k < 2; ++k) \
;     acc[ai][bj][m][n] = __builtin_amdgcn_mfma_f32_16x16x32_bf16(Bt[n][k], At[m][k], acc[ai][bj][m][n], 0, 0, 0); __builtin_amdgcn_s_setprio(0); } while (0)
; #define PG8_WAIT_L(n) asm volatile("s_waitcnt lgkmcnt(" #n ")" ::: "memory")
; #define PG8_BAR __builtin_amdgcn_s_barrier()
; #define PG8_SCHED __builtin_amdgcn_sched_barrier(0)
; template <class Epi, class Sched>
; DI void gemm_phase(LAS unsigned char* lds, const Gemm g, const Sched& S, const Epi& E) {
;     ...
;       const bool last = (t == nt - 2);
;       const char* a1 = cA + (size_t)(t + 1) * kstep;
;       const char* a2 = last ? nA : cA + (size_t)(t + 2) * kstep; const char* b2 = last ? nB : cB + (size_t)(t + 2) * kstep;
;       const char* a3 = a2 + kstep; const char* b3 = b2 + kstep;
;       PG8_LDB(B0, 0, 0); PG8_SCHED; PG8_LDA(At, 0, 0); PG8_STAGE(PG8_SA(1, 1), a1 + hstep, voffA);
;       PG8_WAIT_L(8); PG8_BAR; PG8_WAIT_L(0); PG8_MMA(0, 0, At, B0); PG8_BAR; PG8_SCHED;
;       PG8_LDB(B1, 0, 1); PG8_STAGE(PG8_SB(0, 0), b2, voffB);
;       PG8_BAR; PG8_WAIT_L(0); PG8_MMA(0, 1, At, B1); PG8_BAR;
;       PG8_LDA(At, 0, 1); PG8_STAGE(PG8_SA(0, 0), a2, voffA);
;       PG8_BAR; PG8_WAIT_L(0); PG8_MMA(1, 0, At, B0); PG8_BAR; PG8_SCHED;
.LBB0_153:
	s_add_i32 s36, s16, 2
	s_add_u32 s17, s14, 0xfa800080
	s_addc_u32 s18, s15, -1
	s_cmp_lg_u32 s35, s16
	s_cselect_b32 s19, s18, 0
	s_cselect_b32 s18, s17, 0
	s_add_u32 s16, s12, s18
	s_addc_u32 s17, s13, s19
	s_add_i32 s37, 16, 0x10000
	v_add_u32_e32 v139, s37, v137
	ds_read_b128 v[140:143], v139
	ds_read_b128 v[144:147], v139 offset:1024
	ds_read_b128 v[150:153], v139 offset:2048
	ds_read_b128 v[154:157], v139 offset:3072
	s_add_u32 s18, s2, s18
	s_addc_u32 s19, s3, s19
	v_lshl_add_u64 v[180:181], v[132:133], 0, s[14:15]
	s_add_i32 m0, s24, 0xc000
	ds_read_b128 v[158:161], v138
	ds_read_b128 v[162:165], v138 offset:1024
	ds_read_b128 v[166:169], v138 offset:2048
	ds_read_b128 v[170:173], v138 offset:3072
	ds_read_b128 v[174:177], v138 offset:4096
	ds_read_b128 v[186:189], v138 offset:5120
	ds_read_b128 v[190:193], v138 offset:6144
	ds_read_b128 v[198:201], v138 offset:7168
	global_load_lds_dwordx4 v[180:181], off
	v_lshl_add_u64 v[180:181], v[134:135], 0, s[14:15]
	s_add_i32 m0, s24, 0xe000
	s_nop 0
	global_load_lds_dwordx4 v[180:181], off
	s_waitcnt lgkmcnt(8)
	s_barrier
	s_waitcnt lgkmcnt(0)
	s_waitcnt lgkmcnt(0)
	v_mfma_f32_16x16x32_bf16 v[126:129], v[140:143], v[158:161], v[126:129]
	v_mfma_f32_16x16x32_bf16 v[122:125], v[150:153], v[158:161], v[122:125]
	v_mfma_f32_16x16x32_bf16 v[110:113], v[140:143], v[166:169], v[110:113]
	v_mfma_f32_16x16x32_bf16 v[106:109], v[150:153], v[166:169], v[106:109]
	v_mfma_f32_16x16x32_bf16 v[94:97], v[140:143], v[174:177], v[94:97]
	v_mfma_f32_16x16x32_bf16 v[90:93], v[150:153], v[174:177], v[90:93]
	v_mfma_f32_16x16x32_bf16 v[78:81], v[140:143], v[190:193], v[78:81]
	v_mfma_f32_16x16x32_bf16 v[74:77], v[150:153], v[190:193], v[74:77]
	v_mfma_f32_16x16x32_bf16 v[126:129], v[144:147], v[162:165], v[126:129]
	v_mfma_f32_16x16x32_bf16 v[122:125], v[154:157], v[162:165], v[122:125]
	v_mfma_f32_16x16x32_bf16 v[110:113], v[144:147], v[170:173], v[110:113]
	v_mfma_f32_16x16x32_bf16 v[106:109], v[154:157], v[170:173], v[106:109]
	v_mfma_f32_16x16x32_bf16 v[94:97], v[144:147], v[186:189], v[94:97]
	v_mfma_f32_16x16x32_bf16 v[90:93], v[154:157], v[186:189], v[90:93]
	v_mfma_f32_16x16x32_bf16 v[78:81], v[144:147], v[198:201], v[78:81]
	v_mfma_f32_16x16x32_bf16 v[74:77], v[154:157], v[198:201], v[74:77]
	s_barrier
	s_add_i32 s38, 16, 0x14000
	s_add_i32 s37, s37, s23
	v_add_u32_e32 v139, s38, v137
	v_lshl_add_u64 v[180:181], s[18:19], 0, v[0:1]
	s_mov_b32 m0, s37
	ds_read_b128 v[202:205], v139
	ds_read_b128 v[206:209], v139 offset:1024
	ds_read_b128 v[214:217], v139 offset:2048
	ds_read_b128 v[218:221], v139 offset:3072
	global_load_lds_dwordx4 v[180:181], off
	v_lshl_add_u64 v[182:183], s[18:19], 0, v[130:131]
	s_add_i32 m0, s37, 0x2000
	s_nop 0
	global_load_lds_dwordx4 v[182:183], off
	s_waitcnt vmcnt(10)
	s_barrier
	s_waitcnt lgkmcnt(0)
	s_waitcnt lgkmcnt(0)
	v_mfma_f32_16x16x32_bf16 v[118:121], v[202:205], v[158:161], v[118:121]
	v_mfma_f32_16x16x32_bf16 v[114:117], v[214:217], v[158:161], v[114:117]
	v_mfma_f32_16x16x32_bf16 v[102:105], v[202:205], v[166:169], v[102:105]
	v_mfma_f32_16x16x32_bf16 v[98:101], v[214:217], v[166:169], v[98:101]
	v_mfma_f32_16x16x32_bf16 v[86:89], v[202:205], v[174:177], v[86:89]
	v_mfma_f32_16x16x32_bf16 v[82:85], v[214:217], v[174:177], v[82:85]
	v_mfma_f32_16x16x32_bf16 v[70:73], v[202:205], v[190:193], v[70:73]
	v_mfma_f32_16x16x32_bf16 v[66:69], v[214:217], v[190:193], v[66:69]
	v_mfma_f32_16x16x32_bf16 v[118:121], v[206:209], v[162:165], v[118:121]
	v_mfma_f32_16x16x32_bf16 v[114:117], v[218:221], v[162:165], v[114:117]
	v_mfma_f32_16x16x32_bf16 v[102:105], v[206:209], v[170:173], v[102:105]
	v_mfma_f32_16x16x32_bf16 v[98:101], v[218:221], v[170:173], v[98:101]
	v_mfma_f32_16x16x32_bf16 v[86:89], v[206:209], v[186:189], v[86:89]
	v_mfma_f32_16x16x32_bf16 v[82:85], v[218:221], v[186:189], v[82:85]
	v_mfma_f32_16x16x32_bf16 v[70:73], v[206:209], v[198:201], v[70:73]
	v_mfma_f32_16x16x32_bf16 v[66:69], v[218:221], v[198:201], v[66:69]
	s_mov_b32 m0, s24
	v_lshl_add_u64 v[184:185], s[16:17], 0, v[0:1]
	s_barrier
	ds_read_b128 v[158:161], v138 offset:16384
	ds_read_b128 v[162:165], v138 offset:17408
	ds_read_b128 v[166:169], v138 offset:18432
	ds_read_b128 v[170:173], v138 offset:19456
	ds_read_b128 v[174:177], v138 offset:20480
	ds_read_b128 v[186:189], v138 offset:21504
	ds_read_b128 v[190:193], v138 offset:22528
	ds_read_b128 v[198:201], v138 offset:23552
	global_load_lds_dwordx4 v[184:185], off
	v_lshl_add_u64 v[222:223], s[16:17], 0, v[130:131]
	s_mov_b32 m0, s25
	s_nop 0
	global_load_lds_dwordx4 v[222:223], off
	s_barrier
	s_waitcnt lgkmcnt(0)
	s_waitcnt lgkmcnt(0)
	v_mfma_f32_16x16x32_bf16 v[62:65], v[140:143], v[158:161], v[62:65]
	v_mfma_f32_16x16x32_bf16 v[58:61], v[150:153], v[158:161], v[58:61]
	v_mfma_f32_16x16x32_bf16 v[46:49], v[140:143], v[166:169], v[46:49]
	v_mfma_f32_16x16x32_bf16 v[42:45], v[150:153], v[166:169], v[42:45]
	v_mfma_f32_16x16x32_bf16 v[30:33], v[140:143], v[174:177], v[30:33]
	v_mfma_f32_16x16x32_bf16 v[26:29], v[150:153], v[174:177], v[26:29]
	v_mfma_f32_16x16x32_bf16 v[14:17], v[140:143], v[190:193], v[14:17]
	v_mfma_f32_16x16x32_bf16 v[10:13], v[150:153], v[190:193], v[10:13]
	v_mfma_f32_16x16x32_bf16 v[62:65], v[144:147], v[162:165], v[62:65]
	v_mfma_f32_16x16x32_bf16 v[58:61], v[154:157], v[162:165], v[58:61]
	v_mfma_f32_16x16x32_bf16 v[46:49], v[144:147], v[170:173], v[46:49]
	v_mfma_f32_16x16x32_bf16 v[42:45], v[154:157], v[170:173], v[42:45]
	v_mfma_f32_16x16x32_bf16 v[30:33], v[144:147], v[186:189], v[30:33]
	v_mfma_f32_16x16x32_bf16 v[26:29], v[154:157], v[186:189], v[26:29]
	v_mfma_f32_16x16x32_bf16 v[14:17], v[144:147], v[198:201], v[14:17]
	v_mfma_f32_16x16x32_bf16 v[10:13], v[154:157], v[198:201], v[10:13]
	s_barrier
; #define PG8_STAGE(bufoff, gbase, voff) do { _Pragma("unroll") for (int _i = 0; _i < 2; ++_i) \
;     __builtin_amdgcn_global_load_lds((const unsigned*)((const char*)(gbase) + (voff)[_i]), (LAS unsigned*)(lds + (bufoff) + ldsw + _i * 8192), 16, 0, 0); } while (0)
; #define PG8_LDA(dst, b, h) do { _Pragma("unroll") for (int m = 0; m < 4; ++m) _Pragma("unroll") for (int k = 0; k < 2; ++k) dst[m][k] = *(const LAS bf16x8*)(lds + PG8_SA(b, h) + aoff + m * 2048 + k * 1024); } while (0)
; #define PG8_LDB(dst, b, h) do { _Pragma("unroll") for (int n = 0; n < 2; ++n) _Pragma("unroll") for (int k = 0; k < 2; ++k) dst[n][k] = *(const LAS bf16x8*)(lds + PG8_SB(b, h) + boff + n * 2048 + k * 1024); } while (0)
; #define PG8_MMA(ai, bj, At, Bt) do { __builtin_amdgcn_s_setprio(1); _Pragma("unroll") for (int m = 0; m < 4; ++m) _Pragma("unroll") for (int n = 0; n < 2; ++n) _Pragma("unroll") for (int k = 0; k < 2; ++k) \
;     acc[ai][bj][m][n] = __builtin_amdgcn_mfma_f32_16x16x32_bf16(Bt[n][k], At[m][k], acc[ai][bj][m][n], 0, 0, 0); __builtin_amdgcn_s_setprio(0); } while (0)
; #define PG8_WAIT_V(n) asm volatile("s_waitcnt vmcnt(" #n ")" ::: "memory")
; #define PG8_WAIT_L(n) asm volatile("s_waitcnt lgkmcnt(" #n ")" ::: "memory")
; #define PG8_BAR __builtin_amdgcn_s_barrier()
; #define PG8_SCHED __builtin_amdgcn_sched_barrier(0)
; template <class Epi, class Sched>
; DI void gemm_phase(LAS unsigned char* lds, const Gemm g, const Sched& S, const Epi& E) {
;     ...
;       PG8_STAGE(PG8_SB(0, 1), b2 + hstepB, voffB);
;       PG8_WAIT_V(6); PG8_BAR; PG8_MMA(1, 1, At, B1); PG8_BAR;
;       PG8_LDB(B0, 1, 0); PG8_SCHED; PG8_LDA(At, 1, 0); PG8_STAGE(PG8_SA(0, 1), a2 + hstep, voffA);
;       PG8_WAIT_L(8); PG8_BAR; PG8_WAIT_L(0); PG8_MMA(0, 0, At, B0); PG8_BAR; PG8_SCHED;
;       PG8_LDB(B1, 1, 1); PG8_STAGE(PG8_SB(1, 0), b3, voffB);
	s_add_u32 s18, s18, s0
	s_addc_u32 s19, s19, s1
	s_add_i32 s37, s38, s23
	v_lshl_add_u64 v[224:225], s[18:19], 0, v[0:1]
	s_mov_b32 m0, s37
	v_lshl_add_u64 v[226:227], s[18:19], 0, v[130:131]
	global_load_lds_dwordx4 v[224:225], off
	s_add_i32 m0, s37, 0x2000
	s_nop 0
	global_load_lds_dwordx4 v[226:227], off
	s_waitcnt vmcnt(8)
	s_barrier
	v_mfma_f32_16x16x32_bf16 v[54:57], v[202:205], v[158:161], v[54:57]
	v_mfma_f32_16x16x32_bf16 v[50:53], v[214:217], v[158:161], v[50:53]
	v_mfma_f32_16x16x32_bf16 v[38:41], v[202:205], v[166:169], v[38:41]
	v_mfma_f32_16x16x32_bf16 v[34:37], v[214:217], v[166:169], v[34:37]
	v_mfma_f32_16x16x32_bf16 v[22:25], v[202:205], v[174:177], v[22:25]
	v_mfma_f32_16x16x32_bf16 v[18:21], v[214:217], v[174:177], v[18:21]
	v_mfma_f32_16x16x32_bf16 v[6:9], v[202:205], v[190:193], v[6:9]
	v_mfma_f32_16x16x32_bf16 v[2:5], v[214:217], v[190:193], v[2:5]
	v_mfma_f32_16x16x32_bf16 v[54:57], v[206:209], v[162:165], v[54:57]
	v_mfma_f32_16x16x32_bf16 v[50:53], v[218:221], v[162:165], v[50:53]
	v_mfma_f32_16x16x32_bf16 v[38:41], v[206:209], v[170:173], v[38:41]
	v_mfma_f32_16x16x32_bf16 v[34:37], v[218:221], v[170:173], v[34:37]
	v_mfma_f32_16x16x32_bf16 v[22:25], v[206:209], v[186:189], v[22:25]
	v_mfma_f32_16x16x32_bf16 v[18:21], v[218:221], v[186:189], v[18:21]
	v_mfma_f32_16x16x32_bf16 v[6:9], v[206:209], v[198:201], v[6:9]
	v_mfma_f32_16x16x32_bf16 v[2:5], v[218:221], v[198:201], v[2:5]
	s_add_i32 s18, 16, 0x18000
	v_add_u32_e32 v139, s18, v137
	s_barrier
	ds_read_b128 v[140:143], v139
	ds_read_b128 v[144:147], v139 offset:1024
	ds_read_b128 v[150:153], v139 offset:2048
	ds_read_b128 v[154:157], v139 offset:3072
	s_add_u32 s16, s16, s0
	s_addc_u32 s17, s17, s1
	s_mov_b32 m0, s26
	v_lshl_add_u64 v[202:203], s[16:17], 0, v[0:1]
	ds_read_b128 v[158:161], v138 offset:32768
	ds_read_b128 v[162:165], v138 offset:33792
	ds_read_b128 v[166:169], v138 offset:34816
	ds_read_b128 v[170:173], v138 offset:35840
	ds_read_b128 v[174:177], v138 offset:36864
	ds_read_b128 v[186:189], v138 offset:37888
	ds_read_b128 v[190:193], v138 offset:38912
	ds_read_b128 v[198:201], v138 offset:39936
	global_load_lds_dwordx4 v[202:203], off
	v_lshl_add_u64 v[202:203], s[16:17], 0, v[130:131]
	s_mov_b32 m0, s27
	s_nop 0
	global_load_lds_dwordx4 v[202:203], off
	s_waitcnt lgkmcnt(8)
	s_barrier
	s_waitcnt lgkmcnt(0)
	s_waitcnt lgkmcnt(0)
	v_mfma_f32_16x16x32_bf16 v[126:129], v[140:143], v[158:161], v[126:129]
	v_mfma_f32_16x16x32_bf16 v[122:125], v[150:153], v[158:161], v[122:125]
	v_mfma_f32_16x16x32_bf16 v[110:113], v[140:143], v[166:169], v[110:113]
	v_mfma_f32_16x16x32_bf16 v[106:109], v[150:153], v[166:169], v[106:109]
	v_mfma_f32_16x16x32_bf16 v[94:97], v[140:143], v[174:177], v[94:97]
	v_mfma_f32_16x16x32_bf16 v[90:93], v[150:153], v[174:177], v[90:93]
	v_mfma_f32_16x16x32_bf16 v[78:81], v[140:143], v[190:193], v[78:81]
	v_mfma_f32_16x16x32_bf16 v[74:77], v[150:153], v[190:193], v[74:77]
	v_mfma_f32_16x16x32_bf16 v[126:129], v[144:147], v[162:165], v[126:129]
	v_mfma_f32_16x16x32_bf16 v[122:125], v[154:157], v[162:165], v[122:125]
	v_mfma_f32_16x16x32_bf16 v[110:113], v[144:147], v[170:173], v[110:113]
	v_mfma_f32_16x16x32_bf16 v[106:109], v[154:157], v[170:173], v[106:109]
	v_mfma_f32_16x16x32_bf16 v[94:97], v[144:147], v[186:189], v[94:97]
	v_mfma_f32_16x16x32_bf16 v[90:93], v[154:157], v[186:189], v[90:93]
	v_mfma_f32_16x16x32_bf16 v[78:81], v[144:147], v[198:201], v[78:81]
	v_mfma_f32_16x16x32_bf16 v[74:77], v[154:157], v[198:201], v[74:77]
	s_barrier
	s_add_i32 s16, 16, 0x1c000
	s_add_i32 s17, s18, s23
	v_add_u32_e32 v139, s16, v137
	v_lshl_add_u64 v[180:181], v[180:181], 0, s[70:71]
	s_mov_b32 m0, s17
	ds_read_b128 v[202:205], v139
	ds_read_b128 v[206:209], v139 offset:1024
	ds_read_b128 v[214:217], v139 offset:2048
	ds_read_b128 v[218:221], v139 offset:3072
	global_load_lds_dwordx4 v[180:181], off
	v_lshl_add_u64 v[180:181], v[182:183], 0, s[70:71]
	s_add_i32 m0, s17, 0x2000
	s_nop 0
	global_load_lds_dwordx4 v[180:181], off
	s_waitcnt vmcnt(10)
	s_barrier
; #define PG8_STAGE(bufoff, gbase, voff) do { _Pragma("unroll") for (int _i = 0; _i < 2; ++_i) \
;     __builtin_amdgcn_global_load_lds((const unsigned*)((const char*)(gbase) + (voff)[_i]), (LAS unsigned*)(lds + (bufoff) + ldsw + _i * 8192), 16, 0, 0); } while (0)
; #define PG8_LDA(dst, b, h) do { _Pragma("unroll") for (int m = 0; m < 4; ++m) _Pragma("unroll") for (int k = 0; k < 2; ++k) dst[m][k] = *(const LAS bf16x8*)(lds + PG8_SA(b, h) + aoff + m * 2048 + k * 1024); } while (0)
; #define PG8_LDB(dst, b, h) do { _Pragma("unroll") for (int n = 0; n < 2; ++n) _Pragma("unroll") for (int k = 0; k < 2; ++k) dst[n][k] = *(const LAS bf16x8*)(lds + PG8_SB(b, h) + boff + n * 2048 + k * 1024); } while (0)
; #define PG8_MMA(ai, bj, At, Bt) do { __builtin_amdgcn_s_setprio(1); _Pragma("unroll") for (int m = 0; m < 4; ++m) _Pragma("unroll") for (int n = 0; n < 2; ++n) _Pragma("unroll") for (int k = 0; k < 2; ++k) \
;     acc[ai][bj][m][n] = __builtin_amdgcn_mfma_f32_16x16x32_bf16(Bt[n][k], At[m][k], acc[ai][bj][m][n], 0, 0, 0); __builtin_amdgcn_s_setprio(0); } while (0)
; #define PG8_WAIT_V(n) asm volatile("s_waitcnt vmcnt(" #n ")" ::: "memory")
; #define PG8_WAIT_L(n) asm volatile("s_waitcnt lgkmcnt(" #n ")" ::: "memory")
; #define PG8_BAR __builtin_amdgcn_s_barrier()
; #define PG8_SCHED __builtin_amdgcn_sched_barrier(0)
; template <class Epi, class Sched>
; DI void gemm_phase(LAS unsigned char* lds, const Gemm g, const Sched& S, const Epi& E) {
;     ...
;       PG8_LDB(B1, 1, 1); PG8_STAGE(PG8_SB(1, 0), b3, voffB);
;       PG8_BAR; PG8_WAIT_L(0); PG8_MMA(0, 1, At, B1); PG8_BAR;
;       PG8_LDA(At, 1, 1); PG8_STAGE(PG8_SA(1, 0), a3, voffA);
;       PG8_BAR; PG8_WAIT_L(0); PG8_MMA(1, 0, At, B0); PG8_BAR; PG8_SCHED;
;       PG8_STAGE(PG8_SB(1, 1), b3 + hstepB, voffB);
;       PG8_WAIT_V(6); PG8_BAR; PG8_MMA(1, 1, At, B1); PG8_BAR;
;     }
	s_waitcnt lgkmcnt(0)
	s_waitcnt lgkmcnt(0)
	v_mfma_f32_16x16x32_bf16 v[118:121], v[202:205], v[158:161], v[118:121]
	v_mfma_f32_16x16x32_bf16 v[114:117], v[214:217], v[158:161], v[114:117]
	v_mfma_f32_16x16x32_bf16 v[102:105], v[202:205], v[166:169], v[102:105]
	v_mfma_f32_16x16x32_bf16 v[98:101], v[214:217], v[166:169], v[98:101]
	v_mfma_f32_16x16x32_bf16 v[86:89], v[202:205], v[174:177], v[86:89]
	v_mfma_f32_16x16x32_bf16 v[82:85], v[214:217], v[174:177], v[82:85]
	v_mfma_f32_16x16x32_bf16 v[70:73], v[202:205], v[190:193], v[70:73]
	v_mfma_f32_16x16x32_bf16 v[66:69], v[214:217], v[190:193], v[66:69]
	v_mfma_f32_16x16x32_bf16 v[118:121], v[206:209], v[162:165], v[118:121]
	v_mfma_f32_16x16x32_bf16 v[114:117], v[218:221], v[162:165], v[114:117]
	v_mfma_f32_16x16x32_bf16 v[102:105], v[206:209], v[170:173], v[102:105]
	v_mfma_f32_16x16x32_bf16 v[98:101], v[218:221], v[170:173], v[98:101]
	v_mfma_f32_16x16x32_bf16 v[86:89], v[206:209], v[186:189], v[86:89]
	v_mfma_f32_16x16x32_bf16 v[82:85], v[218:221], v[186:189], v[82:85]
	v_mfma_f32_16x16x32_bf16 v[70:73], v[206:209], v[198:201], v[70:73]
	v_mfma_f32_16x16x32_bf16 v[66:69], v[218:221], v[198:201], v[66:69]
	s_mov_b32 m0, s30
	v_lshl_add_u64 v[180:181], v[184:185], 0, s[70:71]
	s_barrier
	ds_read_b128 v[158:161], v138 offset:49152
	ds_read_b128 v[162:165], v138 offset:50176
	ds_read_b128 v[166:169], v138 offset:51200
	ds_read_b128 v[170:173], v138 offset:52224
	ds_read_b128 v[174:177], v138 offset:53248
	ds_read_b128 v[186:189], v138 offset:54272
	ds_read_b128 v[190:193], v138 offset:55296
	ds_read_b128 v[198:201], v138 offset:56320
	global_load_lds_dwordx4 v[180:181], off
	v_lshl_add_u64 v[180:181], v[222:223], 0, s[70:71]
	s_mov_b32 m0, s31
	s_nop 0
	global_load_lds_dwordx4 v[180:181], off
	s_barrier
	s_waitcnt lgkmcnt(0)
	s_waitcnt lgkmcnt(0)
	v_mfma_f32_16x16x32_bf16 v[62:65], v[140:143], v[158:161], v[62:65]
	v_mfma_f32_16x16x32_bf16 v[58:61], v[150:153], v[158:161], v[58:61]
	v_mfma_f32_16x16x32_bf16 v[46:49], v[140:143], v[166:169], v[46:49]
	v_mfma_f32_16x16x32_bf16 v[42:45], v[150:153], v[166:169], v[42:45]
	v_mfma_f32_16x16x32_bf16 v[30:33], v[140:143], v[174:177], v[30:33]
	v_mfma_f32_16x16x32_bf16 v[26:29], v[150:153], v[174:177], v[26:29]
	v_mfma_f32_16x16x32_bf16 v[14:17], v[140:143], v[190:193], v[14:17]
	v_mfma_f32_16x16x32_bf16 v[10:13], v[150:153], v[190:193], v[10:13]
	v_mfma_f32_16x16x32_bf16 v[62:65], v[144:147], v[162:165], v[62:65]
	v_mfma_f32_16x16x32_bf16 v[58:61], v[154:157], v[162:165], v[58:61]
	v_mfma_f32_16x16x32_bf16 v[46:49], v[144:147], v[170:173], v[46:49]
	v_mfma_f32_16x16x32_bf16 v[42:45], v[154:157], v[170:173], v[42:45]
	v_mfma_f32_16x16x32_bf16 v[30:33], v[144:147], v[186:189], v[30:33]
	v_mfma_f32_16x16x32_bf16 v[26:29], v[154:157], v[186:189], v[26:29]
	v_mfma_f32_16x16x32_bf16 v[14:17], v[144:147], v[198:201], v[14:17]
	v_mfma_f32_16x16x32_bf16 v[10:13], v[154:157], v[198:201], v[10:13]
	s_barrier
	s_add_i32 s16, s16, s23
	v_lshl_add_u64 v[140:141], v[224:225], 0, s[70:71]
	s_mov_b32 m0, s16
	s_nop 0
	global_load_lds_dwordx4 v[140:141], off
	v_lshl_add_u64 v[140:141], v[226:227], 0, s[70:71]
	s_add_i32 m0, s16, 0x2000
	s_nop 0
	global_load_lds_dwordx4 v[140:141], off
	s_waitcnt vmcnt(8)
	s_barrier
	v_mfma_f32_16x16x32_bf16 v[54:57], v[202:205], v[158:161], v[54:57]
	v_mfma_f32_16x16x32_bf16 v[50:53], v[214:217], v[158:161], v[50:53]
	v_mfma_f32_16x16x32_bf16 v[38:41], v[202:205], v[166:169], v[38:41]
	v_mfma_f32_16x16x32_bf16 v[34:37], v[214:217], v[166:169], v[34:37]
	v_mfma_f32_16x16x32_bf16 v[22:25], v[202:205], v[174:177], v[22:25]
	v_mfma_f32_16x16x32_bf16 v[18:21], v[214:217], v[174:177], v[18:21]
	v_mfma_f32_16x16x32_bf16 v[6:9], v[202:205], v[190:193], v[6:9]
	v_mfma_f32_16x16x32_bf16 v[2:5], v[214:217], v[190:193], v[2:5]
	v_mfma_f32_16x16x32_bf16 v[54:57], v[206:209], v[162:165], v[54:57]
	v_mfma_f32_16x16x32_bf16 v[50:53], v[218:221], v[162:165], v[50:53]
	v_mfma_f32_16x16x32_bf16 v[38:41], v[206:209], v[170:173], v[38:41]
	v_mfma_f32_16x16x32_bf16 v[34:37], v[218:221], v[170:173], v[34:37]
	v_mfma_f32_16x16x32_bf16 v[22:25], v[206:209], v[186:189], v[22:25]
	v_mfma_f32_16x16x32_bf16 v[18:21], v[218:221], v[186:189], v[18:21]
	v_mfma_f32_16x16x32_bf16 v[6:9], v[206:209], v[198:201], v[6:9]
	v_mfma_f32_16x16x32_bf16 v[2:5], v[218:221], v[198:201], v[2:5]
	s_add_u32 s14, s14, 0x100
	s_addc_u32 s15, s15, 0
	s_cmp_ge_i32 s36, s34
	s_mov_b32 s16, s36
	s_barrier
	s_cbranch_scc0 .LBB0_153

; #define PG8_STAGE(bufoff, gbase, voff) do { _Pragma("unroll") for (int _i = 0; _i < 2; ++_i) \
;     __builtin_amdgcn_global_load_lds((const unsigned*)((const char*)(gbase) + (voff)[_i]), (LAS unsigned*)(lds + (bufoff) + ldsw + _i * 8192), 16, 0, 0); } while (0)
; #define PG8_LDA(dst, b, h) do { _Pragma("unroll") for (int m = 0; m < 4; ++m) _Pragma("unroll") for (int k = 0; k < 2; ++k) dst[m][k] = *(const LAS bf16x8*)(lds + PG8_SA(b, h) + aoff + m * 2048 + k * 1024); } while (0)
; #define PG8_LDB(dst, b, h) do { _Pragma("unroll") for (int n = 0; n < 2; ++n) _Pragma("unroll") for (int k = 0; k < 2; ++k) dst[n][k] = *(const LAS bf16x8*)(lds + PG8_SB(b, h) + boff + n * 2048 + k * 1024); } while (0)
; #define PG8_MMA(ai, bj, At, Bt) do { __builtin_amdgcn_s_setprio(1); _Pragma("unroll") for (int m = 0; m < 4; ++m) _Pragma("unroll") for (int n = 0; n < 2; ++n) _Pragma("unroll") for (int k = 0; k < 2; ++k) \
;     acc[ai][bj][m][n] = __builtin_amdgcn_mfma_f32_16x16x32_bf16(Bt[n][k], At[m][k], acc[ai][bj][m][n], 0, 0, 0); __builtin_amdgcn_s_setprio(0); } while (0)
; #define PG8_WAIT_L(n) asm volatile("s_waitcnt lgkmcnt(" #n ")" ::: "memory")
; #define PG8_BAR __builtin_amdgcn_s_barrier()
; #define PG8_SCHED __builtin_amdgcn_sched_barrier(0)
; template <class Epi, class Sched>
; DI void gemm_phase(LAS unsigned char* lds, const Gemm g, const Sched& S, const Epi& E) {
;     ...
;       const bool last = (t == nt - 2);
;       const char* a1 = cA + (size_t)(t + 1) * kstep;
;       const char* a2 = last ? nA : cA + (size_t)(t + 2) * kstep; const char* b2 = last ? nB : cB + (size_t)(t + 2) * kstep;
;       const char* a3 = a2 + kstep; const char* b3 = b2 + kstep;
;       PG8_LDB(B0, 0, 0); PG8_SCHED; PG8_LDA(At, 0, 0); PG8_STAGE(PG8_SA(1, 1), a1 + hstep, voffA);
;       PG8_WAIT_L(8); PG8_BAR; PG8_WAIT_L(0); PG8_MMA(0, 0, At, B0); PG8_BAR; PG8_SCHED;
;       PG8_LDB(B1, 0, 1); PG8_STAGE(PG8_SB(0, 0), b2, voffB);
;       PG8_BAR; PG8_WAIT_L(0); PG8_MMA(0, 1, At, B1); PG8_BAR;
;       PG8_LDA(At, 0, 1); PG8_STAGE(PG8_SA(0, 0), a2, voffA);
;       PG8_BAR; PG8_WAIT_L(0); PG8_MMA(1, 0, At, B0); PG8_BAR; PG8_SCHED;
.LBB0_178:
	s_add_i32 s51, s24, 2
	s_add_u32 s26, s22, 0x80
	s_addc_u32 s25, s23, 0
	s_add_i32 s52, 16, 0x10000
	v_add_u32_e32 v156, s52, v141
	ds_read_b128 v[144:147], v156
	ds_read_b128 v[148:151], v156 offset:1024
	ds_read_b128 v[152:155], v156 offset:2048
	ds_read_b128 v[156:159], v156 offset:3072
	s_cmp_eq_u32 s43, s24
	s_cselect_b32 s24, s18, s26
	s_cselect_b32 s25, s19, s25
	s_cselect_b32 s27, s21, s50
	s_cselect_b32 s26, s20, s49
	v_lshl_add_u64 v[176:177], s[22:23], 0, v[136:137]
	s_add_i32 m0, s36, 0xc000
	ds_read_b128 v[160:163], v143
	ds_read_b128 v[164:167], v143 offset:1024
	ds_read_b128 v[168:171], v143 offset:2048
	ds_read_b128 v[172:175], v143 offset:3072
	ds_read_b128 v[186:189], v143 offset:4096
	ds_read_b128 v[190:193], v143 offset:5120
	ds_read_b128 v[198:201], v143 offset:6144
	ds_read_b128 v[202:205], v143 offset:7168
	global_load_lds_dwordx4 v[176:177], off
	v_lshl_add_u64 v[176:177], s[22:23], 0, v[138:139]
	s_add_i32 m0, s36, 0xe000
	s_nop 0
	global_load_lds_dwordx4 v[176:177], off
	s_waitcnt lgkmcnt(8)
	s_barrier
	s_waitcnt lgkmcnt(0)
	s_waitcnt lgkmcnt(0)
	v_mfma_f32_16x16x32_bf16 v[122:125], v[144:147], v[160:163], v[122:125]
	v_mfma_f32_16x16x32_bf16 v[118:121], v[152:155], v[160:163], v[118:121]
	v_mfma_f32_16x16x32_bf16 v[110:113], v[144:147], v[168:171], v[110:113]
	v_mfma_f32_16x16x32_bf16 v[102:105], v[152:155], v[168:171], v[102:105]
	v_mfma_f32_16x16x32_bf16 v[94:97], v[144:147], v[186:189], v[94:97]
	v_mfma_f32_16x16x32_bf16 v[86:89], v[152:155], v[186:189], v[86:89]
	v_mfma_f32_16x16x32_bf16 v[78:81], v[144:147], v[198:201], v[78:81]
	v_mfma_f32_16x16x32_bf16 v[70:73], v[152:155], v[198:201], v[70:73]
	v_mfma_f32_16x16x32_bf16 v[122:125], v[148:151], v[164:167], v[122:125]
	v_mfma_f32_16x16x32_bf16 v[118:121], v[156:159], v[164:167], v[118:121]
	v_mfma_f32_16x16x32_bf16 v[110:113], v[148:151], v[172:175], v[110:113]
	v_mfma_f32_16x16x32_bf16 v[102:105], v[156:159], v[172:175], v[102:105]
	v_mfma_f32_16x16x32_bf16 v[94:97], v[148:151], v[190:193], v[94:97]
	v_mfma_f32_16x16x32_bf16 v[86:89], v[156:159], v[190:193], v[86:89]
	v_mfma_f32_16x16x32_bf16 v[78:81], v[148:151], v[202:205], v[78:81]
	v_mfma_f32_16x16x32_bf16 v[70:73], v[156:159], v[202:205], v[70:73]
	s_barrier
	s_add_i32 s53, 16, 0x14000
	v_add_u32_e32 v176, s53, v141
	s_add_i32 s52, s52, s35
	ds_read_b128 v[206:209], v176
	ds_read_b128 v[214:217], v176 offset:1024
	ds_read_b128 v[218:221], v176 offset:2048
	ds_read_b128 v[222:225], v176 offset:3072
	v_lshl_add_u64 v[176:177], s[26:27], 0, v[0:1]
	s_mov_b32 m0, s52
	v_lshl_add_u64 v[180:181], s[26:27], 0, v[130:131]
	global_load_lds_dwordx4 v[176:177], off
	s_add_i32 m0, s52, 0x2000
	s_nop 0
	global_load_lds_dwordx4 v[180:181], off
	s_waitcnt vmcnt(10)
	s_barrier
	s_waitcnt lgkmcnt(0)
	s_waitcnt lgkmcnt(0)
	v_mfma_f32_16x16x32_bf16 v[126:129], v[206:209], v[160:163], v[126:129]
	v_mfma_f32_16x16x32_bf16 v[114:117], v[218:221], v[160:163], v[114:117]
	v_mfma_f32_16x16x32_bf16 v[106:109], v[206:209], v[168:171], v[106:109]
	v_mfma_f32_16x16x32_bf16 v[98:101], v[218:221], v[168:171], v[98:101]
	v_mfma_f32_16x16x32_bf16 v[90:93], v[206:209], v[186:189], v[90:93]
	v_mfma_f32_16x16x32_bf16 v[82:85], v[218:221], v[186:189], v[82:85]
	v_mfma_f32_16x16x32_bf16 v[74:77], v[206:209], v[198:201], v[74:77]
	v_mfma_f32_16x16x32_bf16 v[66:69], v[218:221], v[198:201], v[66:69]
	v_mfma_f32_16x16x32_bf16 v[126:129], v[214:217], v[164:167], v[126:129]
	v_mfma_f32_16x16x32_bf16 v[114:117], v[222:225], v[164:167], v[114:117]
	v_mfma_f32_16x16x32_bf16 v[106:109], v[214:217], v[172:175], v[106:109]
	v_mfma_f32_16x16x32_bf16 v[98:101], v[222:225], v[172:175], v[98:101]
	v_mfma_f32_16x16x32_bf16 v[90:93], v[214:217], v[190:193], v[90:93]
	v_mfma_f32_16x16x32_bf16 v[82:85], v[222:225], v[190:193], v[82:85]
	v_mfma_f32_16x16x32_bf16 v[74:77], v[214:217], v[202:205], v[74:77]
	v_mfma_f32_16x16x32_bf16 v[66:69], v[222:225], v[202:205], v[66:69]
	s_mov_b32 m0, s36
	v_lshl_add_u64 v[182:183], s[24:25], 0, v[134:135]
	s_barrier
	ds_read_b128 v[160:163], v143 offset:16384
	ds_read_b128 v[164:167], v143 offset:17408
	ds_read_b128 v[168:171], v143 offset:18432
	ds_read_b128 v[172:175], v143 offset:19456
	ds_read_b128 v[186:189], v143 offset:20480
	ds_read_b128 v[190:193], v143 offset:21504
	ds_read_b128 v[198:201], v143 offset:22528
	ds_read_b128 v[202:205], v143 offset:23552
	global_load_lds_dwordx4 v[182:183], off
	v_lshl_add_u64 v[184:185], s[24:25], 0, v[132:133]
	s_mov_b32 m0, s37
	s_nop 0
	global_load_lds_dwordx4 v[184:185], off
	s_barrier
	s_waitcnt lgkmcnt(0)
	s_waitcnt lgkmcnt(0)
	v_mfma_f32_16x16x32_bf16 v[62:65], v[144:147], v[160:163], v[62:65]
	v_mfma_f32_16x16x32_bf16 v[54:57], v[152:155], v[160:163], v[54:57]
	v_mfma_f32_16x16x32_bf16 v[46:49], v[144:147], v[168:171], v[46:49]
	v_mfma_f32_16x16x32_bf16 v[38:41], v[152:155], v[168:171], v[38:41]
	v_mfma_f32_16x16x32_bf16 v[30:33], v[144:147], v[186:189], v[30:33]
	v_mfma_f32_16x16x32_bf16 v[22:25], v[152:155], v[186:189], v[22:25]
	v_mfma_f32_16x16x32_bf16 v[14:17], v[144:147], v[198:201], v[14:17]
	v_mfma_f32_16x16x32_bf16 v[6:9], v[152:155], v[198:201], v[6:9]
	v_mfma_f32_16x16x32_bf16 v[62:65], v[148:151], v[164:167], v[62:65]
	v_mfma_f32_16x16x32_bf16 v[54:57], v[156:159], v[164:167], v[54:57]
	v_mfma_f32_16x16x32_bf16 v[46:49], v[148:151], v[172:175], v[46:49]
	v_mfma_f32_16x16x32_bf16 v[38:41], v[156:159], v[172:175], v[38:41]
	v_mfma_f32_16x16x32_bf16 v[30:33], v[148:151], v[190:193], v[30:33]
	v_mfma_f32_16x16x32_bf16 v[22:25], v[156:159], v[190:193], v[22:25]
	v_mfma_f32_16x16x32_bf16 v[14:17], v[148:151], v[202:205], v[14:17]
	v_mfma_f32_16x16x32_bf16 v[6:9], v[156:159], v[202:205], v[6:9]
	s_barrier
; #define PG8_STAGE(bufoff, gbase, voff) do { _Pragma("unroll") for (int _i = 0; _i < 2; ++_i) \
;     __builtin_amdgcn_global_load_lds((const unsigned*)((const char*)(gbase) + (voff)[_i]), (LAS unsigned*)(lds + (bufoff) + ldsw + _i * 8192), 16, 0, 0); } while (0)
; #define PG8_LDA(dst, b, h) do { _Pragma("unroll") for (int m = 0; m < 4; ++m) _Pragma("unroll") for (int k = 0; k < 2; ++k) dst[m][k] = *(const LAS bf16x8*)(lds + PG8_SA(b, h) + aoff + m * 2048 + k * 1024); } while (0)
; #define PG8_LDB(dst, b, h) do { _Pragma("unroll") for (int n = 0; n < 2; ++n) _Pragma("unroll") for (int k = 0; k < 2; ++k) dst[n][k] = *(const LAS bf16x8*)(lds + PG8_SB(b, h) + boff + n * 2048 + k * 1024); } while (0)
; #define PG8_MMA(ai, bj, At, Bt) do { __builtin_amdgcn_s_setprio(1); _Pragma("unroll") for (int m = 0; m < 4; ++m) _Pragma("unroll") for (int n = 0; n < 2; ++n) _Pragma("unroll") for (int k = 0; k < 2; ++k) \
;     acc[ai][bj][m][n] = __builtin_amdgcn_mfma_f32_16x16x32_bf16(Bt[n][k], At[m][k], acc[ai][bj][m][n], 0, 0, 0); __builtin_amdgcn_s_setprio(0); } while (0)
; #define PG8_WAIT_V(n) asm volatile("s_waitcnt vmcnt(" #n ")" ::: "memory")
; #define PG8_WAIT_L(n) asm volatile("s_waitcnt lgkmcnt(" #n ")" ::: "memory")
; #define PG8_BAR __builtin_amdgcn_s_barrier()
; #define PG8_SCHED __builtin_amdgcn_sched_barrier(0)
; template <class Epi, class Sched>
; DI void gemm_phase(LAS unsigned char* lds, const Gemm g, const Sched& S, const Epi& E) {
;     ...
;       PG8_STAGE(PG8_SB(0, 1), b2 + hstepB, voffB);
;       PG8_WAIT_V(6); PG8_BAR; PG8_MMA(1, 1, At, B1); PG8_BAR;
;       PG8_LDB(B0, 1, 0); PG8_SCHED; PG8_LDA(At, 1, 0); PG8_STAGE(PG8_SA(0, 1), a2 + hstep, voffA);
;       PG8_WAIT_L(8); PG8_BAR; PG8_WAIT_L(0); PG8_MMA(0, 0, At, B0); PG8_BAR; PG8_SCHED;
;       PG8_LDB(B1, 1, 1); PG8_STAGE(PG8_SB(1, 0), b3, voffB);
	s_add_u32 s26, s26, s0
	s_addc_u32 s27, s27, s1
	s_add_i32 s52, s53, s35
	v_lshl_add_u64 v[226:227], s[26:27], 0, v[0:1]
	s_mov_b32 m0, s52
	v_lshl_add_u64 v[228:229], s[26:27], 0, v[130:131]
	global_load_lds_dwordx4 v[226:227], off
	s_add_i32 m0, s52, 0x2000
	s_nop 0
	global_load_lds_dwordx4 v[228:229], off
	s_waitcnt vmcnt(8)
	s_barrier
	v_mfma_f32_16x16x32_bf16 v[58:61], v[206:209], v[160:163], v[58:61]
	v_mfma_f32_16x16x32_bf16 v[50:53], v[218:221], v[160:163], v[50:53]
	v_mfma_f32_16x16x32_bf16 v[42:45], v[206:209], v[168:171], v[42:45]
	v_mfma_f32_16x16x32_bf16 v[34:37], v[218:221], v[168:171], v[34:37]
	v_mfma_f32_16x16x32_bf16 v[26:29], v[206:209], v[186:189], v[26:29]
	v_mfma_f32_16x16x32_bf16 v[18:21], v[218:221], v[186:189], v[18:21]
	v_mfma_f32_16x16x32_bf16 v[10:13], v[206:209], v[198:201], v[10:13]
	v_mfma_f32_16x16x32_bf16 v[2:5], v[218:221], v[198:201], v[2:5]
	v_mfma_f32_16x16x32_bf16 v[58:61], v[214:217], v[164:167], v[58:61]
	v_mfma_f32_16x16x32_bf16 v[50:53], v[222:225], v[164:167], v[50:53]
	v_mfma_f32_16x16x32_bf16 v[42:45], v[214:217], v[172:175], v[42:45]
	v_mfma_f32_16x16x32_bf16 v[34:37], v[222:225], v[172:175], v[34:37]
	v_mfma_f32_16x16x32_bf16 v[26:29], v[214:217], v[190:193], v[26:29]
	v_mfma_f32_16x16x32_bf16 v[18:21], v[222:225], v[190:193], v[18:21]
	v_mfma_f32_16x16x32_bf16 v[10:13], v[214:217], v[202:205], v[10:13]
	v_mfma_f32_16x16x32_bf16 v[2:5], v[222:225], v[202:205], v[2:5]
	s_add_i32 s26, 16, 0x18000
	v_add_u32_e32 v156, s26, v141
	s_barrier
	ds_read_b128 v[144:147], v156
	ds_read_b128 v[148:151], v156 offset:1024
	ds_read_b128 v[152:155], v156 offset:2048
	ds_read_b128 v[156:159], v156 offset:3072
	s_add_u32 s24, s24, s0
	s_addc_u32 s25, s25, s1
	s_mov_b32 m0, s38
	v_lshl_add_u64 v[206:207], s[24:25], 0, v[134:135]
	ds_read_b128 v[160:163], v143 offset:32768
	ds_read_b128 v[164:167], v143 offset:33792
	ds_read_b128 v[168:171], v143 offset:34816
	ds_read_b128 v[172:175], v143 offset:35840
	ds_read_b128 v[186:189], v143 offset:36864
	ds_read_b128 v[190:193], v143 offset:37888
	ds_read_b128 v[198:201], v143 offset:38912
	ds_read_b128 v[202:205], v143 offset:39936
	global_load_lds_dwordx4 v[206:207], off
	v_lshl_add_u64 v[206:207], s[24:25], 0, v[132:133]
	s_mov_b32 m0, s39
	s_nop 0
	global_load_lds_dwordx4 v[206:207], off
	s_waitcnt lgkmcnt(8)
	s_barrier
	s_waitcnt lgkmcnt(0)
	s_waitcnt lgkmcnt(0)
	v_mfma_f32_16x16x32_bf16 v[122:125], v[144:147], v[160:163], v[122:125]
	v_mfma_f32_16x16x32_bf16 v[118:121], v[152:155], v[160:163], v[118:121]
	v_mfma_f32_16x16x32_bf16 v[110:113], v[144:147], v[168:171], v[110:113]
	v_mfma_f32_16x16x32_bf16 v[102:105], v[152:155], v[168:171], v[102:105]
	v_mfma_f32_16x16x32_bf16 v[94:97], v[144:147], v[186:189], v[94:97]
	v_mfma_f32_16x16x32_bf16 v[86:89], v[152:155], v[186:189], v[86:89]
	v_mfma_f32_16x16x32_bf16 v[78:81], v[144:147], v[198:201], v[78:81]
	v_mfma_f32_16x16x32_bf16 v[70:73], v[152:155], v[198:201], v[70:73]
	v_mfma_f32_16x16x32_bf16 v[122:125], v[148:151], v[164:167], v[122:125]
	v_mfma_f32_16x16x32_bf16 v[118:121], v[156:159], v[164:167], v[118:121]
	v_mfma_f32_16x16x32_bf16 v[110:113], v[148:151], v[172:175], v[110:113]
	v_mfma_f32_16x16x32_bf16 v[102:105], v[156:159], v[172:175], v[102:105]
	v_mfma_f32_16x16x32_bf16 v[94:97], v[148:151], v[190:193], v[94:97]
	v_mfma_f32_16x16x32_bf16 v[86:89], v[156:159], v[190:193], v[86:89]
	v_mfma_f32_16x16x32_bf16 v[78:81], v[148:151], v[202:205], v[78:81]
	v_mfma_f32_16x16x32_bf16 v[70:73], v[156:159], v[202:205], v[70:73]
	s_barrier
	s_add_i32 s24, 16, 0x1c000
	s_add_i32 s25, s26, s35
	v_add_u32_e32 v194, s24, v141
	v_lshl_add_u64 v[176:177], v[176:177], 0, s[70:71]
	s_mov_b32 m0, s25
	ds_read_b128 v[206:209], v194
	ds_read_b128 v[214:217], v194 offset:1024
	ds_read_b128 v[218:221], v194 offset:2048
	ds_read_b128 v[222:225], v194 offset:3072
	global_load_lds_dwordx4 v[176:177], off
	v_lshl_add_u64 v[176:177], v[180:181], 0, s[70:71]
	s_add_i32 m0, s25, 0x2000
	s_nop 0
	global_load_lds_dwordx4 v[176:177], off
	s_waitcnt vmcnt(10)
	s_barrier
; #define PG8_STAGE(bufoff, gbase, voff) do { _Pragma("unroll") for (int _i = 0; _i < 2; ++_i) \
;     __builtin_amdgcn_global_load_lds((const unsigned*)((const char*)(gbase) + (voff)[_i]), (LAS unsigned*)(lds + (bufoff) + ldsw + _i * 8192), 16, 0, 0); } while (0)
; #define PG8_LDA(dst, b, h) do { _Pragma("unroll") for (int m = 0; m < 4; ++m) _Pragma("unroll") for (int k = 0; k < 2; ++k) dst[m][k] = *(const LAS bf16x8*)(lds + PG8_SA(b, h) + aoff + m * 2048 + k * 1024); } while (0)
; #define PG8_LDB(dst, b, h) do { _Pragma("unroll") for (int n = 0; n < 2; ++n) _Pragma("unroll") for (int k = 0; k < 2; ++k) dst[n][k] = *(const LAS bf16x8*)(lds + PG8_SB(b, h) + boff + n * 2048 + k * 1024); } while (0)
; #define PG8_MMA(ai, bj, At, Bt) do { __builtin_amdgcn_s_setprio(1); _Pragma("unroll") for (int m = 0; m < 4; ++m) _Pragma("unroll") for (int n = 0; n < 2; ++n) _Pragma("unroll") for (int k = 0; k < 2; ++k) \
;     acc[ai][bj][m][n] = __builtin_amdgcn_mfma_f32_16x16x32_bf16(Bt[n][k], At[m][k], acc[ai][bj][m][n], 0, 0, 0); __builtin_amdgcn_s_setprio(0); } while (0)
; #define PG8_WAIT_V(n) asm volatile("s_waitcnt vmcnt(" #n ")" ::: "memory")
; #define PG8_WAIT_L(n) asm volatile("s_waitcnt lgkmcnt(" #n ")" ::: "memory")
; #define PG8_BAR __builtin_amdgcn_s_barrier()
; #define PG8_SCHED __builtin_amdgcn_sched_barrier(0)
; template <class Epi, class Sched>
; DI void gemm_phase(LAS unsigned char* lds, const Gemm g, const Sched& S, const Epi& E) {
;     ...
;       PG8_LDB(B1, 1, 1); PG8_STAGE(PG8_SB(1, 0), b3, voffB);
;       PG8_BAR; PG8_WAIT_L(0); PG8_MMA(0, 1, At, B1); PG8_BAR;
;       PG8_LDA(At, 1, 1); PG8_STAGE(PG8_SA(1, 0), a3, voffA);
;       PG8_BAR; PG8_WAIT_L(0); PG8_MMA(1, 0, At, B0); PG8_BAR; PG8_SCHED;
;       PG8_STAGE(PG8_SB(1, 1), b3 + hstepB, voffB);
;       PG8_WAIT_V(6); PG8_BAR; PG8_MMA(1, 1, At, B1); PG8_BAR;
;     }
	s_waitcnt lgkmcnt(0)
	s_waitcnt lgkmcnt(0)
	v_mfma_f32_16x16x32_bf16 v[126:129], v[206:209], v[160:163], v[126:129]
	v_mfma_f32_16x16x32_bf16 v[114:117], v[218:221], v[160:163], v[114:117]
	v_mfma_f32_16x16x32_bf16 v[106:109], v[206:209], v[168:171], v[106:109]
	v_mfma_f32_16x16x32_bf16 v[98:101], v[218:221], v[168:171], v[98:101]
	v_mfma_f32_16x16x32_bf16 v[90:93], v[206:209], v[186:189], v[90:93]
	v_mfma_f32_16x16x32_bf16 v[82:85], v[218:221], v[186:189], v[82:85]
	v_mfma_f32_16x16x32_bf16 v[74:77], v[206:209], v[198:201], v[74:77]
	v_mfma_f32_16x16x32_bf16 v[66:69], v[218:221], v[198:201], v[66:69]
	v_mfma_f32_16x16x32_bf16 v[126:129], v[214:217], v[164:167], v[126:129]
	v_mfma_f32_16x16x32_bf16 v[114:117], v[222:225], v[164:167], v[114:117]
	v_mfma_f32_16x16x32_bf16 v[106:109], v[214:217], v[172:175], v[106:109]
	v_mfma_f32_16x16x32_bf16 v[98:101], v[222:225], v[172:175], v[98:101]
	v_mfma_f32_16x16x32_bf16 v[90:93], v[214:217], v[190:193], v[90:93]
	v_mfma_f32_16x16x32_bf16 v[82:85], v[222:225], v[190:193], v[82:85]
	v_mfma_f32_16x16x32_bf16 v[74:77], v[214:217], v[202:205], v[74:77]
	v_mfma_f32_16x16x32_bf16 v[66:69], v[222:225], v[202:205], v[66:69]
	s_mov_b32 m0, s41
	v_lshl_add_u64 v[176:177], v[182:183], 0, s[70:71]
	s_barrier
	ds_read_b128 v[160:163], v143 offset:49152
	ds_read_b128 v[164:167], v143 offset:50176
	ds_read_b128 v[168:171], v143 offset:51200
	ds_read_b128 v[172:175], v143 offset:52224
	ds_read_b128 v[186:189], v143 offset:53248
	ds_read_b128 v[190:193], v143 offset:54272
	ds_read_b128 v[198:201], v143 offset:55296
	ds_read_b128 v[202:205], v143 offset:56320
	global_load_lds_dwordx4 v[176:177], off
	v_lshl_add_u64 v[176:177], v[184:185], 0, s[70:71]
	s_mov_b32 m0, s42
	s_nop 0
	global_load_lds_dwordx4 v[176:177], off
	s_barrier
	s_waitcnt lgkmcnt(0)
	s_waitcnt lgkmcnt(0)
	v_mfma_f32_16x16x32_bf16 v[62:65], v[144:147], v[160:163], v[62:65]
	v_mfma_f32_16x16x32_bf16 v[54:57], v[152:155], v[160:163], v[54:57]
	v_mfma_f32_16x16x32_bf16 v[46:49], v[144:147], v[168:171], v[46:49]
	v_mfma_f32_16x16x32_bf16 v[38:41], v[152:155], v[168:171], v[38:41]
	v_mfma_f32_16x16x32_bf16 v[30:33], v[144:147], v[186:189], v[30:33]
	v_mfma_f32_16x16x32_bf16 v[22:25], v[152:155], v[186:189], v[22:25]
	v_mfma_f32_16x16x32_bf16 v[14:17], v[144:147], v[198:201], v[14:17]
	v_mfma_f32_16x16x32_bf16 v[6:9], v[152:155], v[198:201], v[6:9]
	v_mfma_f32_16x16x32_bf16 v[62:65], v[148:151], v[164:167], v[62:65]
	v_mfma_f32_16x16x32_bf16 v[54:57], v[156:159], v[164:167], v[54:57]
	v_mfma_f32_16x16x32_bf16 v[46:49], v[148:151], v[172:175], v[46:49]
	v_mfma_f32_16x16x32_bf16 v[38:41], v[156:159], v[172:175], v[38:41]
	v_mfma_f32_16x16x32_bf16 v[30:33], v[148:151], v[190:193], v[30:33]
	v_mfma_f32_16x16x32_bf16 v[22:25], v[156:159], v[190:193], v[22:25]
	v_mfma_f32_16x16x32_bf16 v[14:17], v[148:151], v[202:205], v[14:17]
	v_mfma_f32_16x16x32_bf16 v[6:9], v[156:159], v[202:205], v[6:9]
	s_barrier
	s_add_i32 s24, s24, s35
	v_lshl_add_u64 v[144:145], v[226:227], 0, s[70:71]
	s_mov_b32 m0, s24
	s_nop 0
	global_load_lds_dwordx4 v[144:145], off
	v_lshl_add_u64 v[144:145], v[228:229], 0, s[70:71]
	s_add_i32 m0, s24, 0x2000
	s_nop 0
	global_load_lds_dwordx4 v[144:145], off
	s_waitcnt vmcnt(8)
	s_barrier
	v_mfma_f32_16x16x32_bf16 v[58:61], v[206:209], v[160:163], v[58:61]
	v_mfma_f32_16x16x32_bf16 v[50:53], v[218:221], v[160:163], v[50:53]
	v_mfma_f32_16x16x32_bf16 v[42:45], v[206:209], v[168:171], v[42:45]
	v_mfma_f32_16x16x32_bf16 v[34:37], v[218:221], v[168:171], v[34:37]
	v_mfma_f32_16x16x32_bf16 v[26:29], v[206:209], v[186:189], v[26:29]
	v_mfma_f32_16x16x32_bf16 v[18:21], v[218:221], v[186:189], v[18:21]
	v_mfma_f32_16x16x32_bf16 v[10:13], v[206:209], v[198:201], v[10:13]
	v_mfma_f32_16x16x32_bf16 v[2:5], v[218:221], v[198:201], v[2:5]
	v_mfma_f32_16x16x32_bf16 v[58:61], v[214:217], v[164:167], v[58:61]
	v_mfma_f32_16x16x32_bf16 v[50:53], v[222:225], v[164:167], v[50:53]
	v_mfma_f32_16x16x32_bf16 v[42:45], v[214:217], v[172:175], v[42:45]
	v_mfma_f32_16x16x32_bf16 v[34:37], v[222:225], v[172:175], v[34:37]
	v_mfma_f32_16x16x32_bf16 v[26:29], v[214:217], v[190:193], v[26:29]
	v_mfma_f32_16x16x32_bf16 v[18:21], v[222:225], v[190:193], v[18:21]
	v_mfma_f32_16x16x32_bf16 v[10:13], v[214:217], v[202:205], v[10:13]
	v_mfma_f32_16x16x32_bf16 v[2:5], v[222:225], v[202:205], v[2:5]
	s_add_u32 s22, s22, 0x100
	s_addc_u32 s23, s23, 0
	s_add_u32 s49, s49, 0x100
	s_addc_u32 s50, s50, 0
	s_cmp_ge_i32 s51, s40
	s_mov_b32 s24, s51
	s_barrier
	s_cbranch_scc0 .LBB0_178
	s_branch .LBB0_161

; #define PG8_STAGE(bufoff, gbase, voff) do { _Pragma("unroll") for (int _i = 0; _i < 2; ++_i) \
;     __builtin_amdgcn_global_load_lds((const unsigned*)((const char*)(gbase) + (voff)[_i]), (LAS unsigned*)(lds + (bufoff) + ldsw + _i * 8192), 16, 0, 0); } while (0)
; #define PG8_LDA(dst, b, h) do { _Pragma("unroll") for (int m = 0; m < 4; ++m) _Pragma("unroll") for (int k = 0; k < 2; ++k) dst[m][k] = *(const LAS bf16x8*)(lds + PG8_SA(b, h) + aoff + m * 2048 + k * 1024); } while (0)
; #define PG8_LDB(dst, b, h) do { _Pragma("unroll") for (int n = 0; n < 2; ++n) _Pragma("unroll") for (int k = 0; k < 2; ++k) dst[n][k] = *(const LAS bf16x8*)(lds + PG8_SB(b, h) + boff + n * 2048 + k * 1024); } while (0)
; #define PG8_MMA(ai, bj, At, Bt) do { __builtin_amdgcn_s_setprio(1); _Pragma("unroll") for (int m = 0; m < 4; ++m) _Pragma("unroll") for (int n = 0; n < 2; ++n) _Pragma("unroll") for (int k = 0; k < 2; ++k) \
;     acc[ai][bj][m][n] = __builtin_amdgcn_mfma_f32_16x16x32_bf16(Bt[n][k], At[m][k], acc[ai][bj][m][n], 0, 0, 0); __builtin_amdgcn_s_setprio(0); } while (0)
; #define PG8_WAIT_L(n) asm volatile("s_waitcnt lgkmcnt(" #n ")" ::: "memory")
; #define PG8_BAR __builtin_amdgcn_s_barrier()
; #define PG8_SCHED __builtin_amdgcn_sched_barrier(0)
; template <class Epi, class Sched>
; DI void gemm_phase(LAS unsigned char* lds, const Gemm g, const Sched& S, const Epi& E) {
;     ...
;       const bool last = (t == nt - 2);
;       const char* a1 = cA + (size_t)(t + 1) * kstep;
;       const char* a2 = last ? nA : cA + (size_t)(t + 2) * kstep; const char* b2 = last ? nB : cB + (size_t)(t + 2) * kstep;
;       const char* a3 = a2 + kstep; const char* b3 = b2 + kstep;
;       PG8_LDB(B0, 0, 0); PG8_SCHED; PG8_LDA(At, 0, 0); PG8_STAGE(PG8_SA(1, 1), a1 + hstep, voffA);
;       PG8_WAIT_L(8); PG8_BAR; PG8_WAIT_L(0); PG8_MMA(0, 0, At, B0); PG8_BAR; PG8_SCHED;
;       PG8_LDB(B1, 0, 1); PG8_STAGE(PG8_SB(0, 0), b2, voffB);
;       PG8_BAR; PG8_WAIT_L(0); PG8_MMA(0, 1, At, B1); PG8_BAR;
;       PG8_LDA(At, 0, 1); PG8_STAGE(PG8_SA(0, 0), a2, voffA);
;       PG8_BAR; PG8_WAIT_L(0); PG8_MMA(1, 0, At, B0); PG8_BAR; PG8_SCHED;
.LBB0_191:
	s_add_i32 s34, s16, 2
	s_add_u32 s17, s14, 0xfe000080
	s_addc_u32 s18, s15, -1
	s_cmp_lg_u32 s31, s16
	s_cselect_b32 s19, s18, 0
	s_cselect_b32 s18, s17, 0
	s_add_u32 s16, s12, s18
	s_addc_u32 s17, s13, s19
	s_add_i32 s35, 16, 0x10000
	v_add_u32_e32 v156, s35, v142
	ds_read_b128 v[144:147], v156
	ds_read_b128 v[148:151], v156 offset:1024
	ds_read_b128 v[152:155], v156 offset:2048
	ds_read_b128 v[156:159], v156 offset:3072
	s_add_u32 s18, s2, s18
	s_addc_u32 s19, s3, s19
	v_lshl_add_u64 v[176:177], v[136:137], 0, s[14:15]
	s_add_i32 m0, s23, 0xc000
	ds_read_b128 v[160:163], v143
	ds_read_b128 v[164:167], v143 offset:1024
	ds_read_b128 v[168:171], v143 offset:2048
	ds_read_b128 v[172:175], v143 offset:3072
	ds_read_b128 v[186:189], v143 offset:4096
	ds_read_b128 v[190:193], v143 offset:5120
	ds_read_b128 v[198:201], v143 offset:6144
	ds_read_b128 v[202:205], v143 offset:7168
	global_load_lds_dwordx4 v[176:177], off
	v_lshl_add_u64 v[176:177], v[138:139], 0, s[14:15]
	s_add_i32 m0, s23, 0xe000
	s_nop 0
	global_load_lds_dwordx4 v[176:177], off
	s_waitcnt lgkmcnt(8)
	s_barrier
	s_waitcnt lgkmcnt(0)
	s_waitcnt lgkmcnt(0)
	v_mfma_f32_16x16x32_bf16 v[126:129], v[144:147], v[160:163], v[126:129]
	v_mfma_f32_16x16x32_bf16 v[118:121], v[152:155], v[160:163], v[118:121]
	v_mfma_f32_16x16x32_bf16 v[110:113], v[144:147], v[168:171], v[110:113]
	v_mfma_f32_16x16x32_bf16 v[102:105], v[152:155], v[168:171], v[102:105]
	v_mfma_f32_16x16x32_bf16 v[94:97], v[144:147], v[186:189], v[94:97]
	v_mfma_f32_16x16x32_bf16 v[86:89], v[152:155], v[186:189], v[86:89]
	v_mfma_f32_16x16x32_bf16 v[78:81], v[144:147], v[198:201], v[78:81]
	v_mfma_f32_16x16x32_bf16 v[70:73], v[152:155], v[198:201], v[70:73]
	v_mfma_f32_16x16x32_bf16 v[126:129], v[148:151], v[164:167], v[126:129]
	v_mfma_f32_16x16x32_bf16 v[118:121], v[156:159], v[164:167], v[118:121]
	v_mfma_f32_16x16x32_bf16 v[110:113], v[148:151], v[172:175], v[110:113]
	v_mfma_f32_16x16x32_bf16 v[102:105], v[156:159], v[172:175], v[102:105]
	v_mfma_f32_16x16x32_bf16 v[94:97], v[148:151], v[190:193], v[94:97]
	v_mfma_f32_16x16x32_bf16 v[86:89], v[156:159], v[190:193], v[86:89]
	v_mfma_f32_16x16x32_bf16 v[78:81], v[148:151], v[202:205], v[78:81]
	v_mfma_f32_16x16x32_bf16 v[70:73], v[156:159], v[202:205], v[70:73]
	s_barrier
	s_add_i32 s36, 16, 0x14000
	v_add_u32_e32 v176, s36, v142
	s_add_i32 s35, s35, s22
	ds_read_b128 v[206:209], v176
	ds_read_b128 v[214:217], v176 offset:1024
	ds_read_b128 v[218:221], v176 offset:2048
	ds_read_b128 v[222:225], v176 offset:3072
	v_lshl_add_u64 v[176:177], s[18:19], 0, v[0:1]
	s_mov_b32 m0, s35
	v_lshl_add_u64 v[180:181], s[18:19], 0, v[130:131]
	global_load_lds_dwordx4 v[176:177], off
	s_add_i32 m0, s35, 0x2000
	s_nop 0
	global_load_lds_dwordx4 v[180:181], off
	s_waitcnt vmcnt(10)
	s_barrier
	s_waitcnt lgkmcnt(0)
	s_waitcnt lgkmcnt(0)
	v_mfma_f32_16x16x32_bf16 v[122:125], v[206:209], v[160:163], v[122:125]
	v_mfma_f32_16x16x32_bf16 v[114:117], v[218:221], v[160:163], v[114:117]
	v_mfma_f32_16x16x32_bf16 v[106:109], v[206:209], v[168:171], v[106:109]
	v_mfma_f32_16x16x32_bf16 v[98:101], v[218:221], v[168:171], v[98:101]
	v_mfma_f32_16x16x32_bf16 v[90:93], v[206:209], v[186:189], v[90:93]
	v_mfma_f32_16x16x32_bf16 v[82:85], v[218:221], v[186:189], v[82:85]
	v_mfma_f32_16x16x32_bf16 v[74:77], v[206:209], v[198:201], v[74:77]
	v_mfma_f32_16x16x32_bf16 v[66:69], v[218:221], v[198:201], v[66:69]
	v_mfma_f32_16x16x32_bf16 v[122:125], v[214:217], v[164:167], v[122:125]
	v_mfma_f32_16x16x32_bf16 v[114:117], v[222:225], v[164:167], v[114:117]
	v_mfma_f32_16x16x32_bf16 v[106:109], v[214:217], v[172:175], v[106:109]
	v_mfma_f32_16x16x32_bf16 v[98:101], v[222:225], v[172:175], v[98:101]
	v_mfma_f32_16x16x32_bf16 v[90:93], v[214:217], v[190:193], v[90:93]
	v_mfma_f32_16x16x32_bf16 v[82:85], v[222:225], v[190:193], v[82:85]
	v_mfma_f32_16x16x32_bf16 v[74:77], v[214:217], v[202:205], v[74:77]
	v_mfma_f32_16x16x32_bf16 v[66:69], v[222:225], v[202:205], v[66:69]
	s_mov_b32 m0, s23
	v_lshl_add_u64 v[182:183], s[16:17], 0, v[134:135]
	s_barrier
	ds_read_b128 v[160:163], v143 offset:16384
	ds_read_b128 v[164:167], v143 offset:17408
	ds_read_b128 v[168:171], v143 offset:18432
	ds_read_b128 v[172:175], v143 offset:19456
	ds_read_b128 v[186:189], v143 offset:20480
	ds_read_b128 v[190:193], v143 offset:21504
	ds_read_b128 v[198:201], v143 offset:22528
	ds_read_b128 v[202:205], v143 offset:23552
	global_load_lds_dwordx4 v[182:183], off
	v_lshl_add_u64 v[184:185], s[16:17], 0, v[132:133]
	s_mov_b32 m0, s24
	s_nop 0
	global_load_lds_dwordx4 v[184:185], off
	s_barrier
	s_waitcnt lgkmcnt(0)
	s_waitcnt lgkmcnt(0)
	v_mfma_f32_16x16x32_bf16 v[62:65], v[144:147], v[160:163], v[62:65]
	v_mfma_f32_16x16x32_bf16 v[54:57], v[152:155], v[160:163], v[54:57]
	v_mfma_f32_16x16x32_bf16 v[46:49], v[144:147], v[168:171], v[46:49]
	v_mfma_f32_16x16x32_bf16 v[38:41], v[152:155], v[168:171], v[38:41]
	v_mfma_f32_16x16x32_bf16 v[30:33], v[144:147], v[186:189], v[30:33]
	v_mfma_f32_16x16x32_bf16 v[22:25], v[152:155], v[186:189], v[22:25]
	v_mfma_f32_16x16x32_bf16 v[14:17], v[144:147], v[198:201], v[14:17]
	v_mfma_f32_16x16x32_bf16 v[6:9], v[152:155], v[198:201], v[6:9]
	v_mfma_f32_16x16x32_bf16 v[62:65], v[148:151], v[164:167], v[62:65]
	v_mfma_f32_16x16x32_bf16 v[54:57], v[156:159], v[164:167], v[54:57]
	v_mfma_f32_16x16x32_bf16 v[46:49], v[148:151], v[172:175], v[46:49]
	v_mfma_f32_16x16x32_bf16 v[38:41], v[156:159], v[172:175], v[38:41]
	v_mfma_f32_16x16x32_bf16 v[30:33], v[148:151], v[190:193], v[30:33]
	v_mfma_f32_16x16x32_bf16 v[22:25], v[156:159], v[190:193], v[22:25]
	v_mfma_f32_16x16x32_bf16 v[14:17], v[148:151], v[202:205], v[14:17]
	v_mfma_f32_16x16x32_bf16 v[6:9], v[156:159], v[202:205], v[6:9]
	s_barrier
; #define PG8_STAGE(bufoff, gbase, voff) do { _Pragma("unroll") for (int _i = 0; _i < 2; ++_i) \
;     __builtin_amdgcn_global_load_lds((const unsigned*)((const char*)(gbase) + (voff)[_i]), (LAS unsigned*)(lds + (bufoff) + ldsw + _i * 8192), 16, 0, 0); } while (0)
; #define PG8_LDA(dst, b, h) do { _Pragma("unroll") for (int m = 0; m < 4; ++m) _Pragma("unroll") for (int k = 0; k < 2; ++k) dst[m][k] = *(const LAS bf16x8*)(lds + PG8_SA(b, h) + aoff + m * 2048 + k * 1024); } while (0)
; #define PG8_LDB(dst, b, h) do { _Pragma("unroll") for (int n = 0; n < 2; ++n) _Pragma("unroll") for (int k = 0; k < 2; ++k) dst[n][k] = *(const LAS bf16x8*)(lds + PG8_SB(b, h) + boff + n * 2048 + k * 1024); } while (0)
; #define PG8_MMA(ai, bj, At, Bt) do { __builtin_amdgcn_s_setprio(1); _Pragma("unroll") for (int m = 0; m < 4; ++m) _Pragma("unroll") for (int n = 0; n < 2; ++n) _Pragma("unroll") for (int k = 0; k < 2; ++k) \
;     acc[ai][bj][m][n] = __builtin_amdgcn_mfma_f32_16x16x32_bf16(Bt[n][k], At[m][k], acc[ai][bj][m][n], 0, 0, 0); __builtin_amdgcn_s_setprio(0); } while (0)
; #define PG8_WAIT_V(n) asm volatile("s_waitcnt vmcnt(" #n ")" ::: "memory")
; #define PG8_WAIT_L(n) asm volatile("s_waitcnt lgkmcnt(" #n ")" ::: "memory")
; #define PG8_BAR __builtin_amdgcn_s_barrier()
; #define PG8_SCHED __builtin_amdgcn_sched_barrier(0)
; template <class Epi, class Sched>
; DI void gemm_phase(LAS unsigned char* lds, const Gemm g, const Sched& S, const Epi& E) {
;     ...
;       PG8_STAGE(PG8_SB(0, 1), b2 + hstepB, voffB);
;       PG8_WAIT_V(6); PG8_BAR; PG8_MMA(1, 1, At, B1); PG8_BAR;
;       PG8_LDB(B0, 1, 0); PG8_SCHED; PG8_LDA(At, 1, 0); PG8_STAGE(PG8_SA(0, 1), a2 + hstep, voffA);
;       PG8_WAIT_L(8); PG8_BAR; PG8_WAIT_L(0); PG8_MMA(0, 0, At, B0); PG8_BAR; PG8_SCHED;
;       PG8_LDB(B1, 1, 1); PG8_STAGE(PG8_SB(1, 0), b3, voffB);
	s_add_u32 s18, s18, s0
	s_addc_u32 s19, s19, s1
	s_add_i32 s35, s36, s22
	v_lshl_add_u64 v[226:227], s[18:19], 0, v[0:1]
	s_mov_b32 m0, s35
	v_lshl_add_u64 v[228:229], s[18:19], 0, v[130:131]
	global_load_lds_dwordx4 v[226:227], off
	s_add_i32 m0, s35, 0x2000
	s_nop 0
	global_load_lds_dwordx4 v[228:229], off
	s_waitcnt vmcnt(8)
	s_barrier
	v_mfma_f32_16x16x32_bf16 v[58:61], v[206:209], v[160:163], v[58:61]
	v_mfma_f32_16x16x32_bf16 v[50:53], v[218:221], v[160:163], v[50:53]
	v_mfma_f32_16x16x32_bf16 v[42:45], v[206:209], v[168:171], v[42:45]
	v_mfma_f32_16x16x32_bf16 v[34:37], v[218:221], v[168:171], v[34:37]
	v_mfma_f32_16x16x32_bf16 v[26:29], v[206:209], v[186:189], v[26:29]
	v_mfma_f32_16x16x32_bf16 v[18:21], v[218:221], v[186:189], v[18:21]
	v_mfma_f32_16x16x32_bf16 v[10:13], v[206:209], v[198:201], v[10:13]
	v_mfma_f32_16x16x32_bf16 v[2:5], v[218:221], v[198:201], v[2:5]
	v_mfma_f32_16x16x32_bf16 v[58:61], v[214:217], v[164:167], v[58:61]
	v_mfma_f32_16x16x32_bf16 v[50:53], v[222:225], v[164:167], v[50:53]
	v_mfma_f32_16x16x32_bf16 v[42:45], v[214:217], v[172:175], v[42:45]
	v_mfma_f32_16x16x32_bf16 v[34:37], v[222:225], v[172:175], v[34:37]
	v_mfma_f32_16x16x32_bf16 v[26:29], v[214:217], v[190:193], v[26:29]
	v_mfma_f32_16x16x32_bf16 v[18:21], v[222:225], v[190:193], v[18:21]
	v_mfma_f32_16x16x32_bf16 v[10:13], v[214:217], v[202:205], v[10:13]
	v_mfma_f32_16x16x32_bf16 v[2:5], v[222:225], v[202:205], v[2:5]
	s_add_i32 s18, 16, 0x18000
	v_add_u32_e32 v156, s18, v142
	s_barrier
	ds_read_b128 v[144:147], v156
	ds_read_b128 v[148:151], v156 offset:1024
	ds_read_b128 v[152:155], v156 offset:2048
	ds_read_b128 v[156:159], v156 offset:3072
	s_add_u32 s16, s16, s0
	s_addc_u32 s17, s17, s1
	s_mov_b32 m0, s25
	v_lshl_add_u64 v[206:207], s[16:17], 0, v[134:135]
	ds_read_b128 v[160:163], v143 offset:32768
	ds_read_b128 v[164:167], v143 offset:33792
	ds_read_b128 v[168:171], v143 offset:34816
	ds_read_b128 v[172:175], v143 offset:35840
	ds_read_b128 v[186:189], v143 offset:36864
	ds_read_b128 v[190:193], v143 offset:37888
	ds_read_b128 v[198:201], v143 offset:38912
	ds_read_b128 v[202:205], v143 offset:39936
	global_load_lds_dwordx4 v[206:207], off
	v_lshl_add_u64 v[206:207], s[16:17], 0, v[132:133]
	s_mov_b32 m0, s26
	s_nop 0
	global_load_lds_dwordx4 v[206:207], off
	s_waitcnt lgkmcnt(8)
	s_barrier
	s_waitcnt lgkmcnt(0)
	s_waitcnt lgkmcnt(0)
	v_mfma_f32_16x16x32_bf16 v[126:129], v[144:147], v[160:163], v[126:129]
	v_mfma_f32_16x16x32_bf16 v[118:121], v[152:155], v[160:163], v[118:121]
	v_mfma_f32_16x16x32_bf16 v[110:113], v[144:147], v[168:171], v[110:113]
	v_mfma_f32_16x16x32_bf16 v[102:105], v[152:155], v[168:171], v[102:105]
	v_mfma_f32_16x16x32_bf16 v[94:97], v[144:147], v[186:189], v[94:97]
	v_mfma_f32_16x16x32_bf16 v[86:89], v[152:155], v[186:189], v[86:89]
	v_mfma_f32_16x16x32_bf16 v[78:81], v[144:147], v[198:201], v[78:81]
	v_mfma_f32_16x16x32_bf16 v[70:73], v[152:155], v[198:201], v[70:73]
	v_mfma_f32_16x16x32_bf16 v[126:129], v[148:151], v[164:167], v[126:129]
	v_mfma_f32_16x16x32_bf16 v[118:121], v[156:159], v[164:167], v[118:121]
	v_mfma_f32_16x16x32_bf16 v[110:113], v[148:151], v[172:175], v[110:113]
	v_mfma_f32_16x16x32_bf16 v[102:105], v[156:159], v[172:175], v[102:105]
	v_mfma_f32_16x16x32_bf16 v[94:97], v[148:151], v[190:193], v[94:97]
	v_mfma_f32_16x16x32_bf16 v[86:89], v[156:159], v[190:193], v[86:89]
	v_mfma_f32_16x16x32_bf16 v[78:81], v[148:151], v[202:205], v[78:81]
	v_mfma_f32_16x16x32_bf16 v[70:73], v[156:159], v[202:205], v[70:73]
	s_barrier
	s_add_i32 s16, 16, 0x1c000
	s_add_i32 s17, s18, s22
	v_add_u32_e32 v194, s16, v142
	v_lshl_add_u64 v[176:177], v[176:177], 0, s[70:71]
	s_mov_b32 m0, s17
	ds_read_b128 v[206:209], v194
	ds_read_b128 v[214:217], v194 offset:1024
	ds_read_b128 v[218:221], v194 offset:2048
	ds_read_b128 v[222:225], v194 offset:3072
	global_load_lds_dwordx4 v[176:177], off
	v_lshl_add_u64 v[176:177], v[180:181], 0, s[70:71]
	s_add_i32 m0, s17, 0x2000
	s_nop 0
	global_load_lds_dwordx4 v[176:177], off
	s_waitcnt vmcnt(10)
	s_barrier
; #define PG8_STAGE(bufoff, gbase, voff) do { _Pragma("unroll") for (int _i = 0; _i < 2; ++_i) \
;     __builtin_amdgcn_global_load_lds((const unsigned*)((const char*)(gbase) + (voff)[_i]), (LAS unsigned*)(lds + (bufoff) + ldsw + _i * 8192), 16, 0, 0); } while (0)
; #define PG8_LDA(dst, b, h) do { _Pragma("unroll") for (int m = 0; m < 4; ++m) _Pragma("unroll") for (int k = 0; k < 2; ++k) dst[m][k] = *(const LAS bf16x8*)(lds + PG8_SA(b, h) + aoff + m * 2048 + k * 1024); } while (0)
; #define PG8_LDB(dst, b, h) do { _Pragma("unroll") for (int n = 0; n < 2; ++n) _Pragma("unroll") for (int k = 0; k < 2; ++k) dst[n][k] = *(const LAS bf16x8*)(lds + PG8_SB(b, h) + boff + n * 2048 + k * 1024); } while (0)
; #define PG8_MMA(ai, bj, At, Bt) do { __builtin_amdgcn_s_setprio(1); _Pragma("unroll") for (int m = 0; m < 4; ++m) _Pragma("unroll") for (int n = 0; n < 2; ++n) _Pragma("unroll") for (int k = 0; k < 2; ++k) \
;     acc[ai][bj][m][n] = __builtin_amdgcn_mfma_f32_16x16x32_bf16(Bt[n][k], At[m][k], acc[ai][bj][m][n], 0, 0, 0); __builtin_amdgcn_s_setprio(0); } while (0)
; #define PG8_WAIT_V(n) asm volatile("s_waitcnt vmcnt(" #n ")" ::: "memory")
; #define PG8_WAIT_L(n) asm volatile("s_waitcnt lgkmcnt(" #n ")" ::: "memory")
; #define PG8_BAR __builtin_amdgcn_s_barrier()
; #define PG8_SCHED __builtin_amdgcn_sched_barrier(0)
; template <class Epi, class Sched>
; DI void gemm_phase(LAS unsigned char* lds, const Gemm g, const Sched& S, const Epi& E) {
;     ...
;       PG8_LDB(B1, 1, 1); PG8_STAGE(PG8_SB(1, 0), b3, voffB);
;       PG8_BAR; PG8_WAIT_L(0); PG8_MMA(0, 1, At, B1); PG8_BAR;
;       PG8_LDA(At, 1, 1); PG8_STAGE(PG8_SA(1, 0), a3, voffA);
;       PG8_BAR; PG8_WAIT_L(0); PG8_MMA(1, 0, At, B0); PG8_BAR; PG8_SCHED;
;       PG8_STAGE(PG8_SB(1, 1), b3 + hstepB, voffB);
;       PG8_WAIT_V(6); PG8_BAR; PG8_MMA(1, 1, At, B1); PG8_BAR;
;     }
	s_waitcnt lgkmcnt(0)
	s_waitcnt lgkmcnt(0)
	v_mfma_f32_16x16x32_bf16 v[122:125], v[206:209], v[160:163], v[122:125]
	v_mfma_f32_16x16x32_bf16 v[114:117], v[218:221], v[160:163], v[114:117]
	v_mfma_f32_16x16x32_bf16 v[106:109], v[206:209], v[168:171], v[106:109]
	v_mfma_f32_16x16x32_bf16 v[98:101], v[218:221], v[168:171], v[98:101]
	v_mfma_f32_16x16x32_bf16 v[90:93], v[206:209], v[186:189], v[90:93]
	v_mfma_f32_16x16x32_bf16 v[82:85], v[218:221], v[186:189], v[82:85]
	v_mfma_f32_16x16x32_bf16 v[74:77], v[206:209], v[198:201], v[74:77]
	v_mfma_f32_16x16x32_bf16 v[66:69], v[218:221], v[198:201], v[66:69]
	v_mfma_f32_16x16x32_bf16 v[122:125], v[214:217], v[164:167], v[122:125]
	v_mfma_f32_16x16x32_bf16 v[114:117], v[222:225], v[164:167], v[114:117]
	v_mfma_f32_16x16x32_bf16 v[106:109], v[214:217], v[172:175], v[106:109]
	v_mfma_f32_16x16x32_bf16 v[98:101], v[222:225], v[172:175], v[98:101]
	v_mfma_f32_16x16x32_bf16 v[90:93], v[214:217], v[190:193], v[90:93]
	v_mfma_f32_16x16x32_bf16 v[82:85], v[222:225], v[190:193], v[82:85]
	v_mfma_f32_16x16x32_bf16 v[74:77], v[214:217], v[202:205], v[74:77]
	v_mfma_f32_16x16x32_bf16 v[66:69], v[222:225], v[202:205], v[66:69]
	s_mov_b32 m0, s27
	v_lshl_add_u64 v[176:177], v[182:183], 0, s[70:71]
	s_barrier
	ds_read_b128 v[160:163], v143 offset:49152
	ds_read_b128 v[164:167], v143 offset:50176
	ds_read_b128 v[168:171], v143 offset:51200
	ds_read_b128 v[172:175], v143 offset:52224
	ds_read_b128 v[186:189], v143 offset:53248
	ds_read_b128 v[190:193], v143 offset:54272
	ds_read_b128 v[198:201], v143 offset:55296
	ds_read_b128 v[202:205], v143 offset:56320
	global_load_lds_dwordx4 v[176:177], off
	v_lshl_add_u64 v[176:177], v[184:185], 0, s[70:71]
	s_mov_b32 m0, s29
	s_nop 0
	global_load_lds_dwordx4 v[176:177], off
	s_barrier
	s_waitcnt lgkmcnt(0)
	s_waitcnt lgkmcnt(0)
	v_mfma_f32_16x16x32_bf16 v[62:65], v[144:147], v[160:163], v[62:65]
	v_mfma_f32_16x16x32_bf16 v[54:57], v[152:155], v[160:163], v[54:57]
	v_mfma_f32_16x16x32_bf16 v[46:49], v[144:147], v[168:171], v[46:49]
	v_mfma_f32_16x16x32_bf16 v[38:41], v[152:155], v[168:171], v[38:41]
	v_mfma_f32_16x16x32_bf16 v[30:33], v[144:147], v[186:189], v[30:33]
	v_mfma_f32_16x16x32_bf16 v[22:25], v[152:155], v[186:189], v[22:25]
	v_mfma_f32_16x16x32_bf16 v[14:17], v[144:147], v[198:201], v[14:17]
	v_mfma_f32_16x16x32_bf16 v[6:9], v[152:155], v[198:201], v[6:9]
	v_mfma_f32_16x16x32_bf16 v[62:65], v[148:151], v[164:167], v[62:65]
	v_mfma_f32_16x16x32_bf16 v[54:57], v[156:159], v[164:167], v[54:57]
	v_mfma_f32_16x16x32_bf16 v[46:49], v[148:151], v[172:175], v[46:49]
	v_mfma_f32_16x16x32_bf16 v[38:41], v[156:159], v[172:175], v[38:41]
	v_mfma_f32_16x16x32_bf16 v[30:33], v[148:151], v[190:193], v[30:33]
	v_mfma_f32_16x16x32_bf16 v[22:25], v[156:159], v[190:193], v[22:25]
	v_mfma_f32_16x16x32_bf16 v[14:17], v[148:151], v[202:205], v[14:17]
	v_mfma_f32_16x16x32_bf16 v[6:9], v[156:159], v[202:205], v[6:9]
	s_barrier
	s_add_i32 s16, s16, s22
	v_lshl_add_u64 v[144:145], v[226:227], 0, s[70:71]
	s_mov_b32 m0, s16
	s_nop 0
	global_load_lds_dwordx4 v[144:145], off
	v_lshl_add_u64 v[144:145], v[228:229], 0, s[70:71]
	s_add_i32 m0, s16, 0x2000
	s_nop 0
	global_load_lds_dwordx4 v[144:145], off
	s_waitcnt vmcnt(8)
	s_barrier
	v_mfma_f32_16x16x32_bf16 v[58:61], v[206:209], v[160:163], v[58:61]
	v_mfma_f32_16x16x32_bf16 v[50:53], v[218:221], v[160:163], v[50:53]
	v_mfma_f32_16x16x32_bf16 v[42:45], v[206:209], v[168:171], v[42:45]
	v_mfma_f32_16x16x32_bf16 v[34:37], v[218:221], v[168:171], v[34:37]
	v_mfma_f32_16x16x32_bf16 v[26:29], v[206:209], v[186:189], v[26:29]
	v_mfma_f32_16x16x32_bf16 v[18:21], v[218:221], v[186:189], v[18:21]
	v_mfma_f32_16x16x32_bf16 v[10:13], v[206:209], v[198:201], v[10:13]
	v_mfma_f32_16x16x32_bf16 v[2:5], v[218:221], v[198:201], v[2:5]
	v_mfma_f32_16x16x32_bf16 v[58:61], v[214:217], v[164:167], v[58:61]
	v_mfma_f32_16x16x32_bf16 v[50:53], v[222:225], v[164:167], v[50:53]
	v_mfma_f32_16x16x32_bf16 v[42:45], v[214:217], v[172:175], v[42:45]
	v_mfma_f32_16x16x32_bf16 v[34:37], v[222:225], v[172:175], v[34:37]
	v_mfma_f32_16x16x32_bf16 v[26:29], v[214:217], v[190:193], v[26:29]
	v_mfma_f32_16x16x32_bf16 v[18:21], v[222:225], v[190:193], v[18:21]
	v_mfma_f32_16x16x32_bf16 v[10:13], v[214:217], v[202:205], v[10:13]
	v_mfma_f32_16x16x32_bf16 v[2:5], v[222:225], v[202:205], v[2:5]
	s_add_u32 s14, s14, 0x100
	s_addc_u32 s15, s15, 0
	s_cmp_ge_i32 s34, s30
	s_mov_b32 s16, s34
	s_barrier
	s_cbranch_scc0 .LBB0_191

; #define PG8_STAGE(bufoff, gbase, voff) do { _Pragma("unroll") for (int _i = 0; _i < 2; ++_i) \
;     __builtin_amdgcn_global_load_lds((const unsigned*)((const char*)(gbase) + (voff)[_i]), (LAS unsigned*)(lds + (bufoff) + ldsw + _i * 8192), 16, 0, 0); } while (0)
; #define PG8_LDA(dst, b, h) do { _Pragma("unroll") for (int m = 0; m < 4; ++m) _Pragma("unroll") for (int k = 0; k < 2; ++k) dst[m][k] = *(const LAS bf16x8*)(lds + PG8_SA(b, h) + aoff + m * 2048 + k * 1024); } while (0)
; #define PG8_LDB(dst, b, h) do { _Pragma("unroll") for (int n = 0; n < 2; ++n) _Pragma("unroll") for (int k = 0; k < 2; ++k) dst[n][k] = *(const LAS bf16x8*)(lds + PG8_SB(b, h) + boff + n * 2048 + k * 1024); } while (0)
; #define PG8_MMA(ai, bj, At, Bt) do { __builtin_amdgcn_s_setprio(1); _Pragma("unroll") for (int m = 0; m < 4; ++m) _Pragma("unroll") for (int n = 0; n < 2; ++n) _Pragma("unroll") for (int k = 0; k < 2; ++k) \
;     acc[ai][bj][m][n] = __builtin_amdgcn_mfma_f32_16x16x32_bf16(Bt[n][k], At[m][k], acc[ai][bj][m][n], 0, 0, 0); __builtin_amdgcn_s_setprio(0); } while (0)
; #define PG8_WAIT_L(n) asm volatile("s_waitcnt lgkmcnt(" #n ")" ::: "memory")
; #define PG8_BAR __builtin_amdgcn_s_barrier()
; #define PG8_SCHED __builtin_amdgcn_sched_barrier(0)
; template <class Epi, class Sched>
; DI void gemm_phase(LAS unsigned char* lds, const Gemm g, const Sched& S, const Epi& E) {
;     ...
;       const bool last = (t == nt - 2);
;       const char* a1 = cA + (size_t)(t + 1) * kstep;
;       const char* a2 = last ? nA : cA + (size_t)(t + 2) * kstep; const char* b2 = last ? nB : cB + (size_t)(t + 2) * kstep;
;       const char* a3 = a2 + kstep; const char* b3 = b2 + kstep;
;       PG8_LDB(B0, 0, 0); PG8_SCHED; PG8_LDA(At, 0, 0); PG8_STAGE(PG8_SA(1, 1), a1 + hstep, voffA);
;       PG8_WAIT_L(8); PG8_BAR; PG8_WAIT_L(0); PG8_MMA(0, 0, At, B0); PG8_BAR; PG8_SCHED;
;       PG8_LDB(B1, 0, 1); PG8_STAGE(PG8_SB(0, 0), b2, voffB);
;       PG8_BAR; PG8_WAIT_L(0); PG8_MMA(0, 1, At, B1); PG8_BAR;
;       PG8_LDA(At, 0, 1); PG8_STAGE(PG8_SA(0, 0), a2, voffA);
;       PG8_BAR; PG8_WAIT_L(0); PG8_MMA(1, 0, At, B0); PG8_BAR; PG8_SCHED;
.LBB0_217:
	s_add_i32 s40, s3, 2
	s_add_u32 s18, s16, 0x80
	s_addc_u32 s19, s17, 0
	s_cmp_lg_u32 s39, s3
	s_cselect_b32 s20, s18, 0
	s_cselect_b32 s3, s19, 0
	s_add_u32 s18, s14, s20
	s_addc_u32 s19, s15, s3
	s_add_i32 s41, 16, 0x10000
	v_add_u32_e32 v139, s41, v137
	ds_read_b128 v[140:143], v139
	ds_read_b128 v[148:151], v139 offset:1024
	ds_read_b128 v[152:155], v139 offset:2048
	ds_read_b128 v[156:159], v139 offset:3072
	s_add_u32 s20, s12, s20
	s_addc_u32 s21, s13, s3
	v_lshl_add_u64 v[144:145], v[132:133], 0, s[16:17]
	s_add_i32 m0, s30, 0xc000
	ds_read_b128 v[160:163], v138
	ds_read_b128 v[164:167], v138 offset:1024
	ds_read_b128 v[168:171], v138 offset:2048
	ds_read_b128 v[172:175], v138 offset:3072
	ds_read_b128 v[186:189], v138 offset:4096
	ds_read_b128 v[190:193], v138 offset:5120
	ds_read_b128 v[198:201], v138 offset:6144
	ds_read_b128 v[202:205], v138 offset:7168
	global_load_lds_dwordx4 v[144:145], off
	v_lshl_add_u64 v[144:145], v[134:135], 0, s[16:17]
	s_add_i32 m0, s30, 0xe000
	s_nop 0
	global_load_lds_dwordx4 v[144:145], off
	s_waitcnt lgkmcnt(8)
	s_barrier
	s_waitcnt lgkmcnt(0)
	s_waitcnt lgkmcnt(0)
	v_mfma_f32_16x16x32_bf16 v[126:129], v[140:143], v[160:163], v[126:129]
	v_mfma_f32_16x16x32_bf16 v[122:125], v[152:155], v[160:163], v[122:125]
	v_mfma_f32_16x16x32_bf16 v[110:113], v[140:143], v[168:171], v[110:113]
	v_mfma_f32_16x16x32_bf16 v[106:109], v[152:155], v[168:171], v[106:109]
	v_mfma_f32_16x16x32_bf16 v[94:97], v[140:143], v[186:189], v[94:97]
	v_mfma_f32_16x16x32_bf16 v[90:93], v[152:155], v[186:189], v[90:93]
	v_mfma_f32_16x16x32_bf16 v[78:81], v[140:143], v[198:201], v[78:81]
	v_mfma_f32_16x16x32_bf16 v[74:77], v[152:155], v[198:201], v[74:77]
	v_mfma_f32_16x16x32_bf16 v[126:129], v[148:151], v[164:167], v[126:129]
	v_mfma_f32_16x16x32_bf16 v[122:125], v[156:159], v[164:167], v[122:125]
	v_mfma_f32_16x16x32_bf16 v[110:113], v[148:151], v[172:175], v[110:113]
	v_mfma_f32_16x16x32_bf16 v[106:109], v[156:159], v[172:175], v[106:109]
	v_mfma_f32_16x16x32_bf16 v[94:97], v[148:151], v[190:193], v[94:97]
	v_mfma_f32_16x16x32_bf16 v[90:93], v[156:159], v[190:193], v[90:93]
	v_mfma_f32_16x16x32_bf16 v[78:81], v[148:151], v[202:205], v[78:81]
	v_mfma_f32_16x16x32_bf16 v[74:77], v[156:159], v[202:205], v[74:77]
	s_barrier
	s_add_i32 s3, 16, 0x14000
	s_add_i32 s41, s41, s29
	v_add_u32_e32 v139, s3, v137
	v_lshl_add_u64 v[144:145], s[20:21], 0, v[0:1]
	s_mov_b32 m0, s41
	ds_read_b128 v[206:209], v139
	ds_read_b128 v[214:217], v139 offset:1024
	ds_read_b128 v[218:221], v139 offset:2048
	ds_read_b128 v[222:225], v139 offset:3072
	global_load_lds_dwordx4 v[144:145], off
	v_lshl_add_u64 v[176:177], s[20:21], 0, v[130:131]
	s_add_i32 m0, s41, 0x2000
	s_nop 0
	global_load_lds_dwordx4 v[176:177], off
	s_waitcnt vmcnt(10)
	s_barrier
	s_waitcnt lgkmcnt(0)
	s_waitcnt lgkmcnt(0)
	v_mfma_f32_16x16x32_bf16 v[118:121], v[206:209], v[160:163], v[118:121]
	v_mfma_f32_16x16x32_bf16 v[114:117], v[218:221], v[160:163], v[114:117]
	v_mfma_f32_16x16x32_bf16 v[102:105], v[206:209], v[168:171], v[102:105]
	v_mfma_f32_16x16x32_bf16 v[98:101], v[218:221], v[168:171], v[98:101]
	v_mfma_f32_16x16x32_bf16 v[86:89], v[206:209], v[186:189], v[86:89]
	v_mfma_f32_16x16x32_bf16 v[82:85], v[218:221], v[186:189], v[82:85]
	v_mfma_f32_16x16x32_bf16 v[70:73], v[206:209], v[198:201], v[70:73]
	v_mfma_f32_16x16x32_bf16 v[66:69], v[218:221], v[198:201], v[66:69]
	v_mfma_f32_16x16x32_bf16 v[118:121], v[214:217], v[164:167], v[118:121]
	v_mfma_f32_16x16x32_bf16 v[114:117], v[222:225], v[164:167], v[114:117]
	v_mfma_f32_16x16x32_bf16 v[102:105], v[214:217], v[172:175], v[102:105]
	v_mfma_f32_16x16x32_bf16 v[98:101], v[222:225], v[172:175], v[98:101]
	v_mfma_f32_16x16x32_bf16 v[86:89], v[214:217], v[190:193], v[86:89]
	v_mfma_f32_16x16x32_bf16 v[82:85], v[222:225], v[190:193], v[82:85]
	v_mfma_f32_16x16x32_bf16 v[70:73], v[214:217], v[202:205], v[70:73]
	v_mfma_f32_16x16x32_bf16 v[66:69], v[222:225], v[202:205], v[66:69]
	s_mov_b32 m0, s30
	v_lshl_add_u64 v[180:181], s[18:19], 0, v[0:1]
	s_barrier
	ds_read_b128 v[160:163], v138 offset:16384
	ds_read_b128 v[164:167], v138 offset:17408
	ds_read_b128 v[168:171], v138 offset:18432
	ds_read_b128 v[172:175], v138 offset:19456
	ds_read_b128 v[186:189], v138 offset:20480
	ds_read_b128 v[190:193], v138 offset:21504
	ds_read_b128 v[198:201], v138 offset:22528
	ds_read_b128 v[202:205], v138 offset:23552
	global_load_lds_dwordx4 v[180:181], off
	v_lshl_add_u64 v[182:183], s[18:19], 0, v[130:131]
	s_mov_b32 m0, s31
	s_nop 0
	global_load_lds_dwordx4 v[182:183], off
	s_barrier
	s_waitcnt lgkmcnt(0)
	s_waitcnt lgkmcnt(0)
	v_mfma_f32_16x16x32_bf16 v[62:65], v[140:143], v[160:163], v[62:65]
	v_mfma_f32_16x16x32_bf16 v[58:61], v[152:155], v[160:163], v[58:61]
	v_mfma_f32_16x16x32_bf16 v[50:53], v[140:143], v[168:171], v[50:53]
	v_mfma_f32_16x16x32_bf16 v[42:45], v[152:155], v[168:171], v[42:45]
	v_mfma_f32_16x16x32_bf16 v[34:37], v[140:143], v[186:189], v[34:37]
	v_mfma_f32_16x16x32_bf16 v[26:29], v[152:155], v[186:189], v[26:29]
	v_mfma_f32_16x16x32_bf16 v[14:17], v[140:143], v[198:201], v[14:17]
	v_mfma_f32_16x16x32_bf16 v[10:13], v[152:155], v[198:201], v[10:13]
	v_mfma_f32_16x16x32_bf16 v[62:65], v[148:151], v[164:167], v[62:65]
	v_mfma_f32_16x16x32_bf16 v[58:61], v[156:159], v[164:167], v[58:61]
	v_mfma_f32_16x16x32_bf16 v[50:53], v[148:151], v[172:175], v[50:53]
	v_mfma_f32_16x16x32_bf16 v[42:45], v[156:159], v[172:175], v[42:45]
	v_mfma_f32_16x16x32_bf16 v[34:37], v[148:151], v[190:193], v[34:37]
	v_mfma_f32_16x16x32_bf16 v[26:29], v[156:159], v[190:193], v[26:29]
	v_mfma_f32_16x16x32_bf16 v[14:17], v[148:151], v[202:205], v[14:17]
	v_mfma_f32_16x16x32_bf16 v[10:13], v[156:159], v[202:205], v[10:13]
	s_barrier
; #define PG8_STAGE(bufoff, gbase, voff) do { _Pragma("unroll") for (int _i = 0; _i < 2; ++_i) \
;     __builtin_amdgcn_global_load_lds((const unsigned*)((const char*)(gbase) + (voff)[_i]), (LAS unsigned*)(lds + (bufoff) + ldsw + _i * 8192), 16, 0, 0); } while (0)
; #define PG8_LDA(dst, b, h) do { _Pragma("unroll") for (int m = 0; m < 4; ++m) _Pragma("unroll") for (int k = 0; k < 2; ++k) dst[m][k] = *(const LAS bf16x8*)(lds + PG8_SA(b, h) + aoff + m * 2048 + k * 1024); } while (0)
; #define PG8_LDB(dst, b, h) do { _Pragma("unroll") for (int n = 0; n < 2; ++n) _Pragma("unroll") for (int k = 0; k < 2; ++k) dst[n][k] = *(const LAS bf16x8*)(lds + PG8_SB(b, h) + boff + n * 2048 + k * 1024); } while (0)
; #define PG8_MMA(ai, bj, At, Bt) do { __builtin_amdgcn_s_setprio(1); _Pragma("unroll") for (int m = 0; m < 4; ++m) _Pragma("unroll") for (int n = 0; n < 2; ++n) _Pragma("unroll") for (int k = 0; k < 2; ++k) \
;     acc[ai][bj][m][n] = __builtin_amdgcn_mfma_f32_16x16x32_bf16(Bt[n][k], At[m][k], acc[ai][bj][m][n], 0, 0, 0); __builtin_amdgcn_s_setprio(0); } while (0)
; #define PG8_WAIT_V(n) asm volatile("s_waitcnt vmcnt(" #n ")" ::: "memory")
; #define PG8_WAIT_L(n) asm volatile("s_waitcnt lgkmcnt(" #n ")" ::: "memory")
; #define PG8_BAR __builtin_amdgcn_s_barrier()
; #define PG8_SCHED __builtin_amdgcn_sched_barrier(0)
; template <class Epi, class Sched>
; DI void gemm_phase(LAS unsigned char* lds, const Gemm g, const Sched& S, const Epi& E) {
;     ...
;       PG8_STAGE(PG8_SB(0, 1), b2 + hstepB, voffB);
;       PG8_WAIT_V(6); PG8_BAR; PG8_MMA(1, 1, At, B1); PG8_BAR;
;       PG8_LDB(B0, 1, 0); PG8_SCHED; PG8_LDA(At, 1, 0); PG8_STAGE(PG8_SA(0, 1), a2 + hstep, voffA);
;       PG8_WAIT_L(8); PG8_BAR; PG8_WAIT_L(0); PG8_MMA(0, 0, At, B0); PG8_BAR; PG8_SCHED;
;       PG8_LDB(B1, 1, 1); PG8_STAGE(PG8_SB(1, 0), b3, voffB);
	s_add_u32 s20, s20, s10
	s_addc_u32 s21, s21, s11
	s_add_i32 s3, s3, s29
	v_lshl_add_u64 v[184:185], s[20:21], 0, v[0:1]
	s_mov_b32 m0, s3
	v_lshl_add_u64 v[226:227], s[20:21], 0, v[130:131]
	global_load_lds_dwordx4 v[184:185], off
	s_add_i32 m0, s3, 0x2000
	s_nop 0
	global_load_lds_dwordx4 v[226:227], off
	s_waitcnt vmcnt(8)
	s_barrier
	v_mfma_f32_16x16x32_bf16 v[54:57], v[206:209], v[160:163], v[54:57]
	v_mfma_f32_16x16x32_bf16 v[46:49], v[218:221], v[160:163], v[46:49]
	v_mfma_f32_16x16x32_bf16 v[38:41], v[206:209], v[168:171], v[38:41]
	v_mfma_f32_16x16x32_bf16 v[30:33], v[218:221], v[168:171], v[30:33]
	v_mfma_f32_16x16x32_bf16 v[22:25], v[206:209], v[186:189], v[22:25]
	v_mfma_f32_16x16x32_bf16 v[18:21], v[218:221], v[186:189], v[18:21]
	v_mfma_f32_16x16x32_bf16 v[6:9], v[206:209], v[198:201], v[6:9]
	v_mfma_f32_16x16x32_bf16 v[2:5], v[218:221], v[198:201], v[2:5]
	v_mfma_f32_16x16x32_bf16 v[54:57], v[214:217], v[164:167], v[54:57]
	v_mfma_f32_16x16x32_bf16 v[46:49], v[222:225], v[164:167], v[46:49]
	v_mfma_f32_16x16x32_bf16 v[38:41], v[214:217], v[172:175], v[38:41]
	v_mfma_f32_16x16x32_bf16 v[30:33], v[222:225], v[172:175], v[30:33]
	v_mfma_f32_16x16x32_bf16 v[22:25], v[214:217], v[190:193], v[22:25]
	v_mfma_f32_16x16x32_bf16 v[18:21], v[222:225], v[190:193], v[18:21]
	v_mfma_f32_16x16x32_bf16 v[6:9], v[214:217], v[202:205], v[6:9]
	v_mfma_f32_16x16x32_bf16 v[2:5], v[222:225], v[202:205], v[2:5]
	s_add_i32 s3, 16, 0x18000
	v_add_u32_e32 v139, s3, v137
	s_barrier
	ds_read_b128 v[140:143], v139
	ds_read_b128 v[148:151], v139 offset:1024
	ds_read_b128 v[152:155], v139 offset:2048
	ds_read_b128 v[156:159], v139 offset:3072
	s_add_u32 s18, s18, s10
	s_addc_u32 s19, s19, s11
	s_mov_b32 m0, s34
	v_lshl_add_u64 v[206:207], s[18:19], 0, v[0:1]
	ds_read_b128 v[160:163], v138 offset:32768
	ds_read_b128 v[164:167], v138 offset:33792
	ds_read_b128 v[168:171], v138 offset:34816
	ds_read_b128 v[172:175], v138 offset:35840
	ds_read_b128 v[186:189], v138 offset:36864
	ds_read_b128 v[190:193], v138 offset:37888
	ds_read_b128 v[198:201], v138 offset:38912
	ds_read_b128 v[202:205], v138 offset:39936
	global_load_lds_dwordx4 v[206:207], off
	v_lshl_add_u64 v[206:207], s[18:19], 0, v[130:131]
	s_mov_b32 m0, s35
	s_nop 0
	global_load_lds_dwordx4 v[206:207], off
	s_waitcnt lgkmcnt(8)
	s_barrier
	s_waitcnt lgkmcnt(0)
	s_waitcnt lgkmcnt(0)
	v_mfma_f32_16x16x32_bf16 v[126:129], v[140:143], v[160:163], v[126:129]
	v_mfma_f32_16x16x32_bf16 v[122:125], v[152:155], v[160:163], v[122:125]
	v_mfma_f32_16x16x32_bf16 v[110:113], v[140:143], v[168:171], v[110:113]
	v_mfma_f32_16x16x32_bf16 v[106:109], v[152:155], v[168:171], v[106:109]
	v_mfma_f32_16x16x32_bf16 v[94:97], v[140:143], v[186:189], v[94:97]
	v_mfma_f32_16x16x32_bf16 v[90:93], v[152:155], v[186:189], v[90:93]
	v_mfma_f32_16x16x32_bf16 v[78:81], v[140:143], v[198:201], v[78:81]
	v_mfma_f32_16x16x32_bf16 v[74:77], v[152:155], v[198:201], v[74:77]
	v_mfma_f32_16x16x32_bf16 v[126:129], v[148:151], v[164:167], v[126:129]
	v_mfma_f32_16x16x32_bf16 v[122:125], v[156:159], v[164:167], v[122:125]
	v_mfma_f32_16x16x32_bf16 v[110:113], v[148:151], v[172:175], v[110:113]
	v_mfma_f32_16x16x32_bf16 v[106:109], v[156:159], v[172:175], v[106:109]
	v_mfma_f32_16x16x32_bf16 v[94:97], v[148:151], v[190:193], v[94:97]
	v_mfma_f32_16x16x32_bf16 v[90:93], v[156:159], v[190:193], v[90:93]
	v_mfma_f32_16x16x32_bf16 v[78:81], v[148:151], v[202:205], v[78:81]
	v_mfma_f32_16x16x32_bf16 v[74:77], v[156:159], v[202:205], v[74:77]
	s_barrier
	s_add_i32 s18, 16, 0x1c000
	s_add_i32 s3, s3, s29
	v_add_u32_e32 v139, s18, v137
	v_lshl_add_u64 v[144:145], v[144:145], 0, s[70:71]
	s_mov_b32 m0, s3
	ds_read_b128 v[206:209], v139
	ds_read_b128 v[214:217], v139 offset:1024
	ds_read_b128 v[218:221], v139 offset:2048
	ds_read_b128 v[222:225], v139 offset:3072
	global_load_lds_dwordx4 v[144:145], off
	v_lshl_add_u64 v[144:145], v[176:177], 0, s[70:71]
	s_add_i32 m0, s3, 0x2000
	s_nop 0
	global_load_lds_dwordx4 v[144:145], off
	s_waitcnt vmcnt(10)
	s_barrier
; #define PG8_STAGE(bufoff, gbase, voff) do { _Pragma("unroll") for (int _i = 0; _i < 2; ++_i) \
;     __builtin_amdgcn_global_load_lds((const unsigned*)((const char*)(gbase) + (voff)[_i]), (LAS unsigned*)(lds + (bufoff) + ldsw + _i * 8192), 16, 0, 0); } while (0)
; #define PG8_LDA(dst, b, h) do { _Pragma("unroll") for (int m = 0; m < 4; ++m) _Pragma("unroll") for (int k = 0; k < 2; ++k) dst[m][k] = *(const LAS bf16x8*)(lds + PG8_SA(b, h) + aoff + m * 2048 + k * 1024); } while (0)
; #define PG8_LDB(dst, b, h) do { _Pragma("unroll") for (int n = 0; n < 2; ++n) _Pragma("unroll") for (int k = 0; k < 2; ++k) dst[n][k] = *(const LAS bf16x8*)(lds + PG8_SB(b, h) + boff + n * 2048 + k * 1024); } while (0)
; #define PG8_MMA(ai, bj, At, Bt) do { __builtin_amdgcn_s_setprio(1); _Pragma("unroll") for (int m = 0; m < 4; ++m) _Pragma("unroll") for (int n = 0; n < 2; ++n) _Pragma("unroll") for (int k = 0; k < 2; ++k) \
;     acc[ai][bj][m][n] = __builtin_amdgcn_mfma_f32_16x16x32_bf16(Bt[n][k], At[m][k], acc[ai][bj][m][n], 0, 0, 0); __builtin_amdgcn_s_setprio(0); } while (0)
; #define PG8_WAIT_V(n) asm volatile("s_waitcnt vmcnt(" #n ")" ::: "memory")
; #define PG8_WAIT_L(n) asm volatile("s_waitcnt lgkmcnt(" #n ")" ::: "memory")
; #define PG8_BAR __builtin_amdgcn_s_barrier()
; #define PG8_SCHED __builtin_amdgcn_sched_barrier(0)
; template <class Epi, class Sched>
; DI void gemm_phase(LAS unsigned char* lds, const Gemm g, const Sched& S, const Epi& E) {
;     ...
;       PG8_LDB(B1, 1, 1); PG8_STAGE(PG8_SB(1, 0), b3, voffB);
;       PG8_BAR; PG8_WAIT_L(0); PG8_MMA(0, 1, At, B1); PG8_BAR;
;       PG8_LDA(At, 1, 1); PG8_STAGE(PG8_SA(1, 0), a3, voffA);
;       PG8_BAR; PG8_WAIT_L(0); PG8_MMA(1, 0, At, B0); PG8_BAR; PG8_SCHED;
;       PG8_STAGE(PG8_SB(1, 1), b3 + hstepB, voffB);
;       PG8_WAIT_V(6); PG8_BAR; PG8_MMA(1, 1, At, B1); PG8_BAR;
;     }
	s_waitcnt lgkmcnt(0)
	s_waitcnt lgkmcnt(0)
	v_mfma_f32_16x16x32_bf16 v[118:121], v[206:209], v[160:163], v[118:121]
	v_mfma_f32_16x16x32_bf16 v[114:117], v[218:221], v[160:163], v[114:117]
	v_mfma_f32_16x16x32_bf16 v[102:105], v[206:209], v[168:171], v[102:105]
	v_mfma_f32_16x16x32_bf16 v[98:101], v[218:221], v[168:171], v[98:101]
	v_mfma_f32_16x16x32_bf16 v[86:89], v[206:209], v[186:189], v[86:89]
	v_mfma_f32_16x16x32_bf16 v[82:85], v[218:221], v[186:189], v[82:85]
	v_mfma_f32_16x16x32_bf16 v[70:73], v[206:209], v[198:201], v[70:73]
	v_mfma_f32_16x16x32_bf16 v[66:69], v[218:221], v[198:201], v[66:69]
	v_mfma_f32_16x16x32_bf16 v[118:121], v[214:217], v[164:167], v[118:121]
	v_mfma_f32_16x16x32_bf16 v[114:117], v[222:225], v[164:167], v[114:117]
	v_mfma_f32_16x16x32_bf16 v[102:105], v[214:217], v[172:175], v[102:105]
	v_mfma_f32_16x16x32_bf16 v[98:101], v[222:225], v[172:175], v[98:101]
	v_mfma_f32_16x16x32_bf16 v[86:89], v[214:217], v[190:193], v[86:89]
	v_mfma_f32_16x16x32_bf16 v[82:85], v[222:225], v[190:193], v[82:85]
	v_mfma_f32_16x16x32_bf16 v[70:73], v[214:217], v[202:205], v[70:73]
	v_mfma_f32_16x16x32_bf16 v[66:69], v[222:225], v[202:205], v[66:69]
	s_mov_b32 m0, s36
	v_lshl_add_u64 v[144:145], v[180:181], 0, s[70:71]
	s_barrier
	ds_read_b128 v[160:163], v138 offset:49152
	ds_read_b128 v[164:167], v138 offset:50176
	ds_read_b128 v[168:171], v138 offset:51200
	ds_read_b128 v[172:175], v138 offset:52224
	ds_read_b128 v[186:189], v138 offset:53248
	ds_read_b128 v[190:193], v138 offset:54272
	ds_read_b128 v[198:201], v138 offset:55296
	ds_read_b128 v[202:205], v138 offset:56320
	global_load_lds_dwordx4 v[144:145], off
	v_lshl_add_u64 v[144:145], v[182:183], 0, s[70:71]
	s_mov_b32 m0, s37
	s_nop 0
	global_load_lds_dwordx4 v[144:145], off
	s_barrier
	s_waitcnt lgkmcnt(0)
	s_waitcnt lgkmcnt(0)
	v_mfma_f32_16x16x32_bf16 v[62:65], v[140:143], v[160:163], v[62:65]
	v_mfma_f32_16x16x32_bf16 v[58:61], v[152:155], v[160:163], v[58:61]
	v_mfma_f32_16x16x32_bf16 v[50:53], v[140:143], v[168:171], v[50:53]
	v_mfma_f32_16x16x32_bf16 v[42:45], v[152:155], v[168:171], v[42:45]
	v_mfma_f32_16x16x32_bf16 v[34:37], v[140:143], v[186:189], v[34:37]
	v_mfma_f32_16x16x32_bf16 v[26:29], v[152:155], v[186:189], v[26:29]
	v_mfma_f32_16x16x32_bf16 v[14:17], v[140:143], v[198:201], v[14:17]
	v_mfma_f32_16x16x32_bf16 v[10:13], v[152:155], v[198:201], v[10:13]
	v_mfma_f32_16x16x32_bf16 v[62:65], v[148:151], v[164:167], v[62:65]
	v_mfma_f32_16x16x32_bf16 v[58:61], v[156:159], v[164:167], v[58:61]
	v_mfma_f32_16x16x32_bf16 v[50:53], v[148:151], v[172:175], v[50:53]
	v_mfma_f32_16x16x32_bf16 v[42:45], v[156:159], v[172:175], v[42:45]
	v_mfma_f32_16x16x32_bf16 v[34:37], v[148:151], v[190:193], v[34:37]
	v_mfma_f32_16x16x32_bf16 v[26:29], v[156:159], v[190:193], v[26:29]
	v_mfma_f32_16x16x32_bf16 v[14:17], v[148:151], v[202:205], v[14:17]
	v_mfma_f32_16x16x32_bf16 v[10:13], v[156:159], v[202:205], v[10:13]
	s_barrier
	s_add_i32 s3, s18, s29
	v_lshl_add_u64 v[140:141], v[184:185], 0, s[70:71]
	s_mov_b32 m0, s3
	s_nop 0
	global_load_lds_dwordx4 v[140:141], off
	v_lshl_add_u64 v[140:141], v[226:227], 0, s[70:71]
	s_add_i32 m0, s3, 0x2000
	s_nop 0
	global_load_lds_dwordx4 v[140:141], off
	s_waitcnt vmcnt(8)
	s_barrier
	v_mfma_f32_16x16x32_bf16 v[54:57], v[206:209], v[160:163], v[54:57]
	v_mfma_f32_16x16x32_bf16 v[46:49], v[218:221], v[160:163], v[46:49]
	v_mfma_f32_16x16x32_bf16 v[38:41], v[206:209], v[168:171], v[38:41]
	v_mfma_f32_16x16x32_bf16 v[30:33], v[218:221], v[168:171], v[30:33]
	v_mfma_f32_16x16x32_bf16 v[22:25], v[206:209], v[186:189], v[22:25]
	v_mfma_f32_16x16x32_bf16 v[18:21], v[218:221], v[186:189], v[18:21]
	v_mfma_f32_16x16x32_bf16 v[6:9], v[206:209], v[198:201], v[6:9]
	v_mfma_f32_16x16x32_bf16 v[2:5], v[218:221], v[198:201], v[2:5]
	v_mfma_f32_16x16x32_bf16 v[54:57], v[214:217], v[164:167], v[54:57]
	v_mfma_f32_16x16x32_bf16 v[46:49], v[222:225], v[164:167], v[46:49]
	v_mfma_f32_16x16x32_bf16 v[38:41], v[214:217], v[172:175], v[38:41]
	v_mfma_f32_16x16x32_bf16 v[30:33], v[222:225], v[172:175], v[30:33]
	v_mfma_f32_16x16x32_bf16 v[22:25], v[214:217], v[190:193], v[22:25]
	v_mfma_f32_16x16x32_bf16 v[18:21], v[222:225], v[190:193], v[18:21]
	v_mfma_f32_16x16x32_bf16 v[6:9], v[214:217], v[202:205], v[6:9]
	v_mfma_f32_16x16x32_bf16 v[2:5], v[222:225], v[202:205], v[2:5]
	s_add_u32 s16, s16, 0x100
	s_addc_u32 s17, s17, 0
	s_cmp_ge_i32 s40, s38
	s_mov_b32 s3, s40
	s_barrier
	s_cbranch_scc0 .LBB0_217

; #define PG8_STAGE(bufoff, gbase, voff) do { _Pragma("unroll") for (int _i = 0; _i < 2; ++_i) \
;     __builtin_amdgcn_global_load_lds((const unsigned*)((const char*)(gbase) + (voff)[_i]), (LAS unsigned*)(lds + (bufoff) + ldsw + _i * 8192), 16, 0, 0); } while (0)
; #define PG8_LDA(dst, b, h) do { _Pragma("unroll") for (int m = 0; m < 4; ++m) _Pragma("unroll") for (int k = 0; k < 2; ++k) dst[m][k] = *(const LAS bf16x8*)(lds + PG8_SA(b, h) + aoff + m * 2048 + k * 1024); } while (0)
; #define PG8_LDB(dst, b, h) do { _Pragma("unroll") for (int n = 0; n < 2; ++n) _Pragma("unroll") for (int k = 0; k < 2; ++k) dst[n][k] = *(const LAS bf16x8*)(lds + PG8_SB(b, h) + boff + n * 2048 + k * 1024); } while (0)
; #define PG8_MMA(ai, bj, At, Bt) do { __builtin_amdgcn_s_setprio(1); _Pragma("unroll") for (int m = 0; m < 4; ++m) _Pragma("unroll") for (int n = 0; n < 2; ++n) _Pragma("unroll") for (int k = 0; k < 2; ++k) \
;     acc[ai][bj][m][n] = __builtin_amdgcn_mfma_f32_16x16x32_bf16(Bt[n][k], At[m][k], acc[ai][bj][m][n], 0, 0, 0); __builtin_amdgcn_s_setprio(0); } while (0)
; #define PG8_WAIT_L(n) asm volatile("s_waitcnt lgkmcnt(" #n ")" ::: "memory")
; #define PG8_BAR __builtin_amdgcn_s_barrier()
; #define PG8_SCHED __builtin_amdgcn_sched_barrier(0)
; template <class Epi, class Sched>
; DI void gemm_phase(LAS unsigned char* lds, const Gemm g, const Sched& S, const Epi& E) {
;     ...
;       const bool last = (t == nt - 2);
;       const char* a1 = cA + (size_t)(t + 1) * kstep;
;       const char* a2 = last ? nA : cA + (size_t)(t + 2) * kstep; const char* b2 = last ? nB : cB + (size_t)(t + 2) * kstep;
;       const char* a3 = a2 + kstep; const char* b3 = b2 + kstep;
;       PG8_LDB(B0, 0, 0); PG8_SCHED; PG8_LDA(At, 0, 0); PG8_STAGE(PG8_SA(1, 1), a1 + hstep, voffA);
;       PG8_WAIT_L(8); PG8_BAR; PG8_WAIT_L(0); PG8_MMA(0, 0, At, B0); PG8_BAR; PG8_SCHED;
;       PG8_LDB(B1, 0, 1); PG8_STAGE(PG8_SB(0, 0), b2, voffB);
;       PG8_BAR; PG8_WAIT_L(0); PG8_MMA(0, 1, At, B1); PG8_BAR;
;       PG8_LDA(At, 0, 1); PG8_STAGE(PG8_SA(0, 0), a2, voffA);
;       PG8_BAR; PG8_WAIT_L(0); PG8_MMA(1, 0, At, B0); PG8_BAR; PG8_SCHED;
.LBB0_491:
	s_add_i32 s26, s8, 2
	s_add_u32 s9, s6, 0xfe000080
	s_addc_u32 s10, s7, -1
	s_cmp_lg_u32 s25, s8
	s_cselect_b32 s11, s10, 0
	s_cselect_b32 s10, s9, 0
	s_add_u32 s8, s4, s10
	s_addc_u32 s9, s5, s11
	s_add_i32 s27, 16, 0x10000
	v_add_u32_e32 v139, s27, v133
	ds_read_b128 v[140:143], v139
	ds_read_b128 v[148:151], v139 offset:1024
	ds_read_b128 v[152:155], v139 offset:2048
	ds_read_b128 v[156:159], v139 offset:3072
	s_add_u32 s10, s2, s10
	s_addc_u32 s11, s3, s11
	v_lshl_add_u64 v[144:145], v[128:129], 0, s[6:7]
	s_add_i32 m0, s18, 0xc000
	ds_read_b128 v[160:163], v138
	ds_read_b128 v[164:167], v138 offset:1024
	ds_read_b128 v[168:171], v138 offset:2048
	ds_read_b128 v[172:175], v138 offset:3072
	ds_read_b128 v[186:189], v138 offset:4096
	ds_read_b128 v[190:193], v138 offset:5120
	ds_read_b128 v[198:201], v138 offset:6144
	ds_read_b128 v[202:205], v138 offset:7168
	global_load_lds_dwordx4 v[144:145], off
	v_lshl_add_u64 v[144:145], v[130:131], 0, s[6:7]
	s_add_i32 m0, s18, 0xe000
	s_nop 0
	global_load_lds_dwordx4 v[144:145], off
	s_waitcnt lgkmcnt(8)
	s_barrier
	s_waitcnt lgkmcnt(0)
	s_waitcnt lgkmcnt(0)
	v_mfma_f32_16x16x32_bf16 v[134:137], v[140:143], v[160:163], v[134:137]
	v_mfma_f32_16x16x32_bf16 v[122:125], v[152:155], v[160:163], v[122:125]
	v_mfma_f32_16x16x32_bf16 v[110:113], v[140:143], v[168:171], v[110:113]
	v_mfma_f32_16x16x32_bf16 v[106:109], v[152:155], v[168:171], v[106:109]
	v_mfma_f32_16x16x32_bf16 v[94:97], v[140:143], v[186:189], v[94:97]
	v_mfma_f32_16x16x32_bf16 v[90:93], v[152:155], v[186:189], v[90:93]
	v_mfma_f32_16x16x32_bf16 v[78:81], v[140:143], v[198:201], v[78:81]
	v_mfma_f32_16x16x32_bf16 v[74:77], v[152:155], v[198:201], v[74:77]
	v_mfma_f32_16x16x32_bf16 v[134:137], v[148:151], v[164:167], v[134:137]
	v_mfma_f32_16x16x32_bf16 v[122:125], v[156:159], v[164:167], v[122:125]
	v_mfma_f32_16x16x32_bf16 v[110:113], v[148:151], v[172:175], v[110:113]
	v_mfma_f32_16x16x32_bf16 v[106:109], v[156:159], v[172:175], v[106:109]
	v_mfma_f32_16x16x32_bf16 v[94:97], v[148:151], v[190:193], v[94:97]
	v_mfma_f32_16x16x32_bf16 v[90:93], v[156:159], v[190:193], v[90:93]
	v_mfma_f32_16x16x32_bf16 v[78:81], v[148:151], v[202:205], v[78:81]
	v_mfma_f32_16x16x32_bf16 v[74:77], v[156:159], v[202:205], v[74:77]
	s_barrier
	s_add_i32 s28, 16, 0x14000
	s_add_i32 s27, s27, s17
	v_add_u32_e32 v139, s28, v133
	v_lshl_add_u64 v[144:145], s[10:11], 0, v[0:1]
	s_mov_b32 m0, s27
	ds_read_b128 v[206:209], v139
	ds_read_b128 v[214:217], v139 offset:1024
	ds_read_b128 v[218:221], v139 offset:2048
	ds_read_b128 v[222:225], v139 offset:3072
	global_load_lds_dwordx4 v[144:145], off
	v_lshl_add_u64 v[176:177], s[10:11], 0, v[126:127]
	s_add_i32 m0, s27, 0x2000
	s_nop 0
	global_load_lds_dwordx4 v[176:177], off
	s_waitcnt vmcnt(10)
	s_barrier
	s_waitcnt lgkmcnt(0)
	s_waitcnt lgkmcnt(0)
	v_mfma_f32_16x16x32_bf16 v[118:121], v[206:209], v[160:163], v[118:121]
	v_mfma_f32_16x16x32_bf16 v[114:117], v[218:221], v[160:163], v[114:117]
	v_mfma_f32_16x16x32_bf16 v[102:105], v[206:209], v[168:171], v[102:105]
	v_mfma_f32_16x16x32_bf16 v[98:101], v[218:221], v[168:171], v[98:101]
	v_mfma_f32_16x16x32_bf16 v[86:89], v[206:209], v[186:189], v[86:89]
	v_mfma_f32_16x16x32_bf16 v[82:85], v[218:221], v[186:189], v[82:85]
	v_mfma_f32_16x16x32_bf16 v[70:73], v[206:209], v[198:201], v[70:73]
	v_mfma_f32_16x16x32_bf16 v[66:69], v[218:221], v[198:201], v[66:69]
	v_mfma_f32_16x16x32_bf16 v[118:121], v[214:217], v[164:167], v[118:121]
	v_mfma_f32_16x16x32_bf16 v[114:117], v[222:225], v[164:167], v[114:117]
	v_mfma_f32_16x16x32_bf16 v[102:105], v[214:217], v[172:175], v[102:105]
	v_mfma_f32_16x16x32_bf16 v[98:101], v[222:225], v[172:175], v[98:101]
	v_mfma_f32_16x16x32_bf16 v[86:89], v[214:217], v[190:193], v[86:89]
	v_mfma_f32_16x16x32_bf16 v[82:85], v[222:225], v[190:193], v[82:85]
	v_mfma_f32_16x16x32_bf16 v[70:73], v[214:217], v[202:205], v[70:73]
	v_mfma_f32_16x16x32_bf16 v[66:69], v[222:225], v[202:205], v[66:69]
	s_mov_b32 m0, s18
	v_lshl_add_u64 v[180:181], s[8:9], 0, v[0:1]
	s_barrier
	ds_read_b128 v[160:163], v138 offset:16384
	ds_read_b128 v[164:167], v138 offset:17408
	ds_read_b128 v[168:171], v138 offset:18432
	ds_read_b128 v[172:175], v138 offset:19456
	ds_read_b128 v[186:189], v138 offset:20480
	ds_read_b128 v[190:193], v138 offset:21504
	ds_read_b128 v[198:201], v138 offset:22528
	ds_read_b128 v[202:205], v138 offset:23552
	global_load_lds_dwordx4 v[180:181], off
	v_lshl_add_u64 v[182:183], s[8:9], 0, v[126:127]
	s_mov_b32 m0, s19
	s_nop 0
	global_load_lds_dwordx4 v[182:183], off
	s_barrier
	s_waitcnt lgkmcnt(0)
	s_waitcnt lgkmcnt(0)
	v_mfma_f32_16x16x32_bf16 v[62:65], v[140:143], v[160:163], v[62:65]
	v_mfma_f32_16x16x32_bf16 v[58:61], v[152:155], v[160:163], v[58:61]
	v_mfma_f32_16x16x32_bf16 v[50:53], v[140:143], v[168:171], v[50:53]
	v_mfma_f32_16x16x32_bf16 v[42:45], v[152:155], v[168:171], v[42:45]
	v_mfma_f32_16x16x32_bf16 v[34:37], v[140:143], v[186:189], v[34:37]
	v_mfma_f32_16x16x32_bf16 v[26:29], v[152:155], v[186:189], v[26:29]
	v_mfma_f32_16x16x32_bf16 v[18:21], v[140:143], v[198:201], v[18:21]
	v_mfma_f32_16x16x32_bf16 v[10:13], v[152:155], v[198:201], v[10:13]
	v_mfma_f32_16x16x32_bf16 v[62:65], v[148:151], v[164:167], v[62:65]
	v_mfma_f32_16x16x32_bf16 v[58:61], v[156:159], v[164:167], v[58:61]
	v_mfma_f32_16x16x32_bf16 v[50:53], v[148:151], v[172:175], v[50:53]
	v_mfma_f32_16x16x32_bf16 v[42:45], v[156:159], v[172:175], v[42:45]
	v_mfma_f32_16x16x32_bf16 v[34:37], v[148:151], v[190:193], v[34:37]
	v_mfma_f32_16x16x32_bf16 v[26:29], v[156:159], v[190:193], v[26:29]
	v_mfma_f32_16x16x32_bf16 v[18:21], v[148:151], v[202:205], v[18:21]
	v_mfma_f32_16x16x32_bf16 v[10:13], v[156:159], v[202:205], v[10:13]
	s_barrier
; #define PG8_STAGE(bufoff, gbase, voff) do { _Pragma("unroll") for (int _i = 0; _i < 2; ++_i) \
;     __builtin_amdgcn_global_load_lds((const unsigned*)((const char*)(gbase) + (voff)[_i]), (LAS unsigned*)(lds + (bufoff) + ldsw + _i * 8192), 16, 0, 0); } while (0)
; #define PG8_LDA(dst, b, h) do { _Pragma("unroll") for (int m = 0; m < 4; ++m) _Pragma("unroll") for (int k = 0; k < 2; ++k) dst[m][k] = *(const LAS bf16x8*)(lds + PG8_SA(b, h) + aoff + m * 2048 + k * 1024); } while (0)
; #define PG8_LDB(dst, b, h) do { _Pragma("unroll") for (int n = 0; n < 2; ++n) _Pragma("unroll") for (int k = 0; k < 2; ++k) dst[n][k] = *(const LAS bf16x8*)(lds + PG8_SB(b, h) + boff + n * 2048 + k * 1024); } while (0)
; #define PG8_MMA(ai, bj, At, Bt) do { __builtin_amdgcn_s_setprio(1); _Pragma("unroll") for (int m = 0; m < 4; ++m) _Pragma("unroll") for (int n = 0; n < 2; ++n) _Pragma("unroll") for (int k = 0; k < 2; ++k) \
;     acc[ai][bj][m][n] = __builtin_amdgcn_mfma_f32_16x16x32_bf16(Bt[n][k], At[m][k], acc[ai][bj][m][n], 0, 0, 0); __builtin_amdgcn_s_setprio(0); } while (0)
; #define PG8_WAIT_V(n) asm volatile("s_waitcnt vmcnt(" #n ")" ::: "memory")
; #define PG8_WAIT_L(n) asm volatile("s_waitcnt lgkmcnt(" #n ")" ::: "memory")
; #define PG8_BAR __builtin_amdgcn_s_barrier()
; #define PG8_SCHED __builtin_amdgcn_sched_barrier(0)
; template <class Epi, class Sched>
; DI void gemm_phase(LAS unsigned char* lds, const Gemm g, const Sched& S, const Epi& E) {
;     ...
;       PG8_STAGE(PG8_SB(0, 1), b2 + hstepB, voffB);
;       PG8_WAIT_V(6); PG8_BAR; PG8_MMA(1, 1, At, B1); PG8_BAR;
;       PG8_LDB(B0, 1, 0); PG8_SCHED; PG8_LDA(At, 1, 0); PG8_STAGE(PG8_SA(0, 1), a2 + hstep, voffA);
;       PG8_WAIT_L(8); PG8_BAR; PG8_WAIT_L(0); PG8_MMA(0, 0, At, B0); PG8_BAR; PG8_SCHED;
;       PG8_LDB(B1, 1, 1); PG8_STAGE(PG8_SB(1, 0), b3, voffB);
	s_add_u32 s10, s10, s0
	s_addc_u32 s11, s11, s1
	s_add_i32 s27, s28, s17
	v_lshl_add_u64 v[184:185], s[10:11], 0, v[0:1]
	s_mov_b32 m0, s27
	v_lshl_add_u64 v[226:227], s[10:11], 0, v[126:127]
	global_load_lds_dwordx4 v[184:185], off
	s_add_i32 m0, s27, 0x2000
	s_nop 0
	global_load_lds_dwordx4 v[226:227], off
	s_waitcnt vmcnt(8)
	s_barrier
	v_mfma_f32_16x16x32_bf16 v[54:57], v[206:209], v[160:163], v[54:57]
	v_mfma_f32_16x16x32_bf16 v[46:49], v[218:221], v[160:163], v[46:49]
	v_mfma_f32_16x16x32_bf16 v[38:41], v[206:209], v[168:171], v[38:41]
	v_mfma_f32_16x16x32_bf16 v[30:33], v[218:221], v[168:171], v[30:33]
	v_mfma_f32_16x16x32_bf16 v[22:25], v[206:209], v[186:189], v[22:25]
	v_mfma_f32_16x16x32_bf16 v[14:17], v[218:221], v[186:189], v[14:17]
	v_mfma_f32_16x16x32_bf16 v[6:9], v[206:209], v[198:201], v[6:9]
	v_mfma_f32_16x16x32_bf16 v[2:5], v[218:221], v[198:201], v[2:5]
	v_mfma_f32_16x16x32_bf16 v[54:57], v[214:217], v[164:167], v[54:57]
	v_mfma_f32_16x16x32_bf16 v[46:49], v[222:225], v[164:167], v[46:49]
	v_mfma_f32_16x16x32_bf16 v[38:41], v[214:217], v[172:175], v[38:41]
	v_mfma_f32_16x16x32_bf16 v[30:33], v[222:225], v[172:175], v[30:33]
	v_mfma_f32_16x16x32_bf16 v[22:25], v[214:217], v[190:193], v[22:25]
	v_mfma_f32_16x16x32_bf16 v[14:17], v[222:225], v[190:193], v[14:17]
	v_mfma_f32_16x16x32_bf16 v[6:9], v[214:217], v[202:205], v[6:9]
	v_mfma_f32_16x16x32_bf16 v[2:5], v[222:225], v[202:205], v[2:5]
	s_add_i32 s10, 16, 0x18000
	v_add_u32_e32 v139, s10, v133
	s_barrier
	ds_read_b128 v[140:143], v139
	ds_read_b128 v[148:151], v139 offset:1024
	ds_read_b128 v[152:155], v139 offset:2048
	ds_read_b128 v[156:159], v139 offset:3072
	s_add_u32 s8, s8, s0
	s_addc_u32 s9, s9, s1
	s_mov_b32 m0, s20
	v_lshl_add_u64 v[206:207], s[8:9], 0, v[0:1]
	ds_read_b128 v[160:163], v138 offset:32768
	ds_read_b128 v[164:167], v138 offset:33792
	ds_read_b128 v[168:171], v138 offset:34816
	ds_read_b128 v[172:175], v138 offset:35840
	ds_read_b128 v[186:189], v138 offset:36864
	ds_read_b128 v[190:193], v138 offset:37888
	ds_read_b128 v[198:201], v138 offset:38912
	ds_read_b128 v[202:205], v138 offset:39936
	global_load_lds_dwordx4 v[206:207], off
	v_lshl_add_u64 v[206:207], s[8:9], 0, v[126:127]
	s_mov_b32 m0, s21
	s_nop 0
	global_load_lds_dwordx4 v[206:207], off
	s_waitcnt lgkmcnt(8)
	s_barrier
	s_waitcnt lgkmcnt(0)
	s_waitcnt lgkmcnt(0)
	v_mfma_f32_16x16x32_bf16 v[134:137], v[140:143], v[160:163], v[134:137]
	v_mfma_f32_16x16x32_bf16 v[122:125], v[152:155], v[160:163], v[122:125]
	v_mfma_f32_16x16x32_bf16 v[110:113], v[140:143], v[168:171], v[110:113]
	v_mfma_f32_16x16x32_bf16 v[106:109], v[152:155], v[168:171], v[106:109]
	v_mfma_f32_16x16x32_bf16 v[94:97], v[140:143], v[186:189], v[94:97]
	v_mfma_f32_16x16x32_bf16 v[90:93], v[152:155], v[186:189], v[90:93]
	v_mfma_f32_16x16x32_bf16 v[78:81], v[140:143], v[198:201], v[78:81]
	v_mfma_f32_16x16x32_bf16 v[74:77], v[152:155], v[198:201], v[74:77]
	v_mfma_f32_16x16x32_bf16 v[134:137], v[148:151], v[164:167], v[134:137]
	v_mfma_f32_16x16x32_bf16 v[122:125], v[156:159], v[164:167], v[122:125]
	v_mfma_f32_16x16x32_bf16 v[110:113], v[148:151], v[172:175], v[110:113]
	v_mfma_f32_16x16x32_bf16 v[106:109], v[156:159], v[172:175], v[106:109]
	v_mfma_f32_16x16x32_bf16 v[94:97], v[148:151], v[190:193], v[94:97]
	v_mfma_f32_16x16x32_bf16 v[90:93], v[156:159], v[190:193], v[90:93]
	v_mfma_f32_16x16x32_bf16 v[78:81], v[148:151], v[202:205], v[78:81]
	v_mfma_f32_16x16x32_bf16 v[74:77], v[156:159], v[202:205], v[74:77]
	s_barrier
	s_add_i32 s8, 16, 0x1c000
	s_add_i32 s9, s10, s17
	v_add_u32_e32 v139, s8, v133
	v_lshl_add_u64 v[144:145], v[144:145], 0, s[70:71]
	s_mov_b32 m0, s9
	ds_read_b128 v[206:209], v139
	ds_read_b128 v[214:217], v139 offset:1024
	ds_read_b128 v[218:221], v139 offset:2048
	ds_read_b128 v[222:225], v139 offset:3072
	global_load_lds_dwordx4 v[144:145], off
	v_lshl_add_u64 v[144:145], v[176:177], 0, s[70:71]
	s_add_i32 m0, s9, 0x2000
	s_nop 0
	global_load_lds_dwordx4 v[144:145], off
	s_waitcnt vmcnt(10)
	s_barrier
; #define PG8_STAGE(bufoff, gbase, voff) do { _Pragma("unroll") for (int _i = 0; _i < 2; ++_i) \
;     __builtin_amdgcn_global_load_lds((const unsigned*)((const char*)(gbase) + (voff)[_i]), (LAS unsigned*)(lds + (bufoff) + ldsw + _i * 8192), 16, 0, 0); } while (0)
; #define PG8_LDA(dst, b, h) do { _Pragma("unroll") for (int m = 0; m < 4; ++m) _Pragma("unroll") for (int k = 0; k < 2; ++k) dst[m][k] = *(const LAS bf16x8*)(lds + PG8_SA(b, h) + aoff + m * 2048 + k * 1024); } while (0)
; #define PG8_LDB(dst, b, h) do { _Pragma("unroll") for (int n = 0; n < 2; ++n) _Pragma("unroll") for (int k = 0; k < 2; ++k) dst[n][k] = *(const LAS bf16x8*)(lds + PG8_SB(b, h) + boff + n * 2048 + k * 1024); } while (0)
; #define PG8_MMA(ai, bj, At, Bt) do { __builtin_amdgcn_s_setprio(1); _Pragma("unroll") for (int m = 0; m < 4; ++m) _Pragma("unroll") for (int n = 0; n < 2; ++n) _Pragma("unroll") for (int k = 0; k < 2; ++k) \
;     acc[ai][bj][m][n] = __builtin_amdgcn_mfma_f32_16x16x32_bf16(Bt[n][k], At[m][k], acc[ai][bj][m][n], 0, 0, 0); __builtin_amdgcn_s_setprio(0); } while (0)
; #define PG8_WAIT_V(n) asm volatile("s_waitcnt vmcnt(" #n ")" ::: "memory")
; #define PG8_WAIT_L(n) asm volatile("s_waitcnt lgkmcnt(" #n ")" ::: "memory")
; #define PG8_BAR __builtin_amdgcn_s_barrier()
; #define PG8_SCHED __builtin_amdgcn_sched_barrier(0)
; template <class Epi, class Sched>
; DI void gemm_phase(LAS unsigned char* lds, const Gemm g, const Sched& S, const Epi& E) {
;     ...
;       PG8_LDB(B1, 1, 1); PG8_STAGE(PG8_SB(1, 0), b3, voffB);
;       PG8_BAR; PG8_WAIT_L(0); PG8_MMA(0, 1, At, B1); PG8_BAR;
;       PG8_LDA(At, 1, 1); PG8_STAGE(PG8_SA(1, 0), a3, voffA);
;       PG8_BAR; PG8_WAIT_L(0); PG8_MMA(1, 0, At, B0); PG8_BAR; PG8_SCHED;
;       PG8_STAGE(PG8_SB(1, 1), b3 + hstepB, voffB);
;       PG8_WAIT_V(6); PG8_BAR; PG8_MMA(1, 1, At, B1); PG8_BAR;
;     }
;     E(acc, cur, wr, wc, fr, fq);
	s_waitcnt lgkmcnt(0)
	s_waitcnt lgkmcnt(0)
	v_mfma_f32_16x16x32_bf16 v[118:121], v[206:209], v[160:163], v[118:121]
	v_mfma_f32_16x16x32_bf16 v[114:117], v[218:221], v[160:163], v[114:117]
	v_mfma_f32_16x16x32_bf16 v[102:105], v[206:209], v[168:171], v[102:105]
	v_mfma_f32_16x16x32_bf16 v[98:101], v[218:221], v[168:171], v[98:101]
	v_mfma_f32_16x16x32_bf16 v[86:89], v[206:209], v[186:189], v[86:89]
	v_mfma_f32_16x16x32_bf16 v[82:85], v[218:221], v[186:189], v[82:85]
	v_mfma_f32_16x16x32_bf16 v[70:73], v[206:209], v[198:201], v[70:73]
	v_mfma_f32_16x16x32_bf16 v[66:69], v[218:221], v[198:201], v[66:69]
	v_mfma_f32_16x16x32_bf16 v[118:121], v[214:217], v[164:167], v[118:121]
	v_mfma_f32_16x16x32_bf16 v[114:117], v[222:225], v[164:167], v[114:117]
	v_mfma_f32_16x16x32_bf16 v[102:105], v[214:217], v[172:175], v[102:105]
	v_mfma_f32_16x16x32_bf16 v[98:101], v[222:225], v[172:175], v[98:101]
	v_mfma_f32_16x16x32_bf16 v[86:89], v[214:217], v[190:193], v[86:89]
	v_mfma_f32_16x16x32_bf16 v[82:85], v[222:225], v[190:193], v[82:85]
	v_mfma_f32_16x16x32_bf16 v[70:73], v[214:217], v[202:205], v[70:73]
	v_mfma_f32_16x16x32_bf16 v[66:69], v[222:225], v[202:205], v[66:69]
	s_mov_b32 m0, s22
	v_lshl_add_u64 v[144:145], v[180:181], 0, s[70:71]
	s_barrier
	ds_read_b128 v[160:163], v138 offset:49152
	ds_read_b128 v[164:167], v138 offset:50176
	ds_read_b128 v[168:171], v138 offset:51200
	ds_read_b128 v[172:175], v138 offset:52224
	ds_read_b128 v[186:189], v138 offset:53248
	ds_read_b128 v[190:193], v138 offset:54272
	ds_read_b128 v[198:201], v138 offset:55296
	ds_read_b128 v[202:205], v138 offset:56320
	global_load_lds_dwordx4 v[144:145], off
	v_lshl_add_u64 v[144:145], v[182:183], 0, s[70:71]
	s_mov_b32 m0, s23
	s_nop 0
	global_load_lds_dwordx4 v[144:145], off
	s_barrier
	s_waitcnt lgkmcnt(0)
	s_waitcnt lgkmcnt(0)
	v_mfma_f32_16x16x32_bf16 v[62:65], v[140:143], v[160:163], v[62:65]
	v_mfma_f32_16x16x32_bf16 v[58:61], v[152:155], v[160:163], v[58:61]
	v_mfma_f32_16x16x32_bf16 v[50:53], v[140:143], v[168:171], v[50:53]
	v_mfma_f32_16x16x32_bf16 v[42:45], v[152:155], v[168:171], v[42:45]
	v_mfma_f32_16x16x32_bf16 v[34:37], v[140:143], v[186:189], v[34:37]
	v_mfma_f32_16x16x32_bf16 v[26:29], v[152:155], v[186:189], v[26:29]
	v_mfma_f32_16x16x32_bf16 v[18:21], v[140:143], v[198:201], v[18:21]
	v_mfma_f32_16x16x32_bf16 v[10:13], v[152:155], v[198:201], v[10:13]
	v_mfma_f32_16x16x32_bf16 v[62:65], v[148:151], v[164:167], v[62:65]
	v_mfma_f32_16x16x32_bf16 v[58:61], v[156:159], v[164:167], v[58:61]
	v_mfma_f32_16x16x32_bf16 v[50:53], v[148:151], v[172:175], v[50:53]
	v_mfma_f32_16x16x32_bf16 v[42:45], v[156:159], v[172:175], v[42:45]
	v_mfma_f32_16x16x32_bf16 v[34:37], v[148:151], v[190:193], v[34:37]
	v_mfma_f32_16x16x32_bf16 v[26:29], v[156:159], v[190:193], v[26:29]
	v_mfma_f32_16x16x32_bf16 v[18:21], v[148:151], v[202:205], v[18:21]
	v_mfma_f32_16x16x32_bf16 v[10:13], v[156:159], v[202:205], v[10:13]
	s_barrier
	s_add_i32 s8, s8, s17
	v_lshl_add_u64 v[140:141], v[184:185], 0, s[70:71]
	s_mov_b32 m0, s8
	s_nop 0
	global_load_lds_dwordx4 v[140:141], off
	v_lshl_add_u64 v[140:141], v[226:227], 0, s[70:71]
	s_add_i32 m0, s8, 0x2000
	s_nop 0
	global_load_lds_dwordx4 v[140:141], off
	s_waitcnt vmcnt(8)
	s_barrier
	v_mfma_f32_16x16x32_bf16 v[54:57], v[206:209], v[160:163], v[54:57]
	v_mfma_f32_16x16x32_bf16 v[46:49], v[218:221], v[160:163], v[46:49]
	v_mfma_f32_16x16x32_bf16 v[38:41], v[206:209], v[168:171], v[38:41]
	v_mfma_f32_16x16x32_bf16 v[30:33], v[218:221], v[168:171], v[30:33]
	v_mfma_f32_16x16x32_bf16 v[22:25], v[206:209], v[186:189], v[22:25]
	v_mfma_f32_16x16x32_bf16 v[14:17], v[218:221], v[186:189], v[14:17]
	v_mfma_f32_16x16x32_bf16 v[6:9], v[206:209], v[198:201], v[6:9]
	v_mfma_f32_16x16x32_bf16 v[2:5], v[218:221], v[198:201], v[2:5]
	v_mfma_f32_16x16x32_bf16 v[54:57], v[214:217], v[164:167], v[54:57]
	v_mfma_f32_16x16x32_bf16 v[46:49], v[222:225], v[164:167], v[46:49]
	v_mfma_f32_16x16x32_bf16 v[38:41], v[214:217], v[172:175], v[38:41]
	v_mfma_f32_16x16x32_bf16 v[30:33], v[222:225], v[172:175], v[30:33]
	v_mfma_f32_16x16x32_bf16 v[22:25], v[214:217], v[190:193], v[22:25]
	v_mfma_f32_16x16x32_bf16 v[14:17], v[222:225], v[190:193], v[14:17]
	v_mfma_f32_16x16x32_bf16 v[6:9], v[214:217], v[202:205], v[6:9]
	v_mfma_f32_16x16x32_bf16 v[2:5], v[222:225], v[202:205], v[2:5]
	s_add_u32 s6, s6, 0x100
	s_addc_u32 s7, s7, 0
	s_cmp_ge_i32 s26, s24
	s_mov_b32 s8, s26
	s_barrier
	s_cbranch_scc0 .LBB0_491
	s_movk_i32 s27, 0xffd0
	s_movk_i32 s28, 0x2200

; #define PG8_STAGE(bufoff, gbase, voff) do { _Pragma("unroll") for (int _i = 0; _i < 2; ++_i) \
;     __builtin_amdgcn_global_load_lds((const unsigned*)((const char*)(gbase) + (voff)[_i]), (LAS unsigned*)(lds + (bufoff) + ldsw + _i * 8192), 16, 0, 0); } while (0)
; #define PG8_LDA(dst, b, h) do { _Pragma("unroll") for (int m = 0; m < 4; ++m) _Pragma("unroll") for (int k = 0; k < 2; ++k) dst[m][k] = *(const LAS bf16x8*)(lds + PG8_SA(b, h) + aoff + m * 2048 + k * 1024); } while (0)
; #define PG8_LDB(dst, b, h) do { _Pragma("unroll") for (int n = 0; n < 2; ++n) _Pragma("unroll") for (int k = 0; k < 2; ++k) dst[n][k] = *(const LAS bf16x8*)(lds + PG8_SB(b, h) + boff + n * 2048 + k * 1024); } while (0)
; #define PG8_MMA(ai, bj, At, Bt) do { __builtin_amdgcn_s_setprio(1); _Pragma("unroll") for (int m = 0; m < 4; ++m) _Pragma("unroll") for (int n = 0; n < 2; ++n) _Pragma("unroll") for (int k = 0; k < 2; ++k) \
;     acc[ai][bj][m][n] = __builtin_amdgcn_mfma_f32_16x16x32_bf16(Bt[n][k], At[m][k], acc[ai][bj][m][n], 0, 0, 0); __builtin_amdgcn_s_setprio(0); } while (0)
; #define PG8_WAIT_L(n) asm volatile("s_waitcnt lgkmcnt(" #n ")" ::: "memory")
; #define PG8_BAR __builtin_amdgcn_s_barrier()
; #define PG8_SCHED __builtin_amdgcn_sched_barrier(0)
; template <class Epi, class Sched>
; DI void gemm_phase(LAS unsigned char* lds, const Gemm g, const Sched& S, const Epi& E) {
;     ...
;       const bool last = (t == nt - 2);
;       const char* a1 = cA + (size_t)(t + 1) * kstep;
;       const char* a2 = last ? nA : cA + (size_t)(t + 2) * kstep; const char* b2 = last ? nB : cB + (size_t)(t + 2) * kstep;
;       const char* a3 = a2 + kstep; const char* b3 = b2 + kstep;
;       PG8_LDB(B0, 0, 0); PG8_SCHED; PG8_LDA(At, 0, 0); PG8_STAGE(PG8_SA(1, 1), a1 + hstep, voffA);
;       PG8_WAIT_L(8); PG8_BAR; PG8_WAIT_L(0); PG8_MMA(0, 0, At, B0); PG8_BAR; PG8_SCHED;
;       PG8_LDB(B1, 0, 1); PG8_STAGE(PG8_SB(0, 0), b2, voffB);
;       PG8_BAR; PG8_WAIT_L(0); PG8_MMA(0, 1, At, B1); PG8_BAR;
;       PG8_LDA(At, 0, 1); PG8_STAGE(PG8_SA(0, 0), a2, voffA);
;       PG8_BAR; PG8_WAIT_L(0); PG8_MMA(1, 0, At, B0); PG8_BAR; PG8_SCHED;
.LBB0_519:
	s_add_i32 s23, s6, 2
	s_add_u32 s8, s2, 0x80
	s_addc_u32 s7, s3, 0
	s_add_i32 s24, 16, 0x10000
	v_add_u32_e32 v0, s24, v215
	ds_read_b128 v[66:69], v0
	ds_read_b128 v[70:73], v0 offset:1024
	ds_read_b128 v[74:77], v0 offset:2048
	ds_read_b128 v[78:81], v0 offset:3072
	s_cmp_eq_u32 s41, s6
	s_cselect_b32 s6, s0, s8
	s_cselect_b32 s7, s1, s7
	s_cselect_b32 s9, s21, s22
	s_cselect_b32 s8, s20, s11
	v_lshl_add_u64 v[206:207], s[2:3], 0, v[202:203]
	s_add_i32 m0, s30, 0xc000
	ds_read_b128 v[82:85], v216
	ds_read_b128 v[86:89], v216 offset:1024
	ds_read_b128 v[94:97], v216 offset:2048
	ds_read_b128 v[98:101], v216 offset:3072
	ds_read_b128 v[114:117], v216 offset:4096
	ds_read_b128 v[118:121], v216 offset:5120
	ds_read_b128 v[122:125], v216 offset:6144
	ds_read_b128 v[126:129], v216 offset:7168
	global_load_lds_dwordx4 v[206:207], off
	v_lshl_add_u64 v[206:207], s[2:3], 0, v[204:205]
	s_add_i32 m0, s30, 0xe000
	s_nop 0
	global_load_lds_dwordx4 v[206:207], off
	s_waitcnt lgkmcnt(8)
	s_barrier
	s_waitcnt lgkmcnt(0)
	s_waitcnt lgkmcnt(0)
	v_mfma_f32_16x16x32_bf16 v[174:177], v[66:69], v[82:85], v[174:177]
	v_mfma_f32_16x16x32_bf16 v[170:173], v[74:77], v[82:85], v[170:173]
	v_mfma_f32_16x16x32_bf16 v[158:161], v[66:69], v[94:97], v[158:161]
	v_mfma_f32_16x16x32_bf16 v[154:157], v[74:77], v[94:97], v[154:157]
	v_mfma_f32_16x16x32_bf16 v[142:145], v[66:69], v[114:117], v[142:145]
	v_mfma_f32_16x16x32_bf16 v[138:141], v[74:77], v[114:117], v[138:141]
	v_mfma_f32_16x16x32_bf16 v[110:113], v[66:69], v[122:125], v[110:113]
	v_mfma_f32_16x16x32_bf16 v[106:109], v[74:77], v[122:125], v[106:109]
	v_mfma_f32_16x16x32_bf16 v[174:177], v[70:73], v[86:89], v[174:177]
	v_mfma_f32_16x16x32_bf16 v[170:173], v[78:81], v[86:89], v[170:173]
	v_mfma_f32_16x16x32_bf16 v[158:161], v[70:73], v[98:101], v[158:161]
	v_mfma_f32_16x16x32_bf16 v[154:157], v[78:81], v[98:101], v[154:157]
	v_mfma_f32_16x16x32_bf16 v[142:145], v[70:73], v[118:121], v[142:145]
	v_mfma_f32_16x16x32_bf16 v[138:141], v[78:81], v[118:121], v[138:141]
	v_mfma_f32_16x16x32_bf16 v[110:113], v[70:73], v[126:129], v[110:113]
	v_mfma_f32_16x16x32_bf16 v[106:109], v[78:81], v[126:129], v[106:109]
	s_barrier
	s_add_i32 s25, 16, 0x14000
	s_add_i32 s24, s24, s29
	v_add_u32_e32 v0, s25, v215
	v_lshl_add_u64 v[246:247], s[8:9], 0, v[190:191]
	s_mov_b32 m0, s24
	ds_read_b128 v[206:209], v0
	ds_read_b128 v[218:221], v0 offset:1024
	ds_read_b128 v[222:225], v0 offset:2048
	ds_read_b128 v[226:229], v0 offset:3072
	global_load_lds_dwordx4 v[246:247], off
	v_lshl_add_u64 v[248:249], s[8:9], 0, v[186:187]
	s_add_i32 m0, s24, 0x2000
	s_nop 0
	global_load_lds_dwordx4 v[248:249], off
	s_waitcnt vmcnt(10)
	s_barrier
	s_waitcnt lgkmcnt(0)
	s_waitcnt lgkmcnt(0)
	v_mfma_f32_16x16x32_bf16 v[166:169], v[206:209], v[82:85], v[166:169]
	v_mfma_f32_16x16x32_bf16 v[82:85], v[222:225], v[82:85], v[162:165]
	v_mfma_f32_16x16x32_bf16 v[166:169], v[218:221], v[86:89], v[166:169]
	v_mfma_f32_16x16x32_bf16 v[82:85], v[226:229], v[86:89], v[82:85]
	v_mfma_f32_16x16x32_bf16 v[86:89], v[206:209], v[94:97], v[150:153]
	v_mfma_f32_16x16x32_bf16 v[94:97], v[222:225], v[94:97], v[146:149]
	v_mfma_f32_16x16x32_bf16 v[102:105], v[206:209], v[122:125], v[102:105]
	v_mfma_f32_16x16x32_bf16 v[90:93], v[222:225], v[122:125], v[90:93]
	v_mfma_f32_16x16x32_bf16 v[86:89], v[218:221], v[98:101], v[86:89]
	v_mfma_f32_16x16x32_bf16 v[94:97], v[226:229], v[98:101], v[94:97]
	v_mfma_f32_16x16x32_bf16 v[98:101], v[206:209], v[114:117], v[134:137]
	v_mfma_f32_16x16x32_bf16 v[114:117], v[222:225], v[114:117], v[130:133]
	v_mfma_f32_16x16x32_bf16 v[102:105], v[218:221], v[126:129], v[102:105]
	v_mfma_f32_16x16x32_bf16 v[90:93], v[226:229], v[126:129], v[90:93]
	v_mfma_f32_16x16x32_bf16 v[98:101], v[218:221], v[118:121], v[98:101]
	v_mfma_f32_16x16x32_bf16 v[114:117], v[226:229], v[118:121], v[114:117]
	s_mov_b32 m0, s30
	v_lshl_add_u64 v[250:251], s[6:7], 0, v[192:193]
	s_barrier
	ds_read_b128 v[118:121], v216 offset:16384
	ds_read_b128 v[122:125], v216 offset:17408
	ds_read_b128 v[126:129], v216 offset:18432
	ds_read_b128 v[130:133], v216 offset:19456
	ds_read_b128 v[134:137], v216 offset:20480
	ds_read_b128 v[146:149], v216 offset:21504
	ds_read_b128 v[150:153], v216 offset:22528
	ds_read_b128 v[162:165], v216 offset:23552
	global_load_lds_dwordx4 v[250:251], off
	v_lshl_add_u64 v[180:181], s[6:7], 0, v[188:189]
	s_mov_b32 m0, s31
	s_nop 0
	global_load_lds_dwordx4 v[180:181], off
	s_barrier
	s_waitcnt lgkmcnt(0)
	s_waitcnt lgkmcnt(0)
	v_mfma_f32_16x16x32_bf16 v[62:65], v[66:69], v[118:121], v[62:65]
	v_mfma_f32_16x16x32_bf16 v[58:61], v[74:77], v[118:121], v[58:61]
	v_mfma_f32_16x16x32_bf16 v[46:49], v[66:69], v[126:129], v[46:49]
	v_mfma_f32_16x16x32_bf16 v[42:45], v[74:77], v[126:129], v[42:45]
	v_mfma_f32_16x16x32_bf16 v[30:33], v[66:69], v[134:137], v[30:33]
	v_mfma_f32_16x16x32_bf16 v[26:29], v[74:77], v[134:137], v[26:29]
	v_mfma_f32_16x16x32_bf16 v[14:17], v[66:69], v[150:153], v[14:17]
	v_mfma_f32_16x16x32_bf16 v[10:13], v[74:77], v[150:153], v[10:13]
	v_mfma_f32_16x16x32_bf16 v[62:65], v[70:73], v[122:125], v[62:65]
	v_mfma_f32_16x16x32_bf16 v[58:61], v[78:81], v[122:125], v[58:61]
	v_mfma_f32_16x16x32_bf16 v[46:49], v[70:73], v[130:133], v[46:49]
	v_mfma_f32_16x16x32_bf16 v[42:45], v[78:81], v[130:133], v[42:45]
	v_mfma_f32_16x16x32_bf16 v[30:33], v[70:73], v[146:149], v[30:33]
	v_mfma_f32_16x16x32_bf16 v[26:29], v[78:81], v[146:149], v[26:29]
	v_mfma_f32_16x16x32_bf16 v[14:17], v[70:73], v[162:165], v[14:17]
	v_mfma_f32_16x16x32_bf16 v[10:13], v[78:81], v[162:165], v[10:13]
	s_barrier
; #define PG8_STAGE(bufoff, gbase, voff) do { _Pragma("unroll") for (int _i = 0; _i < 2; ++_i) \
;     __builtin_amdgcn_global_load_lds((const unsigned*)((const char*)(gbase) + (voff)[_i]), (LAS unsigned*)(lds + (bufoff) + ldsw + _i * 8192), 16, 0, 0); } while (0)
; #define PG8_LDA(dst, b, h) do { _Pragma("unroll") for (int m = 0; m < 4; ++m) _Pragma("unroll") for (int k = 0; k < 2; ++k) dst[m][k] = *(const LAS bf16x8*)(lds + PG8_SA(b, h) + aoff + m * 2048 + k * 1024); } while (0)
; #define PG8_LDB(dst, b, h) do { _Pragma("unroll") for (int n = 0; n < 2; ++n) _Pragma("unroll") for (int k = 0; k < 2; ++k) dst[n][k] = *(const LAS bf16x8*)(lds + PG8_SB(b, h) + boff + n * 2048 + k * 1024); } while (0)
; #define PG8_MMA(ai, bj, At, Bt) do { __builtin_amdgcn_s_setprio(1); _Pragma("unroll") for (int m = 0; m < 4; ++m) _Pragma("unroll") for (int n = 0; n < 2; ++n) _Pragma("unroll") for (int k = 0; k < 2; ++k) \
;     acc[ai][bj][m][n] = __builtin_amdgcn_mfma_f32_16x16x32_bf16(Bt[n][k], At[m][k], acc[ai][bj][m][n], 0, 0, 0); __builtin_amdgcn_s_setprio(0); } while (0)
; #define PG8_WAIT_V(n) asm volatile("s_waitcnt vmcnt(" #n ")" ::: "memory")
; #define PG8_WAIT_L(n) asm volatile("s_waitcnt lgkmcnt(" #n ")" ::: "memory")
; #define PG8_BAR __builtin_amdgcn_s_barrier()
; #define PG8_SCHED __builtin_amdgcn_sched_barrier(0)
; template <class Epi, class Sched>
; DI void gemm_phase(LAS unsigned char* lds, const Gemm g, const Sched& S, const Epi& E) {
;     ...
;       PG8_STAGE(PG8_SB(0, 1), b2 + hstepB, voffB);
;       PG8_WAIT_V(6); PG8_BAR; PG8_MMA(1, 1, At, B1); PG8_BAR;
;       PG8_LDB(B0, 1, 0); PG8_SCHED; PG8_LDA(At, 1, 0); PG8_STAGE(PG8_SA(0, 1), a2 + hstep, voffA);
;       PG8_WAIT_L(8); PG8_BAR; PG8_WAIT_L(0); PG8_MMA(0, 0, At, B0); PG8_BAR; PG8_SCHED;
;       PG8_LDB(B1, 1, 1); PG8_STAGE(PG8_SB(1, 0), b3, voffB);
;       PG8_BAR; PG8_WAIT_L(0); PG8_MMA(0, 1, At, B1); PG8_BAR;
	s_add_u32 s8, s8, s14
	s_addc_u32 s9, s9, s15
	s_add_i32 s24, s25, s29
	v_lshl_add_u64 v[182:183], s[8:9], 0, v[190:191]
	s_mov_b32 m0, s24
	v_lshl_add_u64 v[184:185], s[8:9], 0, v[186:187]
	global_load_lds_dwordx4 v[182:183], off
	s_add_i32 m0, s24, 0x2000
	s_nop 0
	global_load_lds_dwordx4 v[184:185], off
	s_waitcnt vmcnt(8)
	s_barrier
	v_mfma_f32_16x16x32_bf16 v[54:57], v[206:209], v[118:121], v[54:57]
	v_mfma_f32_16x16x32_bf16 v[50:53], v[222:225], v[118:121], v[50:53]
	v_mfma_f32_16x16x32_bf16 v[38:41], v[206:209], v[126:129], v[38:41]
	v_mfma_f32_16x16x32_bf16 v[34:37], v[222:225], v[126:129], v[34:37]
	v_mfma_f32_16x16x32_bf16 v[22:25], v[206:209], v[134:137], v[22:25]
	v_mfma_f32_16x16x32_bf16 v[18:21], v[222:225], v[134:137], v[18:21]
	v_mfma_f32_16x16x32_bf16 v[6:9], v[206:209], v[150:153], v[6:9]
	v_mfma_f32_16x16x32_bf16 v[2:5], v[222:225], v[150:153], v[2:5]
	v_mfma_f32_16x16x32_bf16 v[54:57], v[218:221], v[122:125], v[54:57]
	v_mfma_f32_16x16x32_bf16 v[50:53], v[226:229], v[122:125], v[50:53]
	v_mfma_f32_16x16x32_bf16 v[38:41], v[218:221], v[130:133], v[38:41]
	v_mfma_f32_16x16x32_bf16 v[34:37], v[226:229], v[130:133], v[34:37]
	v_mfma_f32_16x16x32_bf16 v[22:25], v[218:221], v[146:149], v[22:25]
	v_mfma_f32_16x16x32_bf16 v[18:21], v[226:229], v[146:149], v[18:21]
	v_mfma_f32_16x16x32_bf16 v[6:9], v[218:221], v[162:165], v[6:9]
	v_mfma_f32_16x16x32_bf16 v[2:5], v[226:229], v[162:165], v[2:5]
	s_add_i32 s8, 16, 0x18000
	v_add_u32_e32 v0, s8, v215
	s_barrier
	ds_read_b128 v[66:69], v0
	ds_read_b128 v[70:73], v0 offset:1024
	ds_read_b128 v[74:77], v0 offset:2048
	ds_read_b128 v[78:81], v0 offset:3072
	s_add_u32 s6, s6, s12
	s_addc_u32 s7, s7, s13
	s_mov_b32 m0, s34
	v_lshl_add_u64 v[134:135], s[6:7], 0, v[192:193]
	ds_read_b128 v[118:121], v216 offset:32768
	ds_read_b128 v[122:125], v216 offset:33792
	ds_read_b128 v[126:129], v216 offset:34816
	ds_read_b128 v[130:133], v216 offset:35840
	ds_read_b128 v[206:209], v216 offset:36864
	ds_read_b128 v[218:221], v216 offset:37888
	ds_read_b128 v[222:225], v216 offset:38912
	ds_read_b128 v[226:229], v216 offset:39936
	global_load_lds_dwordx4 v[134:135], off
	v_lshl_add_u64 v[134:135], s[6:7], 0, v[188:189]
	s_mov_b32 m0, s35
	s_nop 0
	global_load_lds_dwordx4 v[134:135], off
	s_waitcnt lgkmcnt(8)
	s_barrier
	s_waitcnt lgkmcnt(0)
	s_waitcnt lgkmcnt(0)
	v_mfma_f32_16x16x32_bf16 v[134:137], v[66:69], v[118:121], v[174:177]
	v_mfma_f32_16x16x32_bf16 v[174:177], v[70:73], v[122:125], v[134:137]
	v_mfma_f32_16x16x32_bf16 v[134:137], v[74:77], v[118:121], v[170:173]
	v_mfma_f32_16x16x32_bf16 v[170:173], v[78:81], v[122:125], v[134:137]
	v_mfma_f32_16x16x32_bf16 v[134:137], v[66:69], v[126:129], v[158:161]
	v_mfma_f32_16x16x32_bf16 v[158:161], v[70:73], v[130:133], v[134:137]
	v_mfma_f32_16x16x32_bf16 v[134:137], v[74:77], v[126:129], v[154:157]
	v_mfma_f32_16x16x32_bf16 v[154:157], v[78:81], v[130:133], v[134:137]
	v_mfma_f32_16x16x32_bf16 v[134:137], v[66:69], v[206:209], v[142:145]
	v_mfma_f32_16x16x32_bf16 v[142:145], v[70:73], v[218:221], v[134:137]
	v_mfma_f32_16x16x32_bf16 v[134:137], v[74:77], v[206:209], v[138:141]
	v_mfma_f32_16x16x32_bf16 v[110:113], v[66:69], v[222:225], v[110:113]
	v_mfma_f32_16x16x32_bf16 v[106:109], v[74:77], v[222:225], v[106:109]
	v_mfma_f32_16x16x32_bf16 v[138:141], v[78:81], v[218:221], v[134:137]
	v_mfma_f32_16x16x32_bf16 v[110:113], v[70:73], v[226:229], v[110:113]
	v_mfma_f32_16x16x32_bf16 v[106:109], v[78:81], v[226:229], v[106:109]
	s_barrier
	s_add_i32 s6, 16, 0x1c000
	s_add_i32 s7, s8, s29
	v_add_u32_e32 v0, s6, v215
	v_lshl_add_u64 v[134:135], v[246:247], 0, s[70:71]
	s_mov_b32 m0, s7
	ds_read_b128 v[230:233], v0
	ds_read_b128 v[234:237], v0 offset:1024
	ds_read_b128 v[238:241], v0 offset:2048
	ds_read_b128 v[242:245], v0 offset:3072
	global_load_lds_dwordx4 v[134:135], off
	v_lshl_add_u64 v[134:135], v[248:249], 0, s[70:71]
	s_add_i32 m0, s7, 0x2000
	s_nop 0
	global_load_lds_dwordx4 v[134:135], off
	s_waitcnt vmcnt(10)
	s_barrier
; #define PG8_STAGE(bufoff, gbase, voff) do { _Pragma("unroll") for (int _i = 0; _i < 2; ++_i) \
;     __builtin_amdgcn_global_load_lds((const unsigned*)((const char*)(gbase) + (voff)[_i]), (LAS unsigned*)(lds + (bufoff) + ldsw + _i * 8192), 16, 0, 0); } while (0)
; #define PG8_LDA(dst, b, h) do { _Pragma("unroll") for (int m = 0; m < 4; ++m) _Pragma("unroll") for (int k = 0; k < 2; ++k) dst[m][k] = *(const LAS bf16x8*)(lds + PG8_SA(b, h) + aoff + m * 2048 + k * 1024); } while (0)
; #define PG8_MMA(ai, bj, At, Bt) do { __builtin_amdgcn_s_setprio(1); _Pragma("unroll") for (int m = 0; m < 4; ++m) _Pragma("unroll") for (int n = 0; n < 2; ++n) _Pragma("unroll") for (int k = 0; k < 2; ++k) \
;     acc[ai][bj][m][n] = __builtin_amdgcn_mfma_f32_16x16x32_bf16(Bt[n][k], At[m][k], acc[ai][bj][m][n], 0, 0, 0); __builtin_amdgcn_s_setprio(0); } while (0)
; #define PG8_WAIT_V(n) asm volatile("s_waitcnt vmcnt(" #n ")" ::: "memory")
; #define PG8_WAIT_L(n) asm volatile("s_waitcnt lgkmcnt(" #n ")" ::: "memory")
; #define PG8_BAR __builtin_amdgcn_s_barrier()
; #define PG8_SCHED __builtin_amdgcn_sched_barrier(0)
; template <class Epi, class Sched>
; DI void gemm_phase(LAS unsigned char* lds, const Gemm g, const Sched& S, const Epi& E) {
;     ...
;       PG8_LDA(At, 1, 1); PG8_STAGE(PG8_SA(1, 0), a3, voffA);
;       PG8_BAR; PG8_WAIT_L(0); PG8_MMA(1, 0, At, B0); PG8_BAR; PG8_SCHED;
;       PG8_STAGE(PG8_SB(1, 1), b3 + hstepB, voffB);
;       PG8_WAIT_V(6); PG8_BAR; PG8_MMA(1, 1, At, B1); PG8_BAR;
;     }
	s_waitcnt lgkmcnt(0)
	s_waitcnt lgkmcnt(0)
	v_mfma_f32_16x16x32_bf16 v[82:85], v[238:241], v[118:121], v[82:85]
	v_mfma_f32_16x16x32_bf16 v[162:165], v[242:245], v[122:125], v[82:85]
	v_mfma_f32_16x16x32_bf16 v[82:85], v[230:233], v[126:129], v[86:89]
	v_mfma_f32_16x16x32_bf16 v[150:153], v[234:237], v[130:133], v[82:85]
	v_mfma_f32_16x16x32_bf16 v[82:85], v[238:241], v[126:129], v[94:97]
	v_mfma_f32_16x16x32_bf16 v[134:137], v[230:233], v[118:121], v[166:169]
	v_mfma_f32_16x16x32_bf16 v[146:149], v[242:245], v[130:133], v[82:85]
	v_mfma_f32_16x16x32_bf16 v[82:85], v[230:233], v[206:209], v[98:101]
	v_mfma_f32_16x16x32_bf16 v[166:169], v[234:237], v[122:125], v[134:137]
	v_mfma_f32_16x16x32_bf16 v[134:137], v[234:237], v[218:221], v[82:85]
	v_mfma_f32_16x16x32_bf16 v[82:85], v[238:241], v[206:209], v[114:117]
	v_mfma_f32_16x16x32_bf16 v[130:133], v[242:245], v[218:221], v[82:85]
	v_mfma_f32_16x16x32_bf16 v[82:85], v[230:233], v[222:225], v[102:105]
	v_mfma_f32_16x16x32_bf16 v[102:105], v[234:237], v[226:229], v[82:85]
	v_mfma_f32_16x16x32_bf16 v[82:85], v[238:241], v[222:225], v[90:93]
	v_mfma_f32_16x16x32_bf16 v[90:93], v[242:245], v[226:229], v[82:85]
	s_mov_b32 m0, s36
	v_lshl_add_u64 v[206:207], v[250:251], 0, s[70:71]
	s_barrier
	s_nop 2
	ds_read_b128 v[82:85], v216 offset:49152
	ds_read_b128 v[86:89], v216 offset:50176
	ds_read_b128 v[94:97], v216 offset:51200
	ds_read_b128 v[98:101], v216 offset:52224
	ds_read_b128 v[114:117], v216 offset:53248
	ds_read_b128 v[118:121], v216 offset:54272
	ds_read_b128 v[122:125], v216 offset:55296
	ds_read_b128 v[126:129], v216 offset:56320
	global_load_lds_dwordx4 v[206:207], off
	v_lshl_add_u64 v[180:181], v[180:181], 0, s[70:71]
	s_mov_b32 m0, s37
	s_nop 0
	global_load_lds_dwordx4 v[180:181], off
	s_barrier
	s_waitcnt lgkmcnt(0)
	s_waitcnt lgkmcnt(0)
	v_mfma_f32_16x16x32_bf16 v[62:65], v[66:69], v[82:85], v[62:65]
	v_mfma_f32_16x16x32_bf16 v[58:61], v[74:77], v[82:85], v[58:61]
	v_mfma_f32_16x16x32_bf16 v[46:49], v[66:69], v[94:97], v[46:49]
	v_mfma_f32_16x16x32_bf16 v[42:45], v[74:77], v[94:97], v[42:45]
	v_mfma_f32_16x16x32_bf16 v[30:33], v[66:69], v[114:117], v[30:33]
	v_mfma_f32_16x16x32_bf16 v[26:29], v[74:77], v[114:117], v[26:29]
	v_mfma_f32_16x16x32_bf16 v[14:17], v[66:69], v[122:125], v[14:17]
	v_mfma_f32_16x16x32_bf16 v[10:13], v[74:77], v[122:125], v[10:13]
	v_mfma_f32_16x16x32_bf16 v[62:65], v[70:73], v[86:89], v[62:65]
	v_mfma_f32_16x16x32_bf16 v[58:61], v[78:81], v[86:89], v[58:61]
	v_mfma_f32_16x16x32_bf16 v[46:49], v[70:73], v[98:101], v[46:49]
	v_mfma_f32_16x16x32_bf16 v[42:45], v[78:81], v[98:101], v[42:45]
	v_mfma_f32_16x16x32_bf16 v[30:33], v[70:73], v[118:121], v[30:33]
	v_mfma_f32_16x16x32_bf16 v[26:29], v[78:81], v[118:121], v[26:29]
	v_mfma_f32_16x16x32_bf16 v[14:17], v[70:73], v[126:129], v[14:17]
	v_mfma_f32_16x16x32_bf16 v[10:13], v[78:81], v[126:129], v[10:13]
	s_barrier
	s_add_i32 s6, s6, s29
	v_lshl_add_u64 v[66:67], v[182:183], 0, s[70:71]
	s_mov_b32 m0, s6
	s_nop 0
	global_load_lds_dwordx4 v[66:67], off
	v_lshl_add_u64 v[66:67], v[184:185], 0, s[70:71]
	s_add_i32 m0, s6, 0x2000
	s_nop 0
	global_load_lds_dwordx4 v[66:67], off
	s_waitcnt vmcnt(8)
	s_barrier
	v_mfma_f32_16x16x32_bf16 v[54:57], v[230:233], v[82:85], v[54:57]
	v_mfma_f32_16x16x32_bf16 v[50:53], v[238:241], v[82:85], v[50:53]
	v_mfma_f32_16x16x32_bf16 v[38:41], v[230:233], v[94:97], v[38:41]
	v_mfma_f32_16x16x32_bf16 v[34:37], v[238:241], v[94:97], v[34:37]
	v_mfma_f32_16x16x32_bf16 v[22:25], v[230:233], v[114:117], v[22:25]
	v_mfma_f32_16x16x32_bf16 v[18:21], v[238:241], v[114:117], v[18:21]
	v_mfma_f32_16x16x32_bf16 v[6:9], v[230:233], v[122:125], v[6:9]
	v_mfma_f32_16x16x32_bf16 v[2:5], v[238:241], v[122:125], v[2:5]
	v_mfma_f32_16x16x32_bf16 v[54:57], v[234:237], v[86:89], v[54:57]
	v_mfma_f32_16x16x32_bf16 v[50:53], v[242:245], v[86:89], v[50:53]
	v_mfma_f32_16x16x32_bf16 v[38:41], v[234:237], v[98:101], v[38:41]
	v_mfma_f32_16x16x32_bf16 v[34:37], v[242:245], v[98:101], v[34:37]
	v_mfma_f32_16x16x32_bf16 v[22:25], v[234:237], v[118:121], v[22:25]
	v_mfma_f32_16x16x32_bf16 v[18:21], v[242:245], v[118:121], v[18:21]
	v_mfma_f32_16x16x32_bf16 v[6:9], v[234:237], v[126:129], v[6:9]
	v_mfma_f32_16x16x32_bf16 v[2:5], v[242:245], v[126:129], v[2:5]
	s_add_u32 s2, s2, 0x100
	s_addc_u32 s3, s3, 0
	s_add_u32 s11, s11, 0x100
	s_addc_u32 s22, s22, 0
	s_cmp_ge_i32 s23, s39
	s_mov_b32 s6, s23
	s_barrier
	s_cbranch_scc0 .LBB0_519
	v_mov_b64_e32 v[244:245], v[178:179]
	v_mov_b64_e32 v[178:179], 0xff
	v_mov_b64_e32 v[246:247], 0x1ff
	v_mov_b32_e32 v195, v217
	v_mov_b32_e32 v248, v210
	v_mov_b32_e32 v210, v201
	v_mov_b32_e32 v184, v200

; #define PG8_STAGE(bufoff, gbase, voff) do { _Pragma("unroll") for (int _i = 0; _i < 2; ++_i) \
;     __builtin_amdgcn_global_load_lds((const unsigned*)((const char*)(gbase) + (voff)[_i]), (LAS unsigned*)(lds + (bufoff) + ldsw + _i * 8192), 16, 0, 0); } while (0)
; #define PG8_LDA(dst, b, h) do { _Pragma("unroll") for (int m = 0; m < 4; ++m) _Pragma("unroll") for (int k = 0; k < 2; ++k) dst[m][k] = *(const LAS bf16x8*)(lds + PG8_SA(b, h) + aoff + m * 2048 + k * 1024); } while (0)
; #define PG8_LDB(dst, b, h) do { _Pragma("unroll") for (int n = 0; n < 2; ++n) _Pragma("unroll") for (int k = 0; k < 2; ++k) dst[n][k] = *(const LAS bf16x8*)(lds + PG8_SB(b, h) + boff + n * 2048 + k * 1024); } while (0)
; #define PG8_MMA(ai, bj, At, Bt) do { __builtin_amdgcn_s_setprio(1); _Pragma("unroll") for (int m = 0; m < 4; ++m) _Pragma("unroll") for (int n = 0; n < 2; ++n) _Pragma("unroll") for (int k = 0; k < 2; ++k) \
;     acc[ai][bj][m][n] = __builtin_amdgcn_mfma_f32_16x16x32_bf16(Bt[n][k], At[m][k], acc[ai][bj][m][n], 0, 0, 0); __builtin_amdgcn_s_setprio(0); } while (0)
; #define PG8_WAIT_L(n) asm volatile("s_waitcnt lgkmcnt(" #n ")" ::: "memory")
; #define PG8_BAR __builtin_amdgcn_s_barrier()
; #define PG8_SCHED __builtin_amdgcn_sched_barrier(0)
; template <class Epi, class Sched>
; DI void gemm_phase(LAS unsigned char* lds, const Gemm g, const Sched& S, const Epi& E) {
;     ...
;     for (int t = 0; t < nt; t += 2) {
;       const bool last = (t == nt - 2);
;       const char* a1 = cA + (size_t)(t + 1) * kstep;
;       const char* a2 = last ? nA : cA + (size_t)(t + 2) * kstep; const char* b2 = last ? nB : cB + (size_t)(t + 2) * kstep;
;       const char* a3 = a2 + kstep; const char* b3 = b2 + kstep;
;       PG8_LDB(B0, 0, 0); PG8_SCHED; PG8_LDA(At, 0, 0); PG8_STAGE(PG8_SA(1, 1), a1 + hstep, voffA);
;       PG8_WAIT_L(8); PG8_BAR; PG8_WAIT_L(0); PG8_MMA(0, 0, At, B0); PG8_BAR; PG8_SCHED;
;       PG8_LDB(B1, 0, 1); PG8_STAGE(PG8_SB(0, 0), b2, voffB);
;       PG8_BAR; PG8_WAIT_L(0); PG8_MMA(0, 1, At, B1); PG8_BAR;
;       PG8_LDA(At, 0, 1); PG8_STAGE(PG8_SA(0, 0), a2, voffA);
;       PG8_BAR; PG8_WAIT_L(0); PG8_MMA(1, 0, At, B0); PG8_BAR; PG8_SCHED;
.LBB0_831:
	s_add_i32 s26, s10, 2
	s_add_u32 s11, s8, 0xfe000080
	s_addc_u32 s12, s9, -1
	s_cmp_lg_u32 s25, s10
	s_cselect_b32 s13, s12, 0
	s_cselect_b32 s12, s11, 0
	s_add_u32 s10, s6, s12
	s_addc_u32 s11, s7, s13
	s_add_i32 s27, 16, 0x10000
	v_add_u32_e32 v146, s27, v92
	ds_read_b128 v[94:97], v146
	ds_read_b128 v[152:155], v146 offset:1024
	ds_read_b128 v[156:159], v146 offset:2048
	ds_read_b128 v[160:163], v146 offset:3072
	s_add_u32 s12, s4, s12
	s_addc_u32 s13, s5, s13
	v_lshl_add_u64 v[146:147], v[88:89], 0, s[8:9]
	s_add_i32 m0, s18, 0xc000
	ds_read_b128 v[164:167], v93
	ds_read_b128 v[168:171], v93 offset:1024
	ds_read_b128 v[172:175], v93 offset:2048
	ds_read_b128 v[186:189], v93 offset:3072
	ds_read_b128 v[190:193], v93 offset:4096
	ds_read_b128 v[198:201], v93 offset:5120
	ds_read_b128 v[202:205], v93 offset:6144
	ds_read_b128 v[206:209], v93 offset:7168
	global_load_lds_dwordx4 v[146:147], off
	v_lshl_add_u64 v[146:147], v[90:91], 0, s[8:9]
	s_add_i32 m0, s18, 0xe000
	s_nop 0
	global_load_lds_dwordx4 v[146:147], off
	s_waitcnt lgkmcnt(8)
	s_barrier
	s_waitcnt lgkmcnt(0)
	s_waitcnt lgkmcnt(0)
	v_mfma_f32_16x16x32_bf16 v[142:145], v[94:97], v[164:167], v[142:145]
	v_mfma_f32_16x16x32_bf16 v[138:141], v[156:159], v[164:167], v[138:141]
	v_mfma_f32_16x16x32_bf16 v[126:129], v[94:97], v[172:175], v[126:129]
	v_mfma_f32_16x16x32_bf16 v[122:125], v[156:159], v[172:175], v[122:125]
	v_mfma_f32_16x16x32_bf16 v[110:113], v[94:97], v[190:193], v[110:113]
	v_mfma_f32_16x16x32_bf16 v[106:109], v[156:159], v[190:193], v[106:109]
	v_mfma_f32_16x16x32_bf16 v[78:81], v[94:97], v[202:205], v[78:81]
	v_mfma_f32_16x16x32_bf16 v[74:77], v[156:159], v[202:205], v[74:77]
	v_mfma_f32_16x16x32_bf16 v[142:145], v[152:155], v[168:171], v[142:145]
	v_mfma_f32_16x16x32_bf16 v[138:141], v[160:163], v[168:171], v[138:141]
	v_mfma_f32_16x16x32_bf16 v[126:129], v[152:155], v[186:189], v[126:129]
	v_mfma_f32_16x16x32_bf16 v[122:125], v[160:163], v[186:189], v[122:125]
	v_mfma_f32_16x16x32_bf16 v[110:113], v[152:155], v[198:201], v[110:113]
	v_mfma_f32_16x16x32_bf16 v[106:109], v[160:163], v[198:201], v[106:109]
	v_mfma_f32_16x16x32_bf16 v[78:81], v[152:155], v[206:209], v[78:81]
	v_mfma_f32_16x16x32_bf16 v[74:77], v[160:163], v[206:209], v[74:77]
	s_barrier
	s_add_i32 s28, 16, 0x14000
	v_add_u32_e32 v146, s28, v92
	s_add_i32 s27, s27, s17
	ds_read_b128 v[214:217], v146
	ds_read_b128 v[218:221], v146 offset:1024
	ds_read_b128 v[222:225], v146 offset:2048
	ds_read_b128 v[226:229], v146 offset:3072
	v_lshl_add_u64 v[146:147], s[12:13], 0, v[0:1]
	s_mov_b32 m0, s27
	v_lshl_add_u64 v[176:177], s[12:13], 0, v[82:83]
	global_load_lds_dwordx4 v[146:147], off
	s_add_i32 m0, s27, 0x2000
	s_nop 0
	global_load_lds_dwordx4 v[176:177], off
	s_waitcnt vmcnt(10)
	s_barrier
	s_waitcnt lgkmcnt(0)
	s_waitcnt lgkmcnt(0)
	v_mfma_f32_16x16x32_bf16 v[134:137], v[214:217], v[164:167], v[134:137]
	v_mfma_f32_16x16x32_bf16 v[130:133], v[222:225], v[164:167], v[130:133]
	v_mfma_f32_16x16x32_bf16 v[118:121], v[214:217], v[172:175], v[118:121]
	v_mfma_f32_16x16x32_bf16 v[114:117], v[222:225], v[172:175], v[114:117]
	v_mfma_f32_16x16x32_bf16 v[102:105], v[214:217], v[190:193], v[102:105]
	v_mfma_f32_16x16x32_bf16 v[98:101], v[222:225], v[190:193], v[98:101]
	v_mfma_f32_16x16x32_bf16 v[70:73], v[214:217], v[202:205], v[70:73]
	v_mfma_f32_16x16x32_bf16 v[66:69], v[222:225], v[202:205], v[66:69]
	v_mfma_f32_16x16x32_bf16 v[134:137], v[218:221], v[168:171], v[134:137]
	v_mfma_f32_16x16x32_bf16 v[130:133], v[226:229], v[168:171], v[130:133]
	v_mfma_f32_16x16x32_bf16 v[118:121], v[218:221], v[186:189], v[118:121]
	v_mfma_f32_16x16x32_bf16 v[114:117], v[226:229], v[186:189], v[114:117]
	v_mfma_f32_16x16x32_bf16 v[102:105], v[218:221], v[198:201], v[102:105]
	v_mfma_f32_16x16x32_bf16 v[98:101], v[226:229], v[198:201], v[98:101]
	v_mfma_f32_16x16x32_bf16 v[70:73], v[218:221], v[206:209], v[70:73]
	v_mfma_f32_16x16x32_bf16 v[66:69], v[226:229], v[206:209], v[66:69]
	s_mov_b32 m0, s18
	v_lshl_add_u64 v[230:231], s[10:11], 0, v[86:87]
	s_barrier
	ds_read_b128 v[164:167], v93 offset:16384
	ds_read_b128 v[168:171], v93 offset:17408
	ds_read_b128 v[172:175], v93 offset:18432
	ds_read_b128 v[186:189], v93 offset:19456
	ds_read_b128 v[190:193], v93 offset:20480
	ds_read_b128 v[198:201], v93 offset:21504
	ds_read_b128 v[202:205], v93 offset:22528
	ds_read_b128 v[206:209], v93 offset:23552
	global_load_lds_dwordx4 v[230:231], off
	v_lshl_add_u64 v[232:233], s[10:11], 0, v[84:85]
	s_mov_b32 m0, s19
	s_nop 0
	global_load_lds_dwordx4 v[232:233], off
	s_barrier
	s_waitcnt lgkmcnt(0)
	s_waitcnt lgkmcnt(0)
	v_mfma_f32_16x16x32_bf16 v[62:65], v[94:97], v[164:167], v[62:65]
	v_mfma_f32_16x16x32_bf16 v[58:61], v[156:159], v[164:167], v[58:61]
	v_mfma_f32_16x16x32_bf16 v[46:49], v[94:97], v[172:175], v[46:49]
	v_mfma_f32_16x16x32_bf16 v[42:45], v[156:159], v[172:175], v[42:45]
	v_mfma_f32_16x16x32_bf16 v[30:33], v[94:97], v[190:193], v[30:33]
	v_mfma_f32_16x16x32_bf16 v[26:29], v[156:159], v[190:193], v[26:29]
	v_mfma_f32_16x16x32_bf16 v[14:17], v[94:97], v[202:205], v[14:17]
	v_mfma_f32_16x16x32_bf16 v[10:13], v[156:159], v[202:205], v[10:13]
	v_mfma_f32_16x16x32_bf16 v[62:65], v[152:155], v[168:171], v[62:65]
	v_mfma_f32_16x16x32_bf16 v[58:61], v[160:163], v[168:171], v[58:61]
	v_mfma_f32_16x16x32_bf16 v[46:49], v[152:155], v[186:189], v[46:49]
	v_mfma_f32_16x16x32_bf16 v[42:45], v[160:163], v[186:189], v[42:45]
	v_mfma_f32_16x16x32_bf16 v[30:33], v[152:155], v[198:201], v[30:33]
	v_mfma_f32_16x16x32_bf16 v[26:29], v[160:163], v[198:201], v[26:29]
	v_mfma_f32_16x16x32_bf16 v[14:17], v[152:155], v[206:209], v[14:17]
	v_mfma_f32_16x16x32_bf16 v[10:13], v[160:163], v[206:209], v[10:13]
	s_barrier
; #define PG8_STAGE(bufoff, gbase, voff) do { _Pragma("unroll") for (int _i = 0; _i < 2; ++_i) \
;     __builtin_amdgcn_global_load_lds((const unsigned*)((const char*)(gbase) + (voff)[_i]), (LAS unsigned*)(lds + (bufoff) + ldsw + _i * 8192), 16, 0, 0); } while (0)
; #define PG8_LDA(dst, b, h) do { _Pragma("unroll") for (int m = 0; m < 4; ++m) _Pragma("unroll") for (int k = 0; k < 2; ++k) dst[m][k] = *(const LAS bf16x8*)(lds + PG8_SA(b, h) + aoff + m * 2048 + k * 1024); } while (0)
; #define PG8_LDB(dst, b, h) do { _Pragma("unroll") for (int n = 0; n < 2; ++n) _Pragma("unroll") for (int k = 0; k < 2; ++k) dst[n][k] = *(const LAS bf16x8*)(lds + PG8_SB(b, h) + boff + n * 2048 + k * 1024); } while (0)
; #define PG8_MMA(ai, bj, At, Bt) do { __builtin_amdgcn_s_setprio(1); _Pragma("unroll") for (int m = 0; m < 4; ++m) _Pragma("unroll") for (int n = 0; n < 2; ++n) _Pragma("unroll") for (int k = 0; k < 2; ++k) \
;     acc[ai][bj][m][n] = __builtin_amdgcn_mfma_f32_16x16x32_bf16(Bt[n][k], At[m][k], acc[ai][bj][m][n], 0, 0, 0); __builtin_amdgcn_s_setprio(0); } while (0)
; #define PG8_WAIT_V(n) asm volatile("s_waitcnt vmcnt(" #n ")" ::: "memory")
; #define PG8_WAIT_L(n) asm volatile("s_waitcnt lgkmcnt(" #n ")" ::: "memory")
; #define PG8_BAR __builtin_amdgcn_s_barrier()
; #define PG8_SCHED __builtin_amdgcn_sched_barrier(0)
; template <class Epi, class Sched>
; DI void gemm_phase(LAS unsigned char* lds, const Gemm g, const Sched& S, const Epi& E) {
;     ...
;       PG8_STAGE(PG8_SB(0, 1), b2 + hstepB, voffB);
;       PG8_WAIT_V(6); PG8_BAR; PG8_MMA(1, 1, At, B1); PG8_BAR;
;       PG8_LDB(B0, 1, 0); PG8_SCHED; PG8_LDA(At, 1, 0); PG8_STAGE(PG8_SA(0, 1), a2 + hstep, voffA);
;       PG8_WAIT_L(8); PG8_BAR; PG8_WAIT_L(0); PG8_MMA(0, 0, At, B0); PG8_BAR; PG8_SCHED;
;       PG8_LDB(B1, 1, 1); PG8_STAGE(PG8_SB(1, 0), b3, voffB);
;       PG8_BAR; PG8_WAIT_L(0); PG8_MMA(0, 1, At, B1); PG8_BAR;
	s_add_u32 s12, s12, s2
	s_addc_u32 s13, s13, s3
	s_add_i32 s27, s28, s17
	v_lshl_add_u64 v[234:235], s[12:13], 0, v[0:1]
	s_mov_b32 m0, s27
	v_lshl_add_u64 v[236:237], s[12:13], 0, v[82:83]
	global_load_lds_dwordx4 v[234:235], off
	s_add_i32 m0, s27, 0x2000
	s_nop 0
	global_load_lds_dwordx4 v[236:237], off
	s_waitcnt vmcnt(8)
	s_barrier
	v_mfma_f32_16x16x32_bf16 v[54:57], v[214:217], v[164:167], v[54:57]
	v_mfma_f32_16x16x32_bf16 v[50:53], v[222:225], v[164:167], v[50:53]
	v_mfma_f32_16x16x32_bf16 v[38:41], v[214:217], v[172:175], v[38:41]
	v_mfma_f32_16x16x32_bf16 v[34:37], v[222:225], v[172:175], v[34:37]
	v_mfma_f32_16x16x32_bf16 v[22:25], v[214:217], v[190:193], v[22:25]
	v_mfma_f32_16x16x32_bf16 v[18:21], v[222:225], v[190:193], v[18:21]
	v_mfma_f32_16x16x32_bf16 v[6:9], v[214:217], v[202:205], v[6:9]
	v_mfma_f32_16x16x32_bf16 v[2:5], v[222:225], v[202:205], v[2:5]
	v_mfma_f32_16x16x32_bf16 v[54:57], v[218:221], v[168:171], v[54:57]
	v_mfma_f32_16x16x32_bf16 v[50:53], v[226:229], v[168:171], v[50:53]
	v_mfma_f32_16x16x32_bf16 v[38:41], v[218:221], v[186:189], v[38:41]
	v_mfma_f32_16x16x32_bf16 v[34:37], v[226:229], v[186:189], v[34:37]
	v_mfma_f32_16x16x32_bf16 v[22:25], v[218:221], v[198:201], v[22:25]
	v_mfma_f32_16x16x32_bf16 v[18:21], v[226:229], v[198:201], v[18:21]
	v_mfma_f32_16x16x32_bf16 v[6:9], v[218:221], v[206:209], v[6:9]
	v_mfma_f32_16x16x32_bf16 v[2:5], v[226:229], v[206:209], v[2:5]
	s_add_i32 s12, 16, 0x18000
	v_add_u32_e32 v149, s12, v92
	s_barrier
	ds_read_b128 v[94:97], v149
	ds_read_b128 v[152:155], v149 offset:1024
	ds_read_b128 v[156:159], v149 offset:2048
	ds_read_b128 v[160:163], v149 offset:3072
	s_add_u32 s10, s10, s0
	s_addc_u32 s11, s11, s1
	s_mov_b32 m0, s20
	v_lshl_add_u64 v[214:215], s[10:11], 0, v[86:87]
	ds_read_b128 v[164:167], v93 offset:32768
	ds_read_b128 v[168:171], v93 offset:33792
	ds_read_b128 v[172:175], v93 offset:34816
	ds_read_b128 v[186:189], v93 offset:35840
	ds_read_b128 v[190:193], v93 offset:36864
	ds_read_b128 v[198:201], v93 offset:37888
	ds_read_b128 v[202:205], v93 offset:38912
	ds_read_b128 v[206:209], v93 offset:39936
	global_load_lds_dwordx4 v[214:215], off
	v_lshl_add_u64 v[214:215], s[10:11], 0, v[84:85]
	s_mov_b32 m0, s21
	s_nop 0
	global_load_lds_dwordx4 v[214:215], off
	s_waitcnt lgkmcnt(8)
	s_barrier
	s_waitcnt lgkmcnt(0)
	s_waitcnt lgkmcnt(0)
	v_mfma_f32_16x16x32_bf16 v[142:145], v[94:97], v[164:167], v[142:145]
	v_mfma_f32_16x16x32_bf16 v[138:141], v[156:159], v[164:167], v[138:141]
	v_mfma_f32_16x16x32_bf16 v[126:129], v[94:97], v[172:175], v[126:129]
	v_mfma_f32_16x16x32_bf16 v[122:125], v[156:159], v[172:175], v[122:125]
	v_mfma_f32_16x16x32_bf16 v[110:113], v[94:97], v[190:193], v[110:113]
	v_mfma_f32_16x16x32_bf16 v[106:109], v[156:159], v[190:193], v[106:109]
	v_mfma_f32_16x16x32_bf16 v[78:81], v[94:97], v[202:205], v[78:81]
	v_mfma_f32_16x16x32_bf16 v[74:77], v[156:159], v[202:205], v[74:77]
	v_mfma_f32_16x16x32_bf16 v[142:145], v[152:155], v[168:171], v[142:145]
	v_mfma_f32_16x16x32_bf16 v[138:141], v[160:163], v[168:171], v[138:141]
	v_mfma_f32_16x16x32_bf16 v[126:129], v[152:155], v[186:189], v[126:129]
	v_mfma_f32_16x16x32_bf16 v[122:125], v[160:163], v[186:189], v[122:125]
	v_mfma_f32_16x16x32_bf16 v[110:113], v[152:155], v[198:201], v[110:113]
	v_mfma_f32_16x16x32_bf16 v[106:109], v[160:163], v[198:201], v[106:109]
	v_mfma_f32_16x16x32_bf16 v[78:81], v[152:155], v[206:209], v[78:81]
	v_mfma_f32_16x16x32_bf16 v[74:77], v[160:163], v[206:209], v[74:77]
	s_barrier
	s_add_i32 s10, 16, 0x1c000
	s_add_i32 s11, s12, s17
	v_add_u32_e32 v149, s10, v92
	v_lshl_add_u64 v[146:147], v[146:147], 0, s[70:71]
	s_mov_b32 m0, s11
	ds_read_b128 v[214:217], v149
	ds_read_b128 v[218:221], v149 offset:1024
	ds_read_b128 v[222:225], v149 offset:2048
	ds_read_b128 v[226:229], v149 offset:3072
	global_load_lds_dwordx4 v[146:147], off
	v_lshl_add_u64 v[146:147], v[176:177], 0, s[70:71]
	s_add_i32 m0, s11, 0x2000
	s_nop 0
	global_load_lds_dwordx4 v[146:147], off
	s_waitcnt vmcnt(10)
	s_barrier
; #define PG8_STAGE(bufoff, gbase, voff) do { _Pragma("unroll") for (int _i = 0; _i < 2; ++_i) \
;     __builtin_amdgcn_global_load_lds((const unsigned*)((const char*)(gbase) + (voff)[_i]), (LAS unsigned*)(lds + (bufoff) + ldsw + _i * 8192), 16, 0, 0); } while (0)
; #define PG8_LDA(dst, b, h) do { _Pragma("unroll") for (int m = 0; m < 4; ++m) _Pragma("unroll") for (int k = 0; k < 2; ++k) dst[m][k] = *(const LAS bf16x8*)(lds + PG8_SA(b, h) + aoff + m * 2048 + k * 1024); } while (0)
; #define PG8_MMA(ai, bj, At, Bt) do { __builtin_amdgcn_s_setprio(1); _Pragma("unroll") for (int m = 0; m < 4; ++m) _Pragma("unroll") for (int n = 0; n < 2; ++n) _Pragma("unroll") for (int k = 0; k < 2; ++k) \
;     acc[ai][bj][m][n] = __builtin_amdgcn_mfma_f32_16x16x32_bf16(Bt[n][k], At[m][k], acc[ai][bj][m][n], 0, 0, 0); __builtin_amdgcn_s_setprio(0); } while (0)
; #define PG8_WAIT_V(n) asm volatile("s_waitcnt vmcnt(" #n ")" ::: "memory")
; #define PG8_WAIT_L(n) asm volatile("s_waitcnt lgkmcnt(" #n ")" ::: "memory")
; #define PG8_BAR __builtin_amdgcn_s_barrier()
; #define PG8_SCHED __builtin_amdgcn_sched_barrier(0)
; template <class Epi, class Sched>
; DI void gemm_phase(LAS unsigned char* lds, const Gemm g, const Sched& S, const Epi& E) {
;     ...
;       PG8_LDA(At, 1, 1); PG8_STAGE(PG8_SA(1, 0), a3, voffA);
;       PG8_BAR; PG8_WAIT_L(0); PG8_MMA(1, 0, At, B0); PG8_BAR; PG8_SCHED;
;       PG8_STAGE(PG8_SB(1, 1), b3 + hstepB, voffB);
;       PG8_WAIT_V(6); PG8_BAR; PG8_MMA(1, 1, At, B1); PG8_BAR;
;     }
	s_waitcnt lgkmcnt(0)
	s_waitcnt lgkmcnt(0)
	v_mfma_f32_16x16x32_bf16 v[134:137], v[214:217], v[164:167], v[134:137]
	v_mfma_f32_16x16x32_bf16 v[130:133], v[222:225], v[164:167], v[130:133]
	v_mfma_f32_16x16x32_bf16 v[118:121], v[214:217], v[172:175], v[118:121]
	v_mfma_f32_16x16x32_bf16 v[114:117], v[222:225], v[172:175], v[114:117]
	v_mfma_f32_16x16x32_bf16 v[102:105], v[214:217], v[190:193], v[102:105]
	v_mfma_f32_16x16x32_bf16 v[98:101], v[222:225], v[190:193], v[98:101]
	v_mfma_f32_16x16x32_bf16 v[70:73], v[214:217], v[202:205], v[70:73]
	v_mfma_f32_16x16x32_bf16 v[66:69], v[222:225], v[202:205], v[66:69]
	v_mfma_f32_16x16x32_bf16 v[134:137], v[218:221], v[168:171], v[134:137]
	v_mfma_f32_16x16x32_bf16 v[130:133], v[226:229], v[168:171], v[130:133]
	v_mfma_f32_16x16x32_bf16 v[118:121], v[218:221], v[186:189], v[118:121]
	v_mfma_f32_16x16x32_bf16 v[114:117], v[226:229], v[186:189], v[114:117]
	v_mfma_f32_16x16x32_bf16 v[102:105], v[218:221], v[198:201], v[102:105]
	v_mfma_f32_16x16x32_bf16 v[98:101], v[226:229], v[198:201], v[98:101]
	v_mfma_f32_16x16x32_bf16 v[70:73], v[218:221], v[206:209], v[70:73]
	v_mfma_f32_16x16x32_bf16 v[66:69], v[226:229], v[206:209], v[66:69]
	s_mov_b32 m0, s22
	v_lshl_add_u64 v[146:147], v[230:231], 0, s[70:71]
	s_barrier
	ds_read_b128 v[164:167], v93 offset:49152
	ds_read_b128 v[168:171], v93 offset:50176
	ds_read_b128 v[172:175], v93 offset:51200
	ds_read_b128 v[186:189], v93 offset:52224
	ds_read_b128 v[190:193], v93 offset:53248
	ds_read_b128 v[198:201], v93 offset:54272
	ds_read_b128 v[202:205], v93 offset:55296
	ds_read_b128 v[206:209], v93 offset:56320
	global_load_lds_dwordx4 v[146:147], off
	v_lshl_add_u64 v[146:147], v[232:233], 0, s[70:71]
	s_mov_b32 m0, s23
	s_nop 0
	global_load_lds_dwordx4 v[146:147], off
	s_barrier
	s_waitcnt lgkmcnt(0)
	s_waitcnt lgkmcnt(0)
	v_mfma_f32_16x16x32_bf16 v[62:65], v[94:97], v[164:167], v[62:65]
	v_mfma_f32_16x16x32_bf16 v[58:61], v[156:159], v[164:167], v[58:61]
	v_mfma_f32_16x16x32_bf16 v[46:49], v[94:97], v[172:175], v[46:49]
	v_mfma_f32_16x16x32_bf16 v[42:45], v[156:159], v[172:175], v[42:45]
	v_mfma_f32_16x16x32_bf16 v[30:33], v[94:97], v[190:193], v[30:33]
	v_mfma_f32_16x16x32_bf16 v[26:29], v[156:159], v[190:193], v[26:29]
	v_mfma_f32_16x16x32_bf16 v[14:17], v[94:97], v[202:205], v[14:17]
	v_mfma_f32_16x16x32_bf16 v[10:13], v[156:159], v[202:205], v[10:13]
	v_mfma_f32_16x16x32_bf16 v[62:65], v[152:155], v[168:171], v[62:65]
	v_mfma_f32_16x16x32_bf16 v[58:61], v[160:163], v[168:171], v[58:61]
	v_mfma_f32_16x16x32_bf16 v[46:49], v[152:155], v[186:189], v[46:49]
	v_mfma_f32_16x16x32_bf16 v[42:45], v[160:163], v[186:189], v[42:45]
	v_mfma_f32_16x16x32_bf16 v[30:33], v[152:155], v[198:201], v[30:33]
	v_mfma_f32_16x16x32_bf16 v[26:29], v[160:163], v[198:201], v[26:29]
	v_mfma_f32_16x16x32_bf16 v[14:17], v[152:155], v[206:209], v[14:17]
	v_mfma_f32_16x16x32_bf16 v[10:13], v[160:163], v[206:209], v[10:13]
	s_barrier
	s_add_i32 s10, s10, s17
	v_lshl_add_u64 v[94:95], v[234:235], 0, s[70:71]
	s_mov_b32 m0, s10
	s_nop 0
	global_load_lds_dwordx4 v[94:95], off
	v_lshl_add_u64 v[94:95], v[236:237], 0, s[70:71]
	s_add_i32 m0, s10, 0x2000
	s_nop 0
	global_load_lds_dwordx4 v[94:95], off
	s_waitcnt vmcnt(8)
	s_barrier
	v_mfma_f32_16x16x32_bf16 v[54:57], v[214:217], v[164:167], v[54:57]
	v_mfma_f32_16x16x32_bf16 v[50:53], v[222:225], v[164:167], v[50:53]
	v_mfma_f32_16x16x32_bf16 v[38:41], v[214:217], v[172:175], v[38:41]
	v_mfma_f32_16x16x32_bf16 v[34:37], v[222:225], v[172:175], v[34:37]
	v_mfma_f32_16x16x32_bf16 v[22:25], v[214:217], v[190:193], v[22:25]
	v_mfma_f32_16x16x32_bf16 v[18:21], v[222:225], v[190:193], v[18:21]
	v_mfma_f32_16x16x32_bf16 v[6:9], v[214:217], v[202:205], v[6:9]
	v_mfma_f32_16x16x32_bf16 v[2:5], v[222:225], v[202:205], v[2:5]
	v_mfma_f32_16x16x32_bf16 v[54:57], v[218:221], v[168:171], v[54:57]
	v_mfma_f32_16x16x32_bf16 v[50:53], v[226:229], v[168:171], v[50:53]
	v_mfma_f32_16x16x32_bf16 v[38:41], v[218:221], v[186:189], v[38:41]
	v_mfma_f32_16x16x32_bf16 v[34:37], v[226:229], v[186:189], v[34:37]
	v_mfma_f32_16x16x32_bf16 v[22:25], v[218:221], v[198:201], v[22:25]
	v_mfma_f32_16x16x32_bf16 v[18:21], v[226:229], v[198:201], v[18:21]
	v_mfma_f32_16x16x32_bf16 v[6:9], v[218:221], v[206:209], v[6:9]
	v_mfma_f32_16x16x32_bf16 v[2:5], v[226:229], v[206:209], v[2:5]
	s_add_u32 s8, s8, 0x100
	s_addc_u32 s9, s9, 0
	s_cmp_ge_i32 s26, s24
	s_mov_b32 s10, s26
	s_barrier
	s_cbranch_scc0 .LBB0_831
